# attention: V staged row-major + ds_read_b64_tr_b16 PV operand (no b16 transposing LDS writes); attention item split 6/10; pool_run rewritten with batched loads (all window tokens in flight, rs/inv vec
# speedup vs baseline: 1.0331x; 1.0331x over previous
.LBB0_512:
	v_lshlrev_b32_e32 v126, 2, v1
	v_or_b32_e32 v3, 2, v126
	s_mov_b32 s29, 0
	v_mov_b32_e32 v4, 0x3c00
	v_cmp_lt_u32_e32 vcc, v158, v3
	s_cmpk_gt_i32 s2, 0x7f
	v_or_b32_e32 v6, 3, v126
	v_cndmask_b32_e32 v3, 0, v4, vcc
	v_cmp_lt_u32_e32 vcc, v126, v158
	s_cselect_b64 s[30:31], -1, 0
	s_mov_b32 s19, s29
	s_lshl_b32 s0, s6, 4
	v_or_b32_e32 v2, 16, v158
	v_cndmask_b32_e64 v5, v4, 0, vcc
	v_cmp_gt_u32_e32 vcc, v6, v158
	v_or_b32_e32 v7, 17, v126
	s_add_i32 s3, s2, 0x280
	s_and_b32 s44, s0, 48
	s_lshl_b64 s[0:1], s[18:19], 19
	v_cndmask_b32_e32 v6, 0, v4, vcc
	v_cmp_gt_u32_e32 vcc, v7, v2
	s_add_u32 s19, s7, s0
	s_addc_u32 s45, s8, s1
	v_cndmask_b32_e32 v7, 0, v4, vcc
	v_cmp_gt_u32_e32 vcc, v126, v158
	s_add_i32 s46, 0, 0x12000
	s_lshl_b32 s0, s6, 2
	v_cndmask_b32_e32 v8, 0, v4, vcc
	v_pack_b32_f16 v41, v3, v6
	v_or_b32_e32 v3, 19, v126
	s_add_i32 s47, s46, s0
	s_movk_i32 s0, 0x48
	v_pack_b32_f16 v40, v8, v5
	v_or_b32_e32 v5, 18, v126
	v_cmp_gt_u32_e32 vcc, v3, v2
	v_lshrrev_b32_e32 v163, 2, v158
	v_add_u32_e32 v163, v163, v126
	v_mul_u32_u24_e32 v163, 0x90, v163
	v_and_b32_e32 v16, 3, v158
	v_lshl_add_u32 v163, v16, 3, v163
	v_lshlrev_b32_e32 v134, 1, v0
	v_mbcnt_lo_u32_b32 v0, -1, 0
	v_cndmask_b32_e32 v3, 0, v4, vcc
	v_cmp_gt_u32_e32 vcc, v5, v2
	v_mov_b32_e32 v49, 0
	v_mbcnt_hi_u32_b32 v0, -1, v0
	v_mov_b32_e32 v42, 0x3c003c00
	v_cndmask_b32_e32 v2, 0, v4, vcc
	v_lshlrev_b32_e32 v128, 3, v1
	v_mul_i32_i24_e32 v1, 0x48, v160
	v_mov_b32_e32 v125, v49
	v_and_or_b32 v0, v0, 64, v158
	v_pack_b32_f16 v34, v8, v7
	s_mov_b32 s12, 0x3c003c00
	v_mov_b32_e32 v43, v42
	v_pack_b32_f16 v35, v2, v3
	v_mov_b32_e32 v32, v49
	v_mov_b32_e32 v33, v49
	v_or_b32_e32 v129, s44, v158
	v_add_u32_e32 v161, 0x1fc0, v160
	v_lshl_add_u32 v162, v192, 2, s46
	v_and_b32_e32 v164, 48, v192
	v_cmp_eq_u32_e64 s[6:7], 0, v14
	v_lshl_add_u64 v[130:131], s[20:21], 0, v[124:125]
	v_lshl_add_u64 v[132:133], s[24:25], 0, v[124:125]
	v_mul_u32_u24_e32 v125, 0x90, v158
	v_lshlrev_b32_e32 v165, 1, v1
	s_mov_b32 s48, 0xc266d4ca
	v_lshlrev_b32_e32 v136, 1, v126
	s_mov_b64 s[36:37], 0xe940400
	s_mov_b32 s49, 0xe940000
	v_lshlrev_b32_e32 v166, 2, v0
	s_mov_b32 s8, s2
	s_mov_b32 s9, 0
	s_branch .LBB0_515

.LBB0_517:
	s_andn2_b64 vcc, exec, s[0:1]
	s_cbranch_vccnz .LBB0_522
	s_cmp_gt_u32 s9, 4
	s_mov_b64 s[0:1], -1
	s_cbranch_scc0 .LBB0_520
	s_cmp_lt_u32 s9, 9
	s_cselect_b64 s[0:1], -1, 0
	s_lshl_b32 s9, s50, 7
	s_and_b64 s[0:1], s[30:31], s[0:1]
	s_add_i32 s9, s3, s9
	s_and_b64 s[0:1], s[0:1], exec
	s_cselect_b32 s51, s9, -1
	s_mov_b64 s[0:1], 0

.LBB0_528:
	s_mul_i32 s0, s56, 0x9000
	s_add_i32 s0, s0, 0
	v_add3_u32 v16, s0, v165, v124
	s_lshl_b32 s57, s56, 5
	s_waitcnt vmcnt(3)
	ds_write_b128 v16, v[52:55]
	s_waitcnt vmcnt(2)
	ds_write_b128 v16, v[56:59] offset:9216
	s_waitcnt vmcnt(1)
	ds_write_b128 v16, v[60:63] offset:18432
	s_xor_b32 s0, s57, 32
	s_add_i32 s0, s46, s0
	s_waitcnt vmcnt(0)
	ds_write_b128 v16, v[64:67] offset:27648
	v_mov_b32_e32 v16, s0
	s_xor_b32 s0, s57, 36
	s_add_i32 s0, s46, s0
	v_mov_b32_e32 v17, s0
	s_xor_b32 s0, s57, 40
	s_add_i32 s0, s46, s0
	v_mov_b32_e32 v18, s0
	s_xor_b32 s0, s57, 44
	s_add_i32 s0, s46, s0
	v_mov_b32_e32 v19, s0
	s_xor_b32 s0, s57, 48
	s_add_i32 s0, s46, s0
	v_mov_b32_e32 v20, s0
	s_xor_b32 s0, s57, 52
	s_add_i32 s0, s46, s0
	v_mov_b32_e32 v21, s0
	s_xor_b32 s0, s57, 56
	s_add_i32 s0, s46, s0
	v_mov_b32_e32 v22, s0
	s_xor_b32 s0, s57, 60
	s_add_i32 s0, s46, s0
	v_mov_b32_e32 v23, s0
	s_waitcnt lgkmcnt(0)
	s_barrier
	ds_read_b32 v16, v16
	ds_read_b32 v17, v17
	ds_read_b32 v18, v18
	ds_read_b32 v19, v19
	ds_read_b32 v20, v20
	ds_read_b32 v21, v21
	ds_read_b32 v22, v22
	ds_read_b32 v23, v23
	s_waitcnt lgkmcnt(6)
	v_and_b32_e32 v16, v16, v17
	s_waitcnt lgkmcnt(5)
	v_and_b32_e32 v16, v16, v18
	s_waitcnt lgkmcnt(4)
	v_and_b32_e32 v16, v16, v19
	s_waitcnt lgkmcnt(3)
	v_and_b32_e32 v16, v16, v20
	s_waitcnt lgkmcnt(2)
	v_and_b32_e32 v16, v16, v21
	s_waitcnt lgkmcnt(1)
	v_and_b32_e32 v16, v16, v22
	s_waitcnt lgkmcnt(0)
	v_and_b32_e32 v16, v16, v23
	v_and_b32_e32 v16, 1, v16
	v_cmp_eq_u32_e32 vcc, 1, v16
	v_cmp_eq_u32_e64 s[8:9], 0, v16
	s_cbranch_vccnz .LBB0_544
	s_cmp_eq_u32 s54, 0
	s_mov_b32 s13, 0
	s_cbranch_scc1 .LBB0_531
	v_add_u32_e32 v20, s55, v160
	v_subrev_u32_e32 v48, 64, v20
	v_lshlrev_b64 v[16:17], 7, v[48:49]
	v_lshl_add_u64 v[18:19], v[138:139], 0, v[16:17]
	v_lshl_add_u64 v[16:17], v[140:141], 0, v[16:17]
	v_add_u32_e32 v48, 0xfc0, v20
	global_load_dwordx4 v[52:55], v[18:19], off
	global_load_dwordx4 v[56:59], v[16:17], off
	v_lshlrev_b64 v[16:17], 7, v[48:49]
	v_lshl_add_u64 v[18:19], v[138:139], 0, v[16:17]
	v_lshl_add_u64 v[16:17], v[140:141], 0, v[16:17]
	global_load_dwordx4 v[60:63], v[18:19], off
	global_load_dwordx4 v[64:67], v[16:17], off
	s_mov_b32 s13, s55

.LBB0_540:
	v_add_u32_e32 v48, s58, v163
	ds_read_b64_tr_b16 v[108:109], v48 offset:9216
	ds_read_b64_tr_b16 v[110:111], v48 offset:11520
	ds_read_b64_tr_b16 v[142:143], v48 offset:13824
	ds_read_b64_tr_b16 v[144:145], v48 offset:16128
	v_cvt_pk_bf16_f32 v16, v16, v17
	v_cvt_pk_bf16_f32 v17, v18, v19
	v_cvt_pk_bf16_f32 v18, v20, v21
	v_cvt_pk_bf16_f32 v19, v22, v23
	v_cvt_pk_bf16_f32 v20, v25, v29
	v_cvt_pk_bf16_f32 v21, v114, v118
	s_waitcnt lgkmcnt(2)
	v_mfma_f32_16x16x32_bf16 v[24:27], v[108:111], v[16:19], v[104:107]
	v_cvt_pk_bf16_f32 v22, v119, v120
	v_cvt_pk_bf16_f32 v23, v121, v122
	v_add_f32_e32 v135, v135, v50
	s_waitcnt lgkmcnt(0)
	v_mfma_f32_16x16x32_bf16 v[104:107], v[142:145], v[20:23], v[24:27]
	v_cmp_gt_f32_e32 vcc, s48, v135
	s_cmp_eq_u64 vcc, exec
	s_cselect_b64 s[0:1], -1, 0
	s_nop 1
	ds_read_b64_tr_b16 v[24:25], v48 offset:9248
	ds_read_b64_tr_b16 v[26:27], v48 offset:11552
	ds_read_b64_tr_b16 v[28:29], v48 offset:13856
	ds_read_b64_tr_b16 v[30:31], v48 offset:16160
	s_waitcnt lgkmcnt(2)
	v_mfma_f32_16x16x32_bf16 v[24:27], v[24:27], v[16:19], v[100:103]
	s_waitcnt lgkmcnt(0)
	v_mfma_f32_16x16x32_bf16 v[100:103], v[28:31], v[20:23], v[24:27]
	s_nop 4
	ds_read_b64_tr_b16 v[24:25], v48 offset:9280
	ds_read_b64_tr_b16 v[26:27], v48 offset:11584
	ds_read_b64_tr_b16 v[28:29], v48 offset:13888
	ds_read_b64_tr_b16 v[30:31], v48 offset:16192
	s_waitcnt lgkmcnt(2)
	v_mfma_f32_16x16x32_bf16 v[24:27], v[24:27], v[16:19], v[96:99]
	s_waitcnt lgkmcnt(0)
	v_mfma_f32_16x16x32_bf16 v[96:99], v[28:31], v[20:23], v[24:27]
	s_nop 4
	ds_read_b64_tr_b16 v[24:25], v48 offset:9312
	ds_read_b64_tr_b16 v[26:27], v48 offset:11616
	s_waitcnt lgkmcnt(0)
	v_mfma_f32_16x16x32_bf16 v[16:19], v[24:27], v[16:19], v[92:95]
	ds_read_b64_tr_b16 v[24:25], v48 offset:13920
	ds_read_b64_tr_b16 v[26:27], v48 offset:16224
	s_waitcnt lgkmcnt(0)
	v_mfma_f32_16x16x32_bf16 v[92:95], v[24:27], v[20:23], v[16:19]
	s_nop 4
	v_cndmask_b32_e64 v16, 0, 1, s[0:1]

.LBB0_1153:
.LBB0_1154:
	v_and_b32_e32 v1, 63, v192
	v_lshlrev_b32_e32 v0, 3, v1
	v_readfirstlane_b32 s18, v192
	s_lshr_b32 s18, s18, 6
	s_cmpk_lt_i32 s2, 0x80
	s_cbranch_scc0 .Lpool_hi
	s_add_i32 s19, s2, 0
	s_bfe_u32 s0, s19, 0x30004
	s_and_b32 s1, s19, 15
	s_lshl_b32 s1, s1, 3
	s_add_i32 s1, s1, s18
	s_lshl_b32 s28, s1, 5
	s_sub_i32 s29, s28, 1
	s_max_i32 s3, s29, 0
	s_lshl_b32 s6, s0, 23
	s_add_u32 s6, s70, s6
	s_addc_u32 s7, s71, 0
	s_lshl_b32 s8, s3, 11
	s_add_u32 s20, s6, s8
	s_addc_u32 s21, s7, 0
	s_lshl_b32 s8, s28, 11
	s_add_u32 s22, s6, s8
	s_addc_u32 s23, s7, 0
	s_lshl_b32 s6, s0, 21
	s_lshl_b32 s8, s28, 9
	s_add_u32 s6, s6, s8
	s_add_u32 s6, s6, 0xe940000
	s_add_u32 s24, s72, s6
	s_addc_u32 s25, s73, 0
	s_lshl_b32 s6, s0, 14
	s_add_u32 s6, s6, 0x48a0000
	s_add_u32 s26, s72, s6
	s_addc_u32 s27, s73, 0
	v_add_u32_e32 v2, s29, v1
	v_max_i32_e32 v3, 0, v2
	s_add_i32 s6, s28, 31
	v_min_i32_e32 v3, s6, v3
	v_lshlrev_b32_e32 v3, 2, v3
	global_load_dword v26, v3, s[26:27]
	v_mov_b32_e32 v30, v2
	s_add_i32 s19, s2, 256
	s_bfe_u32 s0, s19, 0x30004
	s_and_b32 s1, s19, 15
	s_lshl_b32 s1, s1, 3
	s_add_i32 s1, s1, s18
	s_lshl_b32 s44, s1, 5
	s_sub_i32 s45, s44, 7
	s_max_i32 s3, s45, 0
	s_lshl_b32 s6, s0, 23
	s_add_u32 s6, s70, s6
	s_addc_u32 s7, s71, 0
	s_add_u32 s6, s6, 0x400
	s_addc_u32 s7, s7, 0
	s_lshl_b32 s8, s3, 11
	s_add_u32 s36, s6, s8
	s_addc_u32 s37, s7, 0
	s_lshl_b32 s8, s44, 11
	s_add_u32 s38, s6, s8
	s_addc_u32 s39, s7, 0
	s_lshl_b32 s6, s0, 21
	s_lshl_b32 s8, s44, 9
	s_add_u32 s6, s6, s8
	s_add_u32 s6, s6, 0x10940000
	s_add_u32 s40, s72, s6
	s_addc_u32 s41, s73, 0
	s_lshl_b32 s6, s0, 14
	s_add_u32 s6, s6, 0x48a0000
	s_add_u32 s42, s72, s6
	s_addc_u32 s43, s73, 0
	v_add_u32_e32 v2, s45, v1
	v_max_i32_e32 v3, 0, v2
	s_add_i32 s6, s44, 31
	v_min_i32_e32 v3, s6, v3
	v_lshlrev_b32_e32 v3, 2, v3
	global_load_dword v28, v3, s[42:43]
	v_mov_b32_e32 v31, v2
	global_load_dwordx2 v[44:45], v0, s[20:21]
	global_load_dwordx2 v[46:47], v0, s[22:23]
	global_load_dwordx2 v[48:49], v0, s[22:23] offset:2048
	s_add_u32 s22, s22, 0x1000
	s_addc_u32 s23, s23, 0
	global_load_dwordx2 v[50:51], v0, s[22:23]
	global_load_dwordx2 v[52:53], v0, s[22:23] offset:2048
	s_add_u32 s22, s22, 0x1000
	s_addc_u32 s23, s23, 0
	global_load_dwordx2 v[54:55], v0, s[22:23]
	global_load_dwordx2 v[56:57], v0, s[22:23] offset:2048
	s_add_u32 s22, s22, 0x1000
	s_addc_u32 s23, s23, 0
	global_load_dwordx2 v[58:59], v0, s[22:23]
	global_load_dwordx2 v[60:61], v0, s[22:23] offset:2048
	s_add_u32 s22, s22, 0x1000
	s_addc_u32 s23, s23, 0
	global_load_dwordx2 v[62:63], v0, s[22:23]
	global_load_dwordx2 v[64:65], v0, s[22:23] offset:2048
	s_add_u32 s22, s22, 0x1000
	s_addc_u32 s23, s23, 0
	global_load_dwordx2 v[66:67], v0, s[22:23]
	global_load_dwordx2 v[68:69], v0, s[22:23] offset:2048
	s_add_u32 s22, s22, 0x1000
	s_addc_u32 s23, s23, 0
	global_load_dwordx2 v[70:71], v0, s[22:23]
	global_load_dwordx2 v[72:73], v0, s[22:23] offset:2048
	s_add_u32 s22, s22, 0x1000
	s_addc_u32 s23, s23, 0
	global_load_dwordx2 v[74:75], v0, s[22:23]
	global_load_dwordx2 v[76:77], v0, s[22:23] offset:2048
	s_add_u32 s22, s22, 0x1000
	s_addc_u32 s23, s23, 0
	global_load_dwordx2 v[78:79], v0, s[22:23]
	global_load_dwordx2 v[80:81], v0, s[22:23] offset:2048
	s_add_u32 s22, s22, 0x1000
	s_addc_u32 s23, s23, 0
	global_load_dwordx2 v[82:83], v0, s[22:23]
	global_load_dwordx2 v[84:85], v0, s[22:23] offset:2048
	s_add_u32 s22, s22, 0x1000
	s_addc_u32 s23, s23, 0
	global_load_dwordx2 v[86:87], v0, s[22:23]
	global_load_dwordx2 v[88:89], v0, s[22:23] offset:2048
	s_add_u32 s22, s22, 0x1000
	s_addc_u32 s23, s23, 0
	global_load_dwordx2 v[90:91], v0, s[22:23]
	global_load_dwordx2 v[92:93], v0, s[22:23] offset:2048
	s_add_u32 s22, s22, 0x1000
	s_addc_u32 s23, s23, 0
	global_load_dwordx2 v[94:95], v0, s[22:23]
	global_load_dwordx2 v[96:97], v0, s[22:23] offset:2048
	s_add_u32 s22, s22, 0x1000
	s_addc_u32 s23, s23, 0
	global_load_dwordx2 v[98:99], v0, s[22:23]
	global_load_dwordx2 v[100:101], v0, s[22:23] offset:2048
	s_add_u32 s22, s22, 0x1000
	s_addc_u32 s23, s23, 0
	global_load_dwordx2 v[102:103], v0, s[22:23]
	global_load_dwordx2 v[104:105], v0, s[22:23] offset:2048
	s_add_u32 s22, s22, 0x1000
	s_addc_u32 s23, s23, 0
	global_load_dwordx2 v[106:107], v0, s[22:23]
	global_load_dwordx2 v[108:109], v0, s[22:23] offset:2048
	global_load_dwordx2 v[114:115], v0, s[36:37]
	global_load_dwordx2 v[116:117], v0, s[36:37] offset:2048
	s_add_u32 s36, s36, 0x1000
	s_addc_u32 s37, s37, 0
	global_load_dwordx2 v[118:119], v0, s[36:37]
	global_load_dwordx2 v[120:121], v0, s[36:37] offset:2048
	s_add_u32 s36, s36, 0x1000
	s_addc_u32 s37, s37, 0
	global_load_dwordx2 v[122:123], v0, s[36:37]
	global_load_dwordx2 v[124:125], v0, s[36:37] offset:2048
	s_add_u32 s36, s36, 0x1000
	s_addc_u32 s37, s37, 0
	global_load_dwordx2 v[126:127], v0, s[36:37]
	global_load_dwordx2 v[128:129], v0, s[38:39]
	global_load_dwordx2 v[130:131], v0, s[38:39] offset:2048
	s_add_u32 s38, s38, 0x1000
	s_addc_u32 s39, s39, 0
	global_load_dwordx2 v[132:133], v0, s[38:39]
	global_load_dwordx2 v[134:135], v0, s[38:39] offset:2048
	s_add_u32 s38, s38, 0x1000
	s_addc_u32 s39, s39, 0
	global_load_dwordx2 v[136:137], v0, s[38:39]
	global_load_dwordx2 v[138:139], v0, s[38:39] offset:2048
	s_add_u32 s38, s38, 0x1000
	s_addc_u32 s39, s39, 0
	global_load_dwordx2 v[140:141], v0, s[38:39]
	global_load_dwordx2 v[142:143], v0, s[38:39] offset:2048
	s_add_u32 s38, s38, 0x1000
	s_addc_u32 s39, s39, 0
	global_load_dwordx2 v[144:145], v0, s[38:39]
	s_waitcnt vmcnt(49)
	v_mov_b32_e32 v2, 0x358637bd
	v_fmac_f32_e32 v2, 0x3a800000, v26
	s_mov_b32 s6, 0x800000
	v_mul_f32_e32 v3, 0x4b800000, v2
	v_cmp_gt_f32_e32 vcc, s6, v2
	s_nop 1
	v_cndmask_b32_e32 v2, v2, v3, vcc
	v_rsq_f32_e32 v2, v2
	s_nop 0
	v_mul_f32_e32 v3, 0x45800000, v2
	v_cndmask_b32_e32 v26, v2, v3, vcc
	v_cmp_gt_i32_e32 vcc, 0, v30
	s_nop 1
	v_cndmask_b32_e64 v26, v26, 0, vcc
	v_add_u32_e32 v2, s28, v1
	v_add_u32_e32 v2, 1, v2
	v_min_u32_e32 v2, 2, v2
	v_cvt_f32_u32_e32 v2, v2
	v_div_scale_f32 v32, s[6:7], v2, v2, 1.0
	v_rcp_f32_e32 v33, v32
	v_div_scale_f32 v34, vcc, 1.0, v2, 1.0
	v_fma_f32 v35, -v32, v33, 1.0
	v_fmac_f32_e32 v33, v35, v33
	v_mul_f32_e32 v35, v34, v33
	v_fma_f32 v36, -v32, v35, v34
	v_fmac_f32_e32 v35, v36, v33
	v_fma_f32 v32, -v32, v35, v34
	v_div_fmas_f32 v32, v32, v33, v35
	v_div_fixup_f32 v27, v32, v2, 1.0
	v_mov_b32_e32 v2, 0x358637bd
	v_fmac_f32_e32 v2, 0x3a800000, v28
	s_mov_b32 s6, 0x800000
	v_mul_f32_e32 v3, 0x4b800000, v2
	v_cmp_gt_f32_e32 vcc, s6, v2
	s_nop 1
	v_cndmask_b32_e32 v2, v2, v3, vcc
	v_rsq_f32_e32 v2, v2
	s_nop 0
	v_mul_f32_e32 v3, 0x45800000, v2
	v_cndmask_b32_e32 v28, v2, v3, vcc
	v_cmp_gt_i32_e32 vcc, 0, v31
	s_nop 1
	v_cndmask_b32_e64 v28, v28, 0, vcc
	v_add_u32_e32 v2, s44, v1
	v_add_u32_e32 v2, 1, v2
	v_min_u32_e32 v2, 8, v2
	v_cvt_f32_u32_e32 v2, v2
	v_div_scale_f32 v32, s[6:7], v2, v2, 1.0
	v_rcp_f32_e32 v33, v32
	v_div_scale_f32 v34, vcc, 1.0, v2, 1.0
	v_fma_f32 v35, -v32, v33, 1.0
	v_fmac_f32_e32 v33, v35, v33
	v_mul_f32_e32 v35, v34, v33
	v_fma_f32 v36, -v32, v35, v34
	v_fmac_f32_e32 v35, v36, v33
	v_fma_f32 v32, -v32, v35, v34
	v_div_fmas_f32 v32, v32, v33, v35
	v_div_fixup_f32 v29, v32, v2, 1.0
	s_nop 0
	v_mov_b32_e32 v4, 0
	v_mov_b32_e32 v5, 0
	v_mov_b32_e32 v6, 0
	v_mov_b32_e32 v7, 0
	v_readlane_b32 s46, v26, 0
	s_waitcnt vmcnt(48)
	v_lshlrev_b32_e32 v8, 16, v44
	v_and_b32_e32 v9, 0xffff0000, v44
	v_lshlrev_b32_e32 v10, 16, v45
	v_and_b32_e32 v11, 0xffff0000, v45
	v_fma_f32 v4, s46, v8, v4
	v_fma_f32 v5, s46, v9, v5
	v_fma_f32 v6, s46, v10, v6
	v_fma_f32 v7, s46, v11, v7
	v_readlane_b32 s46, v26, 1
	v_readlane_b32 s47, v27, 0
	v_readlane_b32 s48, v26, 0
	s_waitcnt vmcnt(47)
	v_lshlrev_b32_e32 v8, 16, v46
	v_and_b32_e32 v9, 0xffff0000, v46
	v_lshlrev_b32_e32 v10, 16, v47
	v_and_b32_e32 v11, 0xffff0000, v47
	v_lshlrev_b32_e32 v22, 16, v44
	v_and_b32_e32 v23, 0xffff0000, v44
	v_lshlrev_b32_e32 v24, 16, v45
	v_and_b32_e32 v25, 0xffff0000, v45
	v_mul_f32_e32 v12, s46, v8
	v_mul_f32_e32 v13, s46, v9
	v_mul_f32_e32 v14, s46, v10
	v_mul_f32_e32 v15, s46, v11
	v_fma_f32 v4, s46, v8, v4
	v_fma_f32 v5, s46, v9, v5
	v_fma_f32 v6, s46, v10, v6
	v_fma_f32 v7, s46, v11, v7
	v_fma_f32 v16, s47, v4, -v12
	v_fma_f32 v17, s47, v5, -v13
	v_fma_f32 v18, s47, v6, -v14
	v_fma_f32 v19, s47, v7, -v15
	v_cvt_pk_bf16_f32 v20, v16, v17
	v_cvt_pk_bf16_f32 v21, v18, v19
	global_store_dwordx2 v0, v[20:21], s[24:25]
	global_load_dwordx2 v[146:147], v0, s[38:39] offset:2048
	s_add_u32 s38, s38, 0x1000
	s_addc_u32 s39, s39, 0
	global_load_dwordx2 v[148:149], v0, s[38:39]
	v_fma_f32 v4, -s48, v22, v4
	v_fma_f32 v5, -s48, v23, v5
	v_fma_f32 v6, -s48, v24, v6
	v_fma_f32 v7, -s48, v25, v7
	v_readlane_b32 s46, v26, 2
	v_readlane_b32 s47, v27, 1
	v_readlane_b32 s48, v26, 1
	s_waitcnt vmcnt(49)
	v_lshlrev_b32_e32 v8, 16, v48
	v_and_b32_e32 v9, 0xffff0000, v48
	v_lshlrev_b32_e32 v10, 16, v49
	v_and_b32_e32 v11, 0xffff0000, v49
	v_lshlrev_b32_e32 v22, 16, v46
	v_and_b32_e32 v23, 0xffff0000, v46
	v_lshlrev_b32_e32 v24, 16, v47
	v_and_b32_e32 v25, 0xffff0000, v47
	v_mul_f32_e32 v12, s46, v8
	v_mul_f32_e32 v13, s46, v9
	v_mul_f32_e32 v14, s46, v10
	v_mul_f32_e32 v15, s46, v11
	v_fma_f32 v4, s46, v8, v4
	v_fma_f32 v5, s46, v9, v5
	v_fma_f32 v6, s46, v10, v6
	v_fma_f32 v7, s46, v11, v7
	v_fma_f32 v16, s47, v4, -v12
	v_fma_f32 v17, s47, v5, -v13
	v_fma_f32 v18, s47, v6, -v14
	v_fma_f32 v19, s47, v7, -v15
	v_cvt_pk_bf16_f32 v38, v16, v17
	v_cvt_pk_bf16_f32 v39, v18, v19
	global_store_dwordx2 v0, v[38:39], s[24:25] offset:512
	global_load_dwordx2 v[150:151], v0, s[38:39] offset:2048
	s_add_u32 s38, s38, 0x1000
	s_addc_u32 s39, s39, 0
	global_load_dwordx2 v[152:153], v0, s[38:39]
	v_fma_f32 v4, -s48, v22, v4
	v_fma_f32 v5, -s48, v23, v5
	v_fma_f32 v6, -s48, v24, v6
	v_fma_f32 v7, -s48, v25, v7
	v_readlane_b32 s46, v26, 3
	v_readlane_b32 s47, v27, 2
	v_readlane_b32 s48, v26, 2
	s_waitcnt vmcnt(51)
	v_lshlrev_b32_e32 v8, 16, v50
	v_and_b32_e32 v9, 0xffff0000, v50
	v_lshlrev_b32_e32 v10, 16, v51
	v_and_b32_e32 v11, 0xffff0000, v51
	v_lshlrev_b32_e32 v22, 16, v48
	v_and_b32_e32 v23, 0xffff0000, v48
	v_lshlrev_b32_e32 v24, 16, v49
	v_and_b32_e32 v25, 0xffff0000, v49
	v_mul_f32_e32 v12, s46, v8
	v_mul_f32_e32 v13, s46, v9
	v_mul_f32_e32 v14, s46, v10
	v_mul_f32_e32 v15, s46, v11
	v_fma_f32 v4, s46, v8, v4
	v_fma_f32 v5, s46, v9, v5
	v_fma_f32 v6, s46, v10, v6
	v_fma_f32 v7, s46, v11, v7
	v_fma_f32 v16, s47, v4, -v12
	v_fma_f32 v17, s47, v5, -v13
	v_fma_f32 v18, s47, v6, -v14
	v_fma_f32 v19, s47, v7, -v15
	v_cvt_pk_bf16_f32 v20, v16, v17
	v_cvt_pk_bf16_f32 v21, v18, v19
	global_store_dwordx2 v0, v[20:21], s[24:25] offset:1024
	global_load_dwordx2 v[154:155], v0, s[38:39] offset:2048
	s_add_u32 s38, s38, 0x1000
	s_addc_u32 s39, s39, 0
	global_load_dwordx2 v[156:157], v0, s[38:39]
	v_fma_f32 v4, -s48, v22, v4
	v_fma_f32 v5, -s48, v23, v5
	v_fma_f32 v6, -s48, v24, v6
	v_fma_f32 v7, -s48, v25, v7
	v_readlane_b32 s46, v26, 4
	v_readlane_b32 s47, v27, 3
	v_readlane_b32 s48, v26, 3
	s_waitcnt vmcnt(52)
	v_lshlrev_b32_e32 v8, 16, v52
	v_and_b32_e32 v9, 0xffff0000, v52
	v_lshlrev_b32_e32 v10, 16, v53
	v_and_b32_e32 v11, 0xffff0000, v53
	v_lshlrev_b32_e32 v22, 16, v50
	v_and_b32_e32 v23, 0xffff0000, v50
	v_lshlrev_b32_e32 v24, 16, v51
	v_and_b32_e32 v25, 0xffff0000, v51
	v_mul_f32_e32 v12, s46, v8
	v_mul_f32_e32 v13, s46, v9
	v_mul_f32_e32 v14, s46, v10
	v_mul_f32_e32 v15, s46, v11
	v_fma_f32 v4, s46, v8, v4
	v_fma_f32 v5, s46, v9, v5
	v_fma_f32 v6, s46, v10, v6
	v_fma_f32 v7, s46, v11, v7
	v_fma_f32 v16, s47, v4, -v12
	v_fma_f32 v17, s47, v5, -v13
	v_fma_f32 v18, s47, v6, -v14
	v_fma_f32 v19, s47, v7, -v15
	v_cvt_pk_bf16_f32 v38, v16, v17
	v_cvt_pk_bf16_f32 v39, v18, v19
	global_store_dwordx2 v0, v[38:39], s[24:25] offset:1536
	global_load_dwordx2 v[158:159], v0, s[38:39] offset:2048
	s_add_u32 s38, s38, 0x1000
	s_addc_u32 s39, s39, 0
	global_load_dwordx2 v[160:161], v0, s[38:39]
	v_fma_f32 v4, -s48, v22, v4
	v_fma_f32 v5, -s48, v23, v5
	v_fma_f32 v6, -s48, v24, v6
	v_fma_f32 v7, -s48, v25, v7
	v_readlane_b32 s46, v26, 5
	v_readlane_b32 s47, v27, 4
	v_readlane_b32 s48, v26, 4
	s_waitcnt vmcnt(52)
	v_lshlrev_b32_e32 v8, 16, v54
	v_and_b32_e32 v9, 0xffff0000, v54
	v_lshlrev_b32_e32 v10, 16, v55
	v_and_b32_e32 v11, 0xffff0000, v55
	v_lshlrev_b32_e32 v22, 16, v52
	v_and_b32_e32 v23, 0xffff0000, v52
	v_lshlrev_b32_e32 v24, 16, v53
	v_and_b32_e32 v25, 0xffff0000, v53
	v_mul_f32_e32 v12, s46, v8
	v_mul_f32_e32 v13, s46, v9
	v_mul_f32_e32 v14, s46, v10
	v_mul_f32_e32 v15, s46, v11
	v_fma_f32 v4, s46, v8, v4
	v_fma_f32 v5, s46, v9, v5
	v_fma_f32 v6, s46, v10, v6
	v_fma_f32 v7, s46, v11, v7
	v_fma_f32 v16, s47, v4, -v12
	v_fma_f32 v17, s47, v5, -v13
	v_fma_f32 v18, s47, v6, -v14
	v_fma_f32 v19, s47, v7, -v15
	v_cvt_pk_bf16_f32 v20, v16, v17
	v_cvt_pk_bf16_f32 v21, v18, v19
	global_store_dwordx2 v0, v[20:21], s[24:25] offset:2048
	global_load_dwordx2 v[162:163], v0, s[38:39] offset:2048
	s_add_u32 s38, s38, 0x1000
	s_addc_u32 s39, s39, 0
	global_load_dwordx2 v[164:165], v0, s[38:39]
	v_fma_f32 v4, -s48, v22, v4
	v_fma_f32 v5, -s48, v23, v5
	v_fma_f32 v6, -s48, v24, v6
	v_fma_f32 v7, -s48, v25, v7
	v_readlane_b32 s46, v26, 6
	v_readlane_b32 s47, v27, 5
	v_readlane_b32 s48, v26, 5
	s_waitcnt vmcnt(52)
	v_lshlrev_b32_e32 v8, 16, v56
	v_and_b32_e32 v9, 0xffff0000, v56
	v_lshlrev_b32_e32 v10, 16, v57
	v_and_b32_e32 v11, 0xffff0000, v57
	v_lshlrev_b32_e32 v22, 16, v54
	v_and_b32_e32 v23, 0xffff0000, v54
	v_lshlrev_b32_e32 v24, 16, v55
	v_and_b32_e32 v25, 0xffff0000, v55
	v_mul_f32_e32 v12, s46, v8
	v_mul_f32_e32 v13, s46, v9
	v_mul_f32_e32 v14, s46, v10
	v_mul_f32_e32 v15, s46, v11
	v_fma_f32 v4, s46, v8, v4
	v_fma_f32 v5, s46, v9, v5
	v_fma_f32 v6, s46, v10, v6
	v_fma_f32 v7, s46, v11, v7
	v_fma_f32 v16, s47, v4, -v12
	v_fma_f32 v17, s47, v5, -v13
	v_fma_f32 v18, s47, v6, -v14
	v_fma_f32 v19, s47, v7, -v15
	v_cvt_pk_bf16_f32 v38, v16, v17
	v_cvt_pk_bf16_f32 v39, v18, v19
	global_store_dwordx2 v0, v[38:39], s[24:25] offset:2560
	global_load_dwordx2 v[166:167], v0, s[38:39] offset:2048
	s_add_u32 s38, s38, 0x1000
	s_addc_u32 s39, s39, 0
	global_load_dwordx2 v[168:169], v0, s[38:39]
	v_fma_f32 v4, -s48, v22, v4
	v_fma_f32 v5, -s48, v23, v5
	v_fma_f32 v6, -s48, v24, v6
	v_fma_f32 v7, -s48, v25, v7
	v_readlane_b32 s46, v26, 7
	v_readlane_b32 s47, v27, 6
	v_readlane_b32 s48, v26, 6
	s_waitcnt vmcnt(52)
	v_lshlrev_b32_e32 v8, 16, v58
	v_and_b32_e32 v9, 0xffff0000, v58
	v_lshlrev_b32_e32 v10, 16, v59
	v_and_b32_e32 v11, 0xffff0000, v59
	v_lshlrev_b32_e32 v22, 16, v56
	v_and_b32_e32 v23, 0xffff0000, v56
	v_lshlrev_b32_e32 v24, 16, v57
	v_and_b32_e32 v25, 0xffff0000, v57
	v_mul_f32_e32 v12, s46, v8
	v_mul_f32_e32 v13, s46, v9
	v_mul_f32_e32 v14, s46, v10
	v_mul_f32_e32 v15, s46, v11
	v_fma_f32 v4, s46, v8, v4
	v_fma_f32 v5, s46, v9, v5
	v_fma_f32 v6, s46, v10, v6
	v_fma_f32 v7, s46, v11, v7
	v_fma_f32 v16, s47, v4, -v12
	v_fma_f32 v17, s47, v5, -v13
	v_fma_f32 v18, s47, v6, -v14
	v_fma_f32 v19, s47, v7, -v15
	v_cvt_pk_bf16_f32 v20, v16, v17
	v_cvt_pk_bf16_f32 v21, v18, v19
	global_store_dwordx2 v0, v[20:21], s[24:25] offset:3072
	global_load_dwordx2 v[170:171], v0, s[38:39] offset:2048
	s_add_u32 s38, s38, 0x1000
	s_addc_u32 s39, s39, 0
	global_load_dwordx2 v[172:173], v0, s[38:39]
	v_fma_f32 v4, -s48, v22, v4
	v_fma_f32 v5, -s48, v23, v5
	v_fma_f32 v6, -s48, v24, v6
	v_fma_f32 v7, -s48, v25, v7
	v_readlane_b32 s46, v26, 8
	v_readlane_b32 s47, v27, 7
	v_readlane_b32 s48, v26, 7
	s_waitcnt vmcnt(52)
	v_lshlrev_b32_e32 v8, 16, v60
	v_and_b32_e32 v9, 0xffff0000, v60
	v_lshlrev_b32_e32 v10, 16, v61
	v_and_b32_e32 v11, 0xffff0000, v61
	v_lshlrev_b32_e32 v22, 16, v58
	v_and_b32_e32 v23, 0xffff0000, v58
	v_lshlrev_b32_e32 v24, 16, v59
	v_and_b32_e32 v25, 0xffff0000, v59
	v_mul_f32_e32 v12, s46, v8
	v_mul_f32_e32 v13, s46, v9
	v_mul_f32_e32 v14, s46, v10
	v_mul_f32_e32 v15, s46, v11
	v_fma_f32 v4, s46, v8, v4
	v_fma_f32 v5, s46, v9, v5
	v_fma_f32 v6, s46, v10, v6
	v_fma_f32 v7, s46, v11, v7
	v_fma_f32 v16, s47, v4, -v12
	v_fma_f32 v17, s47, v5, -v13
	v_fma_f32 v18, s47, v6, -v14
	v_fma_f32 v19, s47, v7, -v15
	v_cvt_pk_bf16_f32 v38, v16, v17
	v_cvt_pk_bf16_f32 v39, v18, v19
	global_store_dwordx2 v0, v[38:39], s[24:25] offset:3584
	global_load_dwordx2 v[174:175], v0, s[38:39] offset:2048
	s_add_u32 s38, s38, 0x1000
	s_addc_u32 s39, s39, 0
	global_load_dwordx2 v[176:177], v0, s[38:39]
	v_fma_f32 v4, -s48, v22, v4
	v_fma_f32 v5, -s48, v23, v5
	v_fma_f32 v6, -s48, v24, v6
	v_fma_f32 v7, -s48, v25, v7
	v_readlane_b32 s46, v26, 9
	v_readlane_b32 s47, v27, 8
	v_readlane_b32 s48, v26, 8
	s_waitcnt vmcnt(52)
	v_lshlrev_b32_e32 v8, 16, v62
	v_and_b32_e32 v9, 0xffff0000, v62
	v_lshlrev_b32_e32 v10, 16, v63
	v_and_b32_e32 v11, 0xffff0000, v63
	v_lshlrev_b32_e32 v22, 16, v60
	v_and_b32_e32 v23, 0xffff0000, v60
	v_lshlrev_b32_e32 v24, 16, v61
	v_and_b32_e32 v25, 0xffff0000, v61
	v_mul_f32_e32 v12, s46, v8
	v_mul_f32_e32 v13, s46, v9
	v_mul_f32_e32 v14, s46, v10
	v_mul_f32_e32 v15, s46, v11
	v_fma_f32 v4, s46, v8, v4
	v_fma_f32 v5, s46, v9, v5
	v_fma_f32 v6, s46, v10, v6
	v_fma_f32 v7, s46, v11, v7
	v_fma_f32 v16, s47, v4, -v12
	v_fma_f32 v17, s47, v5, -v13
	v_fma_f32 v18, s47, v6, -v14
	v_fma_f32 v19, s47, v7, -v15
	v_cvt_pk_bf16_f32 v20, v16, v17
	v_cvt_pk_bf16_f32 v21, v18, v19
	s_add_u32 s24, s24, 0x1000
	s_addc_u32 s25, s25, 0
	global_store_dwordx2 v0, v[20:21], s[24:25]
	global_load_dwordx2 v[178:179], v0, s[38:39] offset:2048
	s_add_u32 s38, s38, 0x1000
	s_addc_u32 s39, s39, 0
	global_load_dwordx2 v[180:181], v0, s[38:39]
	v_fma_f32 v4, -s48, v22, v4
	v_fma_f32 v5, -s48, v23, v5
	v_fma_f32 v6, -s48, v24, v6
	v_fma_f32 v7, -s48, v25, v7
	v_readlane_b32 s46, v26, 10
	v_readlane_b32 s47, v27, 9
	v_readlane_b32 s48, v26, 9
	s_waitcnt vmcnt(52)
	v_lshlrev_b32_e32 v8, 16, v64
	v_and_b32_e32 v9, 0xffff0000, v64
	v_lshlrev_b32_e32 v10, 16, v65
	v_and_b32_e32 v11, 0xffff0000, v65
	v_lshlrev_b32_e32 v22, 16, v62
	v_and_b32_e32 v23, 0xffff0000, v62
	v_lshlrev_b32_e32 v24, 16, v63
	v_and_b32_e32 v25, 0xffff0000, v63
	v_mul_f32_e32 v12, s46, v8
	v_mul_f32_e32 v13, s46, v9
	v_mul_f32_e32 v14, s46, v10
	v_mul_f32_e32 v15, s46, v11
	v_fma_f32 v4, s46, v8, v4
	v_fma_f32 v5, s46, v9, v5
	v_fma_f32 v6, s46, v10, v6
	v_fma_f32 v7, s46, v11, v7
	v_fma_f32 v16, s47, v4, -v12
	v_fma_f32 v17, s47, v5, -v13
	v_fma_f32 v18, s47, v6, -v14
	v_fma_f32 v19, s47, v7, -v15
	v_cvt_pk_bf16_f32 v38, v16, v17
	v_cvt_pk_bf16_f32 v39, v18, v19
	global_store_dwordx2 v0, v[38:39], s[24:25] offset:512
	global_load_dwordx2 v[182:183], v0, s[38:39] offset:2048
	s_add_u32 s38, s38, 0x1000
	s_addc_u32 s39, s39, 0
	global_load_dwordx2 v[184:185], v0, s[38:39]
	v_fma_f32 v4, -s48, v22, v4
	v_fma_f32 v5, -s48, v23, v5
	v_fma_f32 v6, -s48, v24, v6
	v_fma_f32 v7, -s48, v25, v7
	v_readlane_b32 s46, v26, 11
	v_readlane_b32 s47, v27, 10
	v_readlane_b32 s48, v26, 10
	s_waitcnt vmcnt(52)
	v_lshlrev_b32_e32 v8, 16, v66
	v_and_b32_e32 v9, 0xffff0000, v66
	v_lshlrev_b32_e32 v10, 16, v67
	v_and_b32_e32 v11, 0xffff0000, v67
	v_lshlrev_b32_e32 v22, 16, v64
	v_and_b32_e32 v23, 0xffff0000, v64
	v_lshlrev_b32_e32 v24, 16, v65
	v_and_b32_e32 v25, 0xffff0000, v65
	v_mul_f32_e32 v12, s46, v8
	v_mul_f32_e32 v13, s46, v9
	v_mul_f32_e32 v14, s46, v10
	v_mul_f32_e32 v15, s46, v11
	v_fma_f32 v4, s46, v8, v4
	v_fma_f32 v5, s46, v9, v5
	v_fma_f32 v6, s46, v10, v6
	v_fma_f32 v7, s46, v11, v7
	v_fma_f32 v16, s47, v4, -v12
	v_fma_f32 v17, s47, v5, -v13
	v_fma_f32 v18, s47, v6, -v14
	v_fma_f32 v19, s47, v7, -v15
	v_cvt_pk_bf16_f32 v20, v16, v17
	v_cvt_pk_bf16_f32 v21, v18, v19
	global_store_dwordx2 v0, v[20:21], s[24:25] offset:1024
	global_load_dwordx2 v[186:187], v0, s[38:39] offset:2048
	s_add_u32 s38, s38, 0x1000
	s_addc_u32 s39, s39, 0
	global_load_dwordx2 v[188:189], v0, s[38:39]
	v_fma_f32 v4, -s48, v22, v4
	v_fma_f32 v5, -s48, v23, v5
	v_fma_f32 v6, -s48, v24, v6
	v_fma_f32 v7, -s48, v25, v7
	v_readlane_b32 s46, v26, 12
	v_readlane_b32 s47, v27, 11
	v_readlane_b32 s48, v26, 11
	s_waitcnt vmcnt(52)
	v_lshlrev_b32_e32 v8, 16, v68
	v_and_b32_e32 v9, 0xffff0000, v68
	v_lshlrev_b32_e32 v10, 16, v69
	v_and_b32_e32 v11, 0xffff0000, v69
	v_lshlrev_b32_e32 v22, 16, v66
	v_and_b32_e32 v23, 0xffff0000, v66
	v_lshlrev_b32_e32 v24, 16, v67
	v_and_b32_e32 v25, 0xffff0000, v67
	v_mul_f32_e32 v12, s46, v8
	v_mul_f32_e32 v13, s46, v9
	v_mul_f32_e32 v14, s46, v10
	v_mul_f32_e32 v15, s46, v11
	v_fma_f32 v4, s46, v8, v4
	v_fma_f32 v5, s46, v9, v5
	v_fma_f32 v6, s46, v10, v6
	v_fma_f32 v7, s46, v11, v7
	v_fma_f32 v16, s47, v4, -v12
	v_fma_f32 v17, s47, v5, -v13
	v_fma_f32 v18, s47, v6, -v14
	v_fma_f32 v19, s47, v7, -v15
	v_cvt_pk_bf16_f32 v38, v16, v17
	v_cvt_pk_bf16_f32 v39, v18, v19
	global_store_dwordx2 v0, v[38:39], s[24:25] offset:1536
	global_load_dwordx2 v[190:191], v0, s[38:39] offset:2048
	v_fma_f32 v4, -s48, v22, v4
	v_fma_f32 v5, -s48, v23, v5
	v_fma_f32 v6, -s48, v24, v6
	v_fma_f32 v7, -s48, v25, v7
	v_readlane_b32 s46, v26, 13
	v_readlane_b32 s47, v27, 12
	v_readlane_b32 s48, v26, 12
	s_waitcnt vmcnt(52)
	v_lshlrev_b32_e32 v8, 16, v70
	v_and_b32_e32 v9, 0xffff0000, v70
	v_lshlrev_b32_e32 v10, 16, v71
	v_and_b32_e32 v11, 0xffff0000, v71
	v_lshlrev_b32_e32 v22, 16, v68
	v_and_b32_e32 v23, 0xffff0000, v68
	v_lshlrev_b32_e32 v24, 16, v69
	v_and_b32_e32 v25, 0xffff0000, v69
	v_mul_f32_e32 v12, s46, v8
	v_mul_f32_e32 v13, s46, v9
	v_mul_f32_e32 v14, s46, v10
	v_mul_f32_e32 v15, s46, v11
	v_fma_f32 v4, s46, v8, v4
	v_fma_f32 v5, s46, v9, v5
	v_fma_f32 v6, s46, v10, v6
	v_fma_f32 v7, s46, v11, v7
	v_fma_f32 v16, s47, v4, -v12
	v_fma_f32 v17, s47, v5, -v13
	v_fma_f32 v18, s47, v6, -v14
	v_fma_f32 v19, s47, v7, -v15
	v_cvt_pk_bf16_f32 v20, v16, v17
	v_cvt_pk_bf16_f32 v21, v18, v19
	global_store_dwordx2 v0, v[20:21], s[24:25] offset:2048
	v_fma_f32 v4, -s48, v22, v4
	v_fma_f32 v5, -s48, v23, v5
	v_fma_f32 v6, -s48, v24, v6
	v_fma_f32 v7, -s48, v25, v7
	v_readlane_b32 s46, v26, 14
	v_readlane_b32 s47, v27, 13
	v_readlane_b32 s48, v26, 13
	s_waitcnt vmcnt(52)
	v_lshlrev_b32_e32 v8, 16, v72
	v_and_b32_e32 v9, 0xffff0000, v72
	v_lshlrev_b32_e32 v10, 16, v73
	v_and_b32_e32 v11, 0xffff0000, v73
	v_lshlrev_b32_e32 v22, 16, v70
	v_and_b32_e32 v23, 0xffff0000, v70
	v_lshlrev_b32_e32 v24, 16, v71
	v_and_b32_e32 v25, 0xffff0000, v71
	v_mul_f32_e32 v12, s46, v8
	v_mul_f32_e32 v13, s46, v9
	v_mul_f32_e32 v14, s46, v10
	v_mul_f32_e32 v15, s46, v11
	v_fma_f32 v4, s46, v8, v4
	v_fma_f32 v5, s46, v9, v5
	v_fma_f32 v6, s46, v10, v6
	v_fma_f32 v7, s46, v11, v7
	v_fma_f32 v16, s47, v4, -v12
	v_fma_f32 v17, s47, v5, -v13
	v_fma_f32 v18, s47, v6, -v14
	v_fma_f32 v19, s47, v7, -v15
	v_cvt_pk_bf16_f32 v38, v16, v17
	v_cvt_pk_bf16_f32 v39, v18, v19
	global_store_dwordx2 v0, v[38:39], s[24:25] offset:2560
	v_fma_f32 v4, -s48, v22, v4
	v_fma_f32 v5, -s48, v23, v5
	v_fma_f32 v6, -s48, v24, v6
	v_fma_f32 v7, -s48, v25, v7
	v_readlane_b32 s46, v26, 15
	v_readlane_b32 s47, v27, 14
	v_readlane_b32 s48, v26, 14
	s_waitcnt vmcnt(52)
	v_lshlrev_b32_e32 v8, 16, v74
	v_and_b32_e32 v9, 0xffff0000, v74
	v_lshlrev_b32_e32 v10, 16, v75
	v_and_b32_e32 v11, 0xffff0000, v75
	v_lshlrev_b32_e32 v22, 16, v72
	v_and_b32_e32 v23, 0xffff0000, v72
	v_lshlrev_b32_e32 v24, 16, v73
	v_and_b32_e32 v25, 0xffff0000, v73
	v_mul_f32_e32 v12, s46, v8
	v_mul_f32_e32 v13, s46, v9
	v_mul_f32_e32 v14, s46, v10
	v_mul_f32_e32 v15, s46, v11
	v_fma_f32 v4, s46, v8, v4
	v_fma_f32 v5, s46, v9, v5
	v_fma_f32 v6, s46, v10, v6
	v_fma_f32 v7, s46, v11, v7
	v_fma_f32 v16, s47, v4, -v12
	v_fma_f32 v17, s47, v5, -v13
	v_fma_f32 v18, s47, v6, -v14
	v_fma_f32 v19, s47, v7, -v15
	v_cvt_pk_bf16_f32 v20, v16, v17
	v_cvt_pk_bf16_f32 v21, v18, v19
	global_store_dwordx2 v0, v[20:21], s[24:25] offset:3072
	v_fma_f32 v4, -s48, v22, v4
	v_fma_f32 v5, -s48, v23, v5
	v_fma_f32 v6, -s48, v24, v6
	v_fma_f32 v7, -s48, v25, v7
	v_readlane_b32 s46, v26, 16
	v_readlane_b32 s47, v27, 15
	v_readlane_b32 s48, v26, 15
	s_waitcnt vmcnt(52)
	v_lshlrev_b32_e32 v8, 16, v76
	v_and_b32_e32 v9, 0xffff0000, v76
	v_lshlrev_b32_e32 v10, 16, v77
	v_and_b32_e32 v11, 0xffff0000, v77
	v_lshlrev_b32_e32 v22, 16, v74
	v_and_b32_e32 v23, 0xffff0000, v74
	v_lshlrev_b32_e32 v24, 16, v75
	v_and_b32_e32 v25, 0xffff0000, v75
	v_mul_f32_e32 v12, s46, v8
	v_mul_f32_e32 v13, s46, v9
	v_mul_f32_e32 v14, s46, v10
	v_mul_f32_e32 v15, s46, v11
	v_fma_f32 v4, s46, v8, v4
	v_fma_f32 v5, s46, v9, v5
	v_fma_f32 v6, s46, v10, v6
	v_fma_f32 v7, s46, v11, v7
	v_fma_f32 v16, s47, v4, -v12
	v_fma_f32 v17, s47, v5, -v13
	v_fma_f32 v18, s47, v6, -v14
	v_fma_f32 v19, s47, v7, -v15
	v_cvt_pk_bf16_f32 v38, v16, v17
	v_cvt_pk_bf16_f32 v39, v18, v19
	global_store_dwordx2 v0, v[38:39], s[24:25] offset:3584
	v_fma_f32 v4, -s48, v22, v4
	v_fma_f32 v5, -s48, v23, v5
	v_fma_f32 v6, -s48, v24, v6
	v_fma_f32 v7, -s48, v25, v7
	v_readlane_b32 s46, v26, 17
	v_readlane_b32 s47, v27, 16
	v_readlane_b32 s48, v26, 16
	s_waitcnt vmcnt(52)
	v_lshlrev_b32_e32 v8, 16, v78
	v_and_b32_e32 v9, 0xffff0000, v78
	v_lshlrev_b32_e32 v10, 16, v79
	v_and_b32_e32 v11, 0xffff0000, v79
	v_lshlrev_b32_e32 v22, 16, v76
	v_and_b32_e32 v23, 0xffff0000, v76
	v_lshlrev_b32_e32 v24, 16, v77
	v_and_b32_e32 v25, 0xffff0000, v77
	v_mul_f32_e32 v12, s46, v8
	v_mul_f32_e32 v13, s46, v9
	v_mul_f32_e32 v14, s46, v10
	v_mul_f32_e32 v15, s46, v11
	v_fma_f32 v4, s46, v8, v4
	v_fma_f32 v5, s46, v9, v5
	v_fma_f32 v6, s46, v10, v6
	v_fma_f32 v7, s46, v11, v7
	v_fma_f32 v16, s47, v4, -v12
	v_fma_f32 v17, s47, v5, -v13
	v_fma_f32 v18, s47, v6, -v14
	v_fma_f32 v19, s47, v7, -v15
	v_cvt_pk_bf16_f32 v20, v16, v17
	v_cvt_pk_bf16_f32 v21, v18, v19
	s_add_u32 s24, s24, 0x1000
	s_addc_u32 s25, s25, 0
	global_store_dwordx2 v0, v[20:21], s[24:25]
	v_fma_f32 v4, -s48, v22, v4
	v_fma_f32 v5, -s48, v23, v5
	v_fma_f32 v6, -s48, v24, v6
	v_fma_f32 v7, -s48, v25, v7
	v_readlane_b32 s46, v26, 18
	v_readlane_b32 s47, v27, 17
	v_readlane_b32 s48, v26, 17
	s_waitcnt vmcnt(52)
	v_lshlrev_b32_e32 v8, 16, v80
	v_and_b32_e32 v9, 0xffff0000, v80
	v_lshlrev_b32_e32 v10, 16, v81
	v_and_b32_e32 v11, 0xffff0000, v81
	v_lshlrev_b32_e32 v22, 16, v78
	v_and_b32_e32 v23, 0xffff0000, v78
	v_lshlrev_b32_e32 v24, 16, v79
	v_and_b32_e32 v25, 0xffff0000, v79
	v_mul_f32_e32 v12, s46, v8
	v_mul_f32_e32 v13, s46, v9
	v_mul_f32_e32 v14, s46, v10
	v_mul_f32_e32 v15, s46, v11
	v_fma_f32 v4, s46, v8, v4
	v_fma_f32 v5, s46, v9, v5
	v_fma_f32 v6, s46, v10, v6
	v_fma_f32 v7, s46, v11, v7
	v_fma_f32 v16, s47, v4, -v12
	v_fma_f32 v17, s47, v5, -v13
	v_fma_f32 v18, s47, v6, -v14
	v_fma_f32 v19, s47, v7, -v15
	v_cvt_pk_bf16_f32 v38, v16, v17
	v_cvt_pk_bf16_f32 v39, v18, v19
	global_store_dwordx2 v0, v[38:39], s[24:25] offset:512
	v_fma_f32 v4, -s48, v22, v4
	v_fma_f32 v5, -s48, v23, v5
	v_fma_f32 v6, -s48, v24, v6
	v_fma_f32 v7, -s48, v25, v7
	v_readlane_b32 s46, v26, 19
	v_readlane_b32 s47, v27, 18
	v_readlane_b32 s48, v26, 18
	s_waitcnt vmcnt(52)
	v_lshlrev_b32_e32 v8, 16, v82
	v_and_b32_e32 v9, 0xffff0000, v82
	v_lshlrev_b32_e32 v10, 16, v83
	v_and_b32_e32 v11, 0xffff0000, v83
	v_lshlrev_b32_e32 v22, 16, v80
	v_and_b32_e32 v23, 0xffff0000, v80
	v_lshlrev_b32_e32 v24, 16, v81
	v_and_b32_e32 v25, 0xffff0000, v81
	v_mul_f32_e32 v12, s46, v8
	v_mul_f32_e32 v13, s46, v9
	v_mul_f32_e32 v14, s46, v10
	v_mul_f32_e32 v15, s46, v11
	v_fma_f32 v4, s46, v8, v4
	v_fma_f32 v5, s46, v9, v5
	v_fma_f32 v6, s46, v10, v6
	v_fma_f32 v7, s46, v11, v7
	v_fma_f32 v16, s47, v4, -v12
	v_fma_f32 v17, s47, v5, -v13
	v_fma_f32 v18, s47, v6, -v14
	v_fma_f32 v19, s47, v7, -v15
	v_cvt_pk_bf16_f32 v20, v16, v17
	v_cvt_pk_bf16_f32 v21, v18, v19
	global_store_dwordx2 v0, v[20:21], s[24:25] offset:1024
	v_fma_f32 v4, -s48, v22, v4
	v_fma_f32 v5, -s48, v23, v5
	v_fma_f32 v6, -s48, v24, v6
	v_fma_f32 v7, -s48, v25, v7
	v_readlane_b32 s46, v26, 20
	v_readlane_b32 s47, v27, 19
	v_readlane_b32 s48, v26, 19
	s_waitcnt vmcnt(52)
	v_lshlrev_b32_e32 v8, 16, v84
	v_and_b32_e32 v9, 0xffff0000, v84
	v_lshlrev_b32_e32 v10, 16, v85
	v_and_b32_e32 v11, 0xffff0000, v85
	v_lshlrev_b32_e32 v22, 16, v82
	v_and_b32_e32 v23, 0xffff0000, v82
	v_lshlrev_b32_e32 v24, 16, v83
	v_and_b32_e32 v25, 0xffff0000, v83
	v_mul_f32_e32 v12, s46, v8
	v_mul_f32_e32 v13, s46, v9
	v_mul_f32_e32 v14, s46, v10
	v_mul_f32_e32 v15, s46, v11
	v_fma_f32 v4, s46, v8, v4
	v_fma_f32 v5, s46, v9, v5
	v_fma_f32 v6, s46, v10, v6
	v_fma_f32 v7, s46, v11, v7
	v_fma_f32 v16, s47, v4, -v12
	v_fma_f32 v17, s47, v5, -v13
	v_fma_f32 v18, s47, v6, -v14
	v_fma_f32 v19, s47, v7, -v15
	v_cvt_pk_bf16_f32 v38, v16, v17
	v_cvt_pk_bf16_f32 v39, v18, v19
	global_store_dwordx2 v0, v[38:39], s[24:25] offset:1536
	v_fma_f32 v4, -s48, v22, v4
	v_fma_f32 v5, -s48, v23, v5
	v_fma_f32 v6, -s48, v24, v6
	v_fma_f32 v7, -s48, v25, v7
	v_readlane_b32 s46, v26, 21
	v_readlane_b32 s47, v27, 20
	v_readlane_b32 s48, v26, 20
	s_waitcnt vmcnt(52)
	v_lshlrev_b32_e32 v8, 16, v86
	v_and_b32_e32 v9, 0xffff0000, v86
	v_lshlrev_b32_e32 v10, 16, v87
	v_and_b32_e32 v11, 0xffff0000, v87
	v_lshlrev_b32_e32 v22, 16, v84
	v_and_b32_e32 v23, 0xffff0000, v84
	v_lshlrev_b32_e32 v24, 16, v85
	v_and_b32_e32 v25, 0xffff0000, v85
	v_mul_f32_e32 v12, s46, v8
	v_mul_f32_e32 v13, s46, v9
	v_mul_f32_e32 v14, s46, v10
	v_mul_f32_e32 v15, s46, v11
	v_fma_f32 v4, s46, v8, v4
	v_fma_f32 v5, s46, v9, v5
	v_fma_f32 v6, s46, v10, v6
	v_fma_f32 v7, s46, v11, v7
	v_fma_f32 v16, s47, v4, -v12
	v_fma_f32 v17, s47, v5, -v13
	v_fma_f32 v18, s47, v6, -v14
	v_fma_f32 v19, s47, v7, -v15
	v_cvt_pk_bf16_f32 v20, v16, v17
	v_cvt_pk_bf16_f32 v21, v18, v19
	global_store_dwordx2 v0, v[20:21], s[24:25] offset:2048
	v_fma_f32 v4, -s48, v22, v4
	v_fma_f32 v5, -s48, v23, v5
	v_fma_f32 v6, -s48, v24, v6
	v_fma_f32 v7, -s48, v25, v7
	v_readlane_b32 s46, v26, 22
	v_readlane_b32 s47, v27, 21
	v_readlane_b32 s48, v26, 21
	s_waitcnt vmcnt(52)
	v_lshlrev_b32_e32 v8, 16, v88
	v_and_b32_e32 v9, 0xffff0000, v88
	v_lshlrev_b32_e32 v10, 16, v89
	v_and_b32_e32 v11, 0xffff0000, v89
	v_lshlrev_b32_e32 v22, 16, v86
	v_and_b32_e32 v23, 0xffff0000, v86
	v_lshlrev_b32_e32 v24, 16, v87
	v_and_b32_e32 v25, 0xffff0000, v87
	v_mul_f32_e32 v12, s46, v8
	v_mul_f32_e32 v13, s46, v9
	v_mul_f32_e32 v14, s46, v10
	v_mul_f32_e32 v15, s46, v11
	v_fma_f32 v4, s46, v8, v4
	v_fma_f32 v5, s46, v9, v5
	v_fma_f32 v6, s46, v10, v6
	v_fma_f32 v7, s46, v11, v7
	v_fma_f32 v16, s47, v4, -v12
	v_fma_f32 v17, s47, v5, -v13
	v_fma_f32 v18, s47, v6, -v14
	v_fma_f32 v19, s47, v7, -v15
	v_cvt_pk_bf16_f32 v38, v16, v17
	v_cvt_pk_bf16_f32 v39, v18, v19
	global_store_dwordx2 v0, v[38:39], s[24:25] offset:2560
	v_fma_f32 v4, -s48, v22, v4
	v_fma_f32 v5, -s48, v23, v5
	v_fma_f32 v6, -s48, v24, v6
	v_fma_f32 v7, -s48, v25, v7
	v_readlane_b32 s46, v26, 23
	v_readlane_b32 s47, v27, 22
	v_readlane_b32 s48, v26, 22
	s_waitcnt vmcnt(52)
	v_lshlrev_b32_e32 v8, 16, v90
	v_and_b32_e32 v9, 0xffff0000, v90
	v_lshlrev_b32_e32 v10, 16, v91
	v_and_b32_e32 v11, 0xffff0000, v91
	v_lshlrev_b32_e32 v22, 16, v88
	v_and_b32_e32 v23, 0xffff0000, v88
	v_lshlrev_b32_e32 v24, 16, v89
	v_and_b32_e32 v25, 0xffff0000, v89
	v_mul_f32_e32 v12, s46, v8
	v_mul_f32_e32 v13, s46, v9
	v_mul_f32_e32 v14, s46, v10
	v_mul_f32_e32 v15, s46, v11
	v_fma_f32 v4, s46, v8, v4
	v_fma_f32 v5, s46, v9, v5
	v_fma_f32 v6, s46, v10, v6
	v_fma_f32 v7, s46, v11, v7
	v_fma_f32 v16, s47, v4, -v12
	v_fma_f32 v17, s47, v5, -v13
	v_fma_f32 v18, s47, v6, -v14
	v_fma_f32 v19, s47, v7, -v15
	v_cvt_pk_bf16_f32 v20, v16, v17
	v_cvt_pk_bf16_f32 v21, v18, v19
	global_store_dwordx2 v0, v[20:21], s[24:25] offset:3072
	v_fma_f32 v4, -s48, v22, v4
	v_fma_f32 v5, -s48, v23, v5
	v_fma_f32 v6, -s48, v24, v6
	v_fma_f32 v7, -s48, v25, v7
	v_readlane_b32 s46, v26, 24
	v_readlane_b32 s47, v27, 23
	v_readlane_b32 s48, v26, 23
	s_waitcnt vmcnt(52)
	v_lshlrev_b32_e32 v8, 16, v92
	v_and_b32_e32 v9, 0xffff0000, v92
	v_lshlrev_b32_e32 v10, 16, v93
	v_and_b32_e32 v11, 0xffff0000, v93
	v_lshlrev_b32_e32 v22, 16, v90
	v_and_b32_e32 v23, 0xffff0000, v90
	v_lshlrev_b32_e32 v24, 16, v91
	v_and_b32_e32 v25, 0xffff0000, v91
	v_mul_f32_e32 v12, s46, v8
	v_mul_f32_e32 v13, s46, v9
	v_mul_f32_e32 v14, s46, v10
	v_mul_f32_e32 v15, s46, v11
	v_fma_f32 v4, s46, v8, v4
	v_fma_f32 v5, s46, v9, v5
	v_fma_f32 v6, s46, v10, v6
	v_fma_f32 v7, s46, v11, v7
	v_fma_f32 v16, s47, v4, -v12
	v_fma_f32 v17, s47, v5, -v13
	v_fma_f32 v18, s47, v6, -v14
	v_fma_f32 v19, s47, v7, -v15
	v_cvt_pk_bf16_f32 v38, v16, v17
	v_cvt_pk_bf16_f32 v39, v18, v19
	global_store_dwordx2 v0, v[38:39], s[24:25] offset:3584
	v_fma_f32 v4, -s48, v22, v4
	v_fma_f32 v5, -s48, v23, v5
	v_fma_f32 v6, -s48, v24, v6
	v_fma_f32 v7, -s48, v25, v7
	v_readlane_b32 s46, v26, 25
	v_readlane_b32 s47, v27, 24
	v_readlane_b32 s48, v26, 24
	s_waitcnt vmcnt(52)
	v_lshlrev_b32_e32 v8, 16, v94
	v_and_b32_e32 v9, 0xffff0000, v94
	v_lshlrev_b32_e32 v10, 16, v95
	v_and_b32_e32 v11, 0xffff0000, v95
	v_lshlrev_b32_e32 v22, 16, v92
	v_and_b32_e32 v23, 0xffff0000, v92
	v_lshlrev_b32_e32 v24, 16, v93
	v_and_b32_e32 v25, 0xffff0000, v93
	v_mul_f32_e32 v12, s46, v8
	v_mul_f32_e32 v13, s46, v9
	v_mul_f32_e32 v14, s46, v10
	v_mul_f32_e32 v15, s46, v11
	v_fma_f32 v4, s46, v8, v4
	v_fma_f32 v5, s46, v9, v5
	v_fma_f32 v6, s46, v10, v6
	v_fma_f32 v7, s46, v11, v7
	v_fma_f32 v16, s47, v4, -v12
	v_fma_f32 v17, s47, v5, -v13
	v_fma_f32 v18, s47, v6, -v14
	v_fma_f32 v19, s47, v7, -v15
	v_cvt_pk_bf16_f32 v20, v16, v17
	v_cvt_pk_bf16_f32 v21, v18, v19
	s_add_u32 s24, s24, 0x1000
	s_addc_u32 s25, s25, 0
	global_store_dwordx2 v0, v[20:21], s[24:25]
	v_fma_f32 v4, -s48, v22, v4
	v_fma_f32 v5, -s48, v23, v5
	v_fma_f32 v6, -s48, v24, v6
	v_fma_f32 v7, -s48, v25, v7
	v_readlane_b32 s46, v26, 26
	v_readlane_b32 s47, v27, 25
	v_readlane_b32 s48, v26, 25
	s_waitcnt vmcnt(52)
	v_lshlrev_b32_e32 v8, 16, v96
	v_and_b32_e32 v9, 0xffff0000, v96
	v_lshlrev_b32_e32 v10, 16, v97
	v_and_b32_e32 v11, 0xffff0000, v97
	v_lshlrev_b32_e32 v22, 16, v94
	v_and_b32_e32 v23, 0xffff0000, v94
	v_lshlrev_b32_e32 v24, 16, v95
	v_and_b32_e32 v25, 0xffff0000, v95
	v_mul_f32_e32 v12, s46, v8
	v_mul_f32_e32 v13, s46, v9
	v_mul_f32_e32 v14, s46, v10
	v_mul_f32_e32 v15, s46, v11
	v_fma_f32 v4, s46, v8, v4
	v_fma_f32 v5, s46, v9, v5
	v_fma_f32 v6, s46, v10, v6
	v_fma_f32 v7, s46, v11, v7
	v_fma_f32 v16, s47, v4, -v12
	v_fma_f32 v17, s47, v5, -v13
	v_fma_f32 v18, s47, v6, -v14
	v_fma_f32 v19, s47, v7, -v15
	v_cvt_pk_bf16_f32 v38, v16, v17
	v_cvt_pk_bf16_f32 v39, v18, v19
	global_store_dwordx2 v0, v[38:39], s[24:25] offset:512
	v_fma_f32 v4, -s48, v22, v4
	v_fma_f32 v5, -s48, v23, v5
	v_fma_f32 v6, -s48, v24, v6
	v_fma_f32 v7, -s48, v25, v7
	v_readlane_b32 s46, v26, 27
	v_readlane_b32 s47, v27, 26
	v_readlane_b32 s48, v26, 26
	s_waitcnt vmcnt(52)
	v_lshlrev_b32_e32 v8, 16, v98
	v_and_b32_e32 v9, 0xffff0000, v98
	v_lshlrev_b32_e32 v10, 16, v99
	v_and_b32_e32 v11, 0xffff0000, v99
	v_lshlrev_b32_e32 v22, 16, v96
	v_and_b32_e32 v23, 0xffff0000, v96
	v_lshlrev_b32_e32 v24, 16, v97
	v_and_b32_e32 v25, 0xffff0000, v97
	v_mul_f32_e32 v12, s46, v8
	v_mul_f32_e32 v13, s46, v9
	v_mul_f32_e32 v14, s46, v10
	v_mul_f32_e32 v15, s46, v11
	v_fma_f32 v4, s46, v8, v4
	v_fma_f32 v5, s46, v9, v5
	v_fma_f32 v6, s46, v10, v6
	v_fma_f32 v7, s46, v11, v7
	v_fma_f32 v16, s47, v4, -v12
	v_fma_f32 v17, s47, v5, -v13
	v_fma_f32 v18, s47, v6, -v14
	v_fma_f32 v19, s47, v7, -v15
	v_cvt_pk_bf16_f32 v20, v16, v17
	v_cvt_pk_bf16_f32 v21, v18, v19
	global_store_dwordx2 v0, v[20:21], s[24:25] offset:1024
	v_fma_f32 v4, -s48, v22, v4
	v_fma_f32 v5, -s48, v23, v5
	v_fma_f32 v6, -s48, v24, v6
	v_fma_f32 v7, -s48, v25, v7
	v_readlane_b32 s46, v26, 28
	v_readlane_b32 s47, v27, 27
	v_readlane_b32 s48, v26, 27
	s_waitcnt vmcnt(52)
	v_lshlrev_b32_e32 v8, 16, v100
	v_and_b32_e32 v9, 0xffff0000, v100
	v_lshlrev_b32_e32 v10, 16, v101
	v_and_b32_e32 v11, 0xffff0000, v101
	v_lshlrev_b32_e32 v22, 16, v98
	v_and_b32_e32 v23, 0xffff0000, v98
	v_lshlrev_b32_e32 v24, 16, v99
	v_and_b32_e32 v25, 0xffff0000, v99
	v_mul_f32_e32 v12, s46, v8
	v_mul_f32_e32 v13, s46, v9
	v_mul_f32_e32 v14, s46, v10
	v_mul_f32_e32 v15, s46, v11
	v_fma_f32 v4, s46, v8, v4
	v_fma_f32 v5, s46, v9, v5
	v_fma_f32 v6, s46, v10, v6
	v_fma_f32 v7, s46, v11, v7
	v_fma_f32 v16, s47, v4, -v12
	v_fma_f32 v17, s47, v5, -v13
	v_fma_f32 v18, s47, v6, -v14
	v_fma_f32 v19, s47, v7, -v15
	v_cvt_pk_bf16_f32 v38, v16, v17
	v_cvt_pk_bf16_f32 v39, v18, v19
	global_store_dwordx2 v0, v[38:39], s[24:25] offset:1536
	v_fma_f32 v4, -s48, v22, v4
	v_fma_f32 v5, -s48, v23, v5
	v_fma_f32 v6, -s48, v24, v6
	v_fma_f32 v7, -s48, v25, v7
	v_readlane_b32 s46, v26, 29
	v_readlane_b32 s47, v27, 28
	v_readlane_b32 s48, v26, 28
	s_waitcnt vmcnt(52)
	v_lshlrev_b32_e32 v8, 16, v102
	v_and_b32_e32 v9, 0xffff0000, v102
	v_lshlrev_b32_e32 v10, 16, v103
	v_and_b32_e32 v11, 0xffff0000, v103
	v_lshlrev_b32_e32 v22, 16, v100
	v_and_b32_e32 v23, 0xffff0000, v100
	v_lshlrev_b32_e32 v24, 16, v101
	v_and_b32_e32 v25, 0xffff0000, v101
	v_mul_f32_e32 v12, s46, v8
	v_mul_f32_e32 v13, s46, v9
	v_mul_f32_e32 v14, s46, v10
	v_mul_f32_e32 v15, s46, v11
	v_fma_f32 v4, s46, v8, v4
	v_fma_f32 v5, s46, v9, v5
	v_fma_f32 v6, s46, v10, v6
	v_fma_f32 v7, s46, v11, v7
	v_fma_f32 v16, s47, v4, -v12
	v_fma_f32 v17, s47, v5, -v13
	v_fma_f32 v18, s47, v6, -v14
	v_fma_f32 v19, s47, v7, -v15
	v_cvt_pk_bf16_f32 v20, v16, v17
	v_cvt_pk_bf16_f32 v21, v18, v19
	global_store_dwordx2 v0, v[20:21], s[24:25] offset:2048
	v_fma_f32 v4, -s48, v22, v4
	v_fma_f32 v5, -s48, v23, v5
	v_fma_f32 v6, -s48, v24, v6
	v_fma_f32 v7, -s48, v25, v7
	v_readlane_b32 s46, v26, 30
	v_readlane_b32 s47, v27, 29
	v_readlane_b32 s48, v26, 29
	s_waitcnt vmcnt(52)
	v_lshlrev_b32_e32 v8, 16, v104
	v_and_b32_e32 v9, 0xffff0000, v104
	v_lshlrev_b32_e32 v10, 16, v105
	v_and_b32_e32 v11, 0xffff0000, v105
	v_lshlrev_b32_e32 v22, 16, v102
	v_and_b32_e32 v23, 0xffff0000, v102
	v_lshlrev_b32_e32 v24, 16, v103
	v_and_b32_e32 v25, 0xffff0000, v103
	v_mul_f32_e32 v12, s46, v8
	v_mul_f32_e32 v13, s46, v9
	v_mul_f32_e32 v14, s46, v10
	v_mul_f32_e32 v15, s46, v11
	v_fma_f32 v4, s46, v8, v4
	v_fma_f32 v5, s46, v9, v5
	v_fma_f32 v6, s46, v10, v6
	v_fma_f32 v7, s46, v11, v7
	v_fma_f32 v16, s47, v4, -v12
	v_fma_f32 v17, s47, v5, -v13
	v_fma_f32 v18, s47, v6, -v14
	v_fma_f32 v19, s47, v7, -v15
	v_cvt_pk_bf16_f32 v38, v16, v17
	v_cvt_pk_bf16_f32 v39, v18, v19
	global_store_dwordx2 v0, v[38:39], s[24:25] offset:2560
	v_fma_f32 v4, -s48, v22, v4
	v_fma_f32 v5, -s48, v23, v5
	v_fma_f32 v6, -s48, v24, v6
	v_fma_f32 v7, -s48, v25, v7
	v_readlane_b32 s46, v26, 31
	v_readlane_b32 s47, v27, 30
	v_readlane_b32 s48, v26, 30
	s_waitcnt vmcnt(52)
	v_lshlrev_b32_e32 v8, 16, v106
	v_and_b32_e32 v9, 0xffff0000, v106
	v_lshlrev_b32_e32 v10, 16, v107
	v_and_b32_e32 v11, 0xffff0000, v107
	v_lshlrev_b32_e32 v22, 16, v104
	v_and_b32_e32 v23, 0xffff0000, v104
	v_lshlrev_b32_e32 v24, 16, v105
	v_and_b32_e32 v25, 0xffff0000, v105
	v_mul_f32_e32 v12, s46, v8
	v_mul_f32_e32 v13, s46, v9
	v_mul_f32_e32 v14, s46, v10
	v_mul_f32_e32 v15, s46, v11
	v_fma_f32 v4, s46, v8, v4
	v_fma_f32 v5, s46, v9, v5
	v_fma_f32 v6, s46, v10, v6
	v_fma_f32 v7, s46, v11, v7
	v_fma_f32 v16, s47, v4, -v12
	v_fma_f32 v17, s47, v5, -v13
	v_fma_f32 v18, s47, v6, -v14
	v_fma_f32 v19, s47, v7, -v15
	v_cvt_pk_bf16_f32 v20, v16, v17
	v_cvt_pk_bf16_f32 v21, v18, v19
	global_store_dwordx2 v0, v[20:21], s[24:25] offset:3072
	v_fma_f32 v4, -s48, v22, v4
	v_fma_f32 v5, -s48, v23, v5
	v_fma_f32 v6, -s48, v24, v6
	v_fma_f32 v7, -s48, v25, v7
	v_readlane_b32 s46, v26, 32
	v_readlane_b32 s47, v27, 31
	v_readlane_b32 s48, v26, 31
	s_waitcnt vmcnt(52)
	v_lshlrev_b32_e32 v8, 16, v108
	v_and_b32_e32 v9, 0xffff0000, v108
	v_lshlrev_b32_e32 v10, 16, v109
	v_and_b32_e32 v11, 0xffff0000, v109
	v_lshlrev_b32_e32 v22, 16, v106
	v_and_b32_e32 v23, 0xffff0000, v106
	v_lshlrev_b32_e32 v24, 16, v107
	v_and_b32_e32 v25, 0xffff0000, v107
	v_mul_f32_e32 v12, s46, v8
	v_mul_f32_e32 v13, s46, v9
	v_mul_f32_e32 v14, s46, v10
	v_mul_f32_e32 v15, s46, v11
	v_fma_f32 v4, s46, v8, v4
	v_fma_f32 v5, s46, v9, v5
	v_fma_f32 v6, s46, v10, v6
	v_fma_f32 v7, s46, v11, v7
	v_fma_f32 v16, s47, v4, -v12
	v_fma_f32 v17, s47, v5, -v13
	v_fma_f32 v18, s47, v6, -v14
	v_fma_f32 v19, s47, v7, -v15
	v_cvt_pk_bf16_f32 v38, v16, v17
	v_cvt_pk_bf16_f32 v39, v18, v19
	global_store_dwordx2 v0, v[38:39], s[24:25] offset:3584
	v_fma_f32 v4, -s48, v22, v4
	v_fma_f32 v5, -s48, v23, v5
	v_fma_f32 v6, -s48, v24, v6
	v_fma_f32 v7, -s48, v25, v7
	v_mov_b32_e32 v4, 0
	v_mov_b32_e32 v5, 0
	v_mov_b32_e32 v6, 0
	v_mov_b32_e32 v7, 0
	v_readlane_b32 s46, v28, 0
	s_waitcnt vmcnt(52)
	v_lshlrev_b32_e32 v8, 16, v114
	v_and_b32_e32 v9, 0xffff0000, v114
	v_lshlrev_b32_e32 v10, 16, v115
	v_and_b32_e32 v11, 0xffff0000, v115
	v_fma_f32 v4, s46, v8, v4
	v_fma_f32 v5, s46, v9, v5
	v_fma_f32 v6, s46, v10, v6
	v_fma_f32 v7, s46, v11, v7
	v_readlane_b32 s46, v28, 1
	s_waitcnt vmcnt(52)
	v_lshlrev_b32_e32 v8, 16, v116
	v_and_b32_e32 v9, 0xffff0000, v116
	v_lshlrev_b32_e32 v10, 16, v117
	v_and_b32_e32 v11, 0xffff0000, v117
	v_fma_f32 v4, s46, v8, v4
	v_fma_f32 v5, s46, v9, v5
	v_fma_f32 v6, s46, v10, v6
	v_fma_f32 v7, s46, v11, v7
	v_readlane_b32 s46, v28, 2
	s_waitcnt vmcnt(52)
	v_lshlrev_b32_e32 v8, 16, v118
	v_and_b32_e32 v9, 0xffff0000, v118
	v_lshlrev_b32_e32 v10, 16, v119
	v_and_b32_e32 v11, 0xffff0000, v119
	v_fma_f32 v4, s46, v8, v4
	v_fma_f32 v5, s46, v9, v5
	v_fma_f32 v6, s46, v10, v6
	v_fma_f32 v7, s46, v11, v7
	v_readlane_b32 s46, v28, 3
	s_waitcnt vmcnt(52)
	v_lshlrev_b32_e32 v8, 16, v120
	v_and_b32_e32 v9, 0xffff0000, v120
	v_lshlrev_b32_e32 v10, 16, v121
	v_and_b32_e32 v11, 0xffff0000, v121
	v_fma_f32 v4, s46, v8, v4
	v_fma_f32 v5, s46, v9, v5
	v_fma_f32 v6, s46, v10, v6
	v_fma_f32 v7, s46, v11, v7
	v_readlane_b32 s46, v28, 4
	s_waitcnt vmcnt(52)
	v_lshlrev_b32_e32 v8, 16, v122
	v_and_b32_e32 v9, 0xffff0000, v122
	v_lshlrev_b32_e32 v10, 16, v123
	v_and_b32_e32 v11, 0xffff0000, v123
	v_fma_f32 v4, s46, v8, v4
	v_fma_f32 v5, s46, v9, v5
	v_fma_f32 v6, s46, v10, v6
	v_fma_f32 v7, s46, v11, v7
	v_readlane_b32 s46, v28, 5
	s_waitcnt vmcnt(52)
	v_lshlrev_b32_e32 v8, 16, v124
	v_and_b32_e32 v9, 0xffff0000, v124
	v_lshlrev_b32_e32 v10, 16, v125
	v_and_b32_e32 v11, 0xffff0000, v125
	v_fma_f32 v4, s46, v8, v4
	v_fma_f32 v5, s46, v9, v5
	v_fma_f32 v6, s46, v10, v6
	v_fma_f32 v7, s46, v11, v7
	v_readlane_b32 s46, v28, 6
	s_waitcnt vmcnt(52)
	v_lshlrev_b32_e32 v8, 16, v126
	v_and_b32_e32 v9, 0xffff0000, v126
	v_lshlrev_b32_e32 v10, 16, v127
	v_and_b32_e32 v11, 0xffff0000, v127
	v_fma_f32 v4, s46, v8, v4
	v_fma_f32 v5, s46, v9, v5
	v_fma_f32 v6, s46, v10, v6
	v_fma_f32 v7, s46, v11, v7
	v_readlane_b32 s46, v28, 7
	v_readlane_b32 s47, v29, 0
	v_readlane_b32 s48, v28, 0
	s_waitcnt vmcnt(52)
	v_lshlrev_b32_e32 v8, 16, v128
	v_and_b32_e32 v9, 0xffff0000, v128
	v_lshlrev_b32_e32 v10, 16, v129
	v_and_b32_e32 v11, 0xffff0000, v129
	v_lshlrev_b32_e32 v22, 16, v114
	v_and_b32_e32 v23, 0xffff0000, v114
	v_lshlrev_b32_e32 v24, 16, v115
	v_and_b32_e32 v25, 0xffff0000, v115
	v_mul_f32_e32 v12, s46, v8
	v_mul_f32_e32 v13, s46, v9
	v_mul_f32_e32 v14, s46, v10
	v_mul_f32_e32 v15, s46, v11
	v_fma_f32 v4, s46, v8, v4
	v_fma_f32 v5, s46, v9, v5
	v_fma_f32 v6, s46, v10, v6
	v_fma_f32 v7, s46, v11, v7
	v_fma_f32 v16, s47, v4, -v12
	v_fma_f32 v17, s47, v5, -v13
	v_fma_f32 v18, s47, v6, -v14
	v_fma_f32 v19, s47, v7, -v15
	v_cvt_pk_bf16_f32 v20, v16, v17
	v_cvt_pk_bf16_f32 v21, v18, v19
	global_store_dwordx2 v0, v[20:21], s[40:41]
	v_fma_f32 v4, -s48, v22, v4
	v_fma_f32 v5, -s48, v23, v5
	v_fma_f32 v6, -s48, v24, v6
	v_fma_f32 v7, -s48, v25, v7
	v_readlane_b32 s46, v28, 8
	v_readlane_b32 s47, v29, 1
	v_readlane_b32 s48, v28, 1
	s_waitcnt vmcnt(52)
	v_lshlrev_b32_e32 v8, 16, v130
	v_and_b32_e32 v9, 0xffff0000, v130
	v_lshlrev_b32_e32 v10, 16, v131
	v_and_b32_e32 v11, 0xffff0000, v131
	v_lshlrev_b32_e32 v22, 16, v116
	v_and_b32_e32 v23, 0xffff0000, v116
	v_lshlrev_b32_e32 v24, 16, v117
	v_and_b32_e32 v25, 0xffff0000, v117
	v_mul_f32_e32 v12, s46, v8
	v_mul_f32_e32 v13, s46, v9
	v_mul_f32_e32 v14, s46, v10
	v_mul_f32_e32 v15, s46, v11
	v_fma_f32 v4, s46, v8, v4
	v_fma_f32 v5, s46, v9, v5
	v_fma_f32 v6, s46, v10, v6
	v_fma_f32 v7, s46, v11, v7
	v_fma_f32 v16, s47, v4, -v12
	v_fma_f32 v17, s47, v5, -v13
	v_fma_f32 v18, s47, v6, -v14
	v_fma_f32 v19, s47, v7, -v15
	v_cvt_pk_bf16_f32 v38, v16, v17
	v_cvt_pk_bf16_f32 v39, v18, v19
	global_store_dwordx2 v0, v[38:39], s[40:41] offset:512
	v_fma_f32 v4, -s48, v22, v4
	v_fma_f32 v5, -s48, v23, v5
	v_fma_f32 v6, -s48, v24, v6
	v_fma_f32 v7, -s48, v25, v7
	v_readlane_b32 s46, v28, 9
	v_readlane_b32 s47, v29, 2
	v_readlane_b32 s48, v28, 2
	s_waitcnt vmcnt(52)
	v_lshlrev_b32_e32 v8, 16, v132
	v_and_b32_e32 v9, 0xffff0000, v132
	v_lshlrev_b32_e32 v10, 16, v133
	v_and_b32_e32 v11, 0xffff0000, v133
	v_lshlrev_b32_e32 v22, 16, v118
	v_and_b32_e32 v23, 0xffff0000, v118
	v_lshlrev_b32_e32 v24, 16, v119
	v_and_b32_e32 v25, 0xffff0000, v119
	v_mul_f32_e32 v12, s46, v8
	v_mul_f32_e32 v13, s46, v9
	v_mul_f32_e32 v14, s46, v10
	v_mul_f32_e32 v15, s46, v11
	v_fma_f32 v4, s46, v8, v4
	v_fma_f32 v5, s46, v9, v5
	v_fma_f32 v6, s46, v10, v6
	v_fma_f32 v7, s46, v11, v7
	v_fma_f32 v16, s47, v4, -v12
	v_fma_f32 v17, s47, v5, -v13
	v_fma_f32 v18, s47, v6, -v14
	v_fma_f32 v19, s47, v7, -v15
	v_cvt_pk_bf16_f32 v20, v16, v17
	v_cvt_pk_bf16_f32 v21, v18, v19
	global_store_dwordx2 v0, v[20:21], s[40:41] offset:1024
	v_fma_f32 v4, -s48, v22, v4
	v_fma_f32 v5, -s48, v23, v5
	v_fma_f32 v6, -s48, v24, v6
	v_fma_f32 v7, -s48, v25, v7
	v_readlane_b32 s46, v28, 10
	v_readlane_b32 s47, v29, 3
	v_readlane_b32 s48, v28, 3
	s_waitcnt vmcnt(52)
	v_lshlrev_b32_e32 v8, 16, v134
	v_and_b32_e32 v9, 0xffff0000, v134
	v_lshlrev_b32_e32 v10, 16, v135
	v_and_b32_e32 v11, 0xffff0000, v135
	v_lshlrev_b32_e32 v22, 16, v120
	v_and_b32_e32 v23, 0xffff0000, v120
	v_lshlrev_b32_e32 v24, 16, v121
	v_and_b32_e32 v25, 0xffff0000, v121
	v_mul_f32_e32 v12, s46, v8
	v_mul_f32_e32 v13, s46, v9
	v_mul_f32_e32 v14, s46, v10
	v_mul_f32_e32 v15, s46, v11
	v_fma_f32 v4, s46, v8, v4
	v_fma_f32 v5, s46, v9, v5
	v_fma_f32 v6, s46, v10, v6
	v_fma_f32 v7, s46, v11, v7
	v_fma_f32 v16, s47, v4, -v12
	v_fma_f32 v17, s47, v5, -v13
	v_fma_f32 v18, s47, v6, -v14
	v_fma_f32 v19, s47, v7, -v15
	v_cvt_pk_bf16_f32 v38, v16, v17
	v_cvt_pk_bf16_f32 v39, v18, v19
	global_store_dwordx2 v0, v[38:39], s[40:41] offset:1536
	v_fma_f32 v4, -s48, v22, v4
	v_fma_f32 v5, -s48, v23, v5
	v_fma_f32 v6, -s48, v24, v6
	v_fma_f32 v7, -s48, v25, v7
	v_readlane_b32 s46, v28, 11
	v_readlane_b32 s47, v29, 4
	v_readlane_b32 s48, v28, 4
	s_waitcnt vmcnt(52)
	v_lshlrev_b32_e32 v8, 16, v136
	v_and_b32_e32 v9, 0xffff0000, v136
	v_lshlrev_b32_e32 v10, 16, v137
	v_and_b32_e32 v11, 0xffff0000, v137
	v_lshlrev_b32_e32 v22, 16, v122
	v_and_b32_e32 v23, 0xffff0000, v122
	v_lshlrev_b32_e32 v24, 16, v123
	v_and_b32_e32 v25, 0xffff0000, v123
	v_mul_f32_e32 v12, s46, v8
	v_mul_f32_e32 v13, s46, v9
	v_mul_f32_e32 v14, s46, v10
	v_mul_f32_e32 v15, s46, v11
	v_fma_f32 v4, s46, v8, v4
	v_fma_f32 v5, s46, v9, v5
	v_fma_f32 v6, s46, v10, v6
	v_fma_f32 v7, s46, v11, v7
	v_fma_f32 v16, s47, v4, -v12
	v_fma_f32 v17, s47, v5, -v13
	v_fma_f32 v18, s47, v6, -v14
	v_fma_f32 v19, s47, v7, -v15
	v_cvt_pk_bf16_f32 v20, v16, v17
	v_cvt_pk_bf16_f32 v21, v18, v19
	global_store_dwordx2 v0, v[20:21], s[40:41] offset:2048
	v_fma_f32 v4, -s48, v22, v4
	v_fma_f32 v5, -s48, v23, v5
	v_fma_f32 v6, -s48, v24, v6
	v_fma_f32 v7, -s48, v25, v7
	v_readlane_b32 s46, v28, 12
	v_readlane_b32 s47, v29, 5
	v_readlane_b32 s48, v28, 5
	s_waitcnt vmcnt(52)
	v_lshlrev_b32_e32 v8, 16, v138
	v_and_b32_e32 v9, 0xffff0000, v138
	v_lshlrev_b32_e32 v10, 16, v139
	v_and_b32_e32 v11, 0xffff0000, v139
	v_lshlrev_b32_e32 v22, 16, v124
	v_and_b32_e32 v23, 0xffff0000, v124
	v_lshlrev_b32_e32 v24, 16, v125
	v_and_b32_e32 v25, 0xffff0000, v125
	v_mul_f32_e32 v12, s46, v8
	v_mul_f32_e32 v13, s46, v9
	v_mul_f32_e32 v14, s46, v10
	v_mul_f32_e32 v15, s46, v11
	v_fma_f32 v4, s46, v8, v4
	v_fma_f32 v5, s46, v9, v5
	v_fma_f32 v6, s46, v10, v6
	v_fma_f32 v7, s46, v11, v7
	v_fma_f32 v16, s47, v4, -v12
	v_fma_f32 v17, s47, v5, -v13
	v_fma_f32 v18, s47, v6, -v14
	v_fma_f32 v19, s47, v7, -v15
	v_cvt_pk_bf16_f32 v38, v16, v17
	v_cvt_pk_bf16_f32 v39, v18, v19
	global_store_dwordx2 v0, v[38:39], s[40:41] offset:2560
	v_fma_f32 v4, -s48, v22, v4
	v_fma_f32 v5, -s48, v23, v5
	v_fma_f32 v6, -s48, v24, v6
	v_fma_f32 v7, -s48, v25, v7
	v_readlane_b32 s46, v28, 13
	v_readlane_b32 s47, v29, 6
	v_readlane_b32 s48, v28, 6
	s_waitcnt vmcnt(52)
	v_lshlrev_b32_e32 v8, 16, v140
	v_and_b32_e32 v9, 0xffff0000, v140
	v_lshlrev_b32_e32 v10, 16, v141
	v_and_b32_e32 v11, 0xffff0000, v141
	v_lshlrev_b32_e32 v22, 16, v126
	v_and_b32_e32 v23, 0xffff0000, v126
	v_lshlrev_b32_e32 v24, 16, v127
	v_and_b32_e32 v25, 0xffff0000, v127
	v_mul_f32_e32 v12, s46, v8
	v_mul_f32_e32 v13, s46, v9
	v_mul_f32_e32 v14, s46, v10
	v_mul_f32_e32 v15, s46, v11
	v_fma_f32 v4, s46, v8, v4
	v_fma_f32 v5, s46, v9, v5
	v_fma_f32 v6, s46, v10, v6
	v_fma_f32 v7, s46, v11, v7
	v_fma_f32 v16, s47, v4, -v12
	v_fma_f32 v17, s47, v5, -v13
	v_fma_f32 v18, s47, v6, -v14
	v_fma_f32 v19, s47, v7, -v15
	v_cvt_pk_bf16_f32 v20, v16, v17
	v_cvt_pk_bf16_f32 v21, v18, v19
	global_store_dwordx2 v0, v[20:21], s[40:41] offset:3072
	v_fma_f32 v4, -s48, v22, v4
	v_fma_f32 v5, -s48, v23, v5
	v_fma_f32 v6, -s48, v24, v6
	v_fma_f32 v7, -s48, v25, v7
	v_readlane_b32 s46, v28, 14
	v_readlane_b32 s47, v29, 7
	v_readlane_b32 s48, v28, 7
	s_waitcnt vmcnt(52)
	v_lshlrev_b32_e32 v8, 16, v142
	v_and_b32_e32 v9, 0xffff0000, v142
	v_lshlrev_b32_e32 v10, 16, v143
	v_and_b32_e32 v11, 0xffff0000, v143
	v_lshlrev_b32_e32 v22, 16, v128
	v_and_b32_e32 v23, 0xffff0000, v128
	v_lshlrev_b32_e32 v24, 16, v129
	v_and_b32_e32 v25, 0xffff0000, v129
	v_mul_f32_e32 v12, s46, v8
	v_mul_f32_e32 v13, s46, v9
	v_mul_f32_e32 v14, s46, v10
	v_mul_f32_e32 v15, s46, v11
	v_fma_f32 v4, s46, v8, v4
	v_fma_f32 v5, s46, v9, v5
	v_fma_f32 v6, s46, v10, v6
	v_fma_f32 v7, s46, v11, v7
	v_fma_f32 v16, s47, v4, -v12
	v_fma_f32 v17, s47, v5, -v13
	v_fma_f32 v18, s47, v6, -v14
	v_fma_f32 v19, s47, v7, -v15
	v_cvt_pk_bf16_f32 v38, v16, v17
	v_cvt_pk_bf16_f32 v39, v18, v19
	global_store_dwordx2 v0, v[38:39], s[40:41] offset:3584
	v_fma_f32 v4, -s48, v22, v4
	v_fma_f32 v5, -s48, v23, v5
	v_fma_f32 v6, -s48, v24, v6
	v_fma_f32 v7, -s48, v25, v7
	v_readlane_b32 s46, v28, 15
	v_readlane_b32 s47, v29, 8
	v_readlane_b32 s48, v28, 8
	s_waitcnt vmcnt(52)
	v_lshlrev_b32_e32 v8, 16, v144
	v_and_b32_e32 v9, 0xffff0000, v144
	v_lshlrev_b32_e32 v10, 16, v145
	v_and_b32_e32 v11, 0xffff0000, v145
	v_lshlrev_b32_e32 v22, 16, v130
	v_and_b32_e32 v23, 0xffff0000, v130
	v_lshlrev_b32_e32 v24, 16, v131
	v_and_b32_e32 v25, 0xffff0000, v131
	v_mul_f32_e32 v12, s46, v8
	v_mul_f32_e32 v13, s46, v9
	v_mul_f32_e32 v14, s46, v10
	v_mul_f32_e32 v15, s46, v11
	v_fma_f32 v4, s46, v8, v4
	v_fma_f32 v5, s46, v9, v5
	v_fma_f32 v6, s46, v10, v6
	v_fma_f32 v7, s46, v11, v7
	v_fma_f32 v16, s47, v4, -v12
	v_fma_f32 v17, s47, v5, -v13
	v_fma_f32 v18, s47, v6, -v14
	v_fma_f32 v19, s47, v7, -v15
	v_cvt_pk_bf16_f32 v20, v16, v17
	v_cvt_pk_bf16_f32 v21, v18, v19
	s_add_u32 s40, s40, 0x1000
	s_addc_u32 s41, s41, 0
	global_store_dwordx2 v0, v[20:21], s[40:41]
	v_fma_f32 v4, -s48, v22, v4
	v_fma_f32 v5, -s48, v23, v5
	v_fma_f32 v6, -s48, v24, v6
	v_fma_f32 v7, -s48, v25, v7
	v_readlane_b32 s46, v28, 16
	v_readlane_b32 s47, v29, 9
	v_readlane_b32 s48, v28, 9
	s_waitcnt vmcnt(52)
	v_lshlrev_b32_e32 v8, 16, v146
	v_and_b32_e32 v9, 0xffff0000, v146
	v_lshlrev_b32_e32 v10, 16, v147
	v_and_b32_e32 v11, 0xffff0000, v147
	v_lshlrev_b32_e32 v22, 16, v132
	v_and_b32_e32 v23, 0xffff0000, v132
	v_lshlrev_b32_e32 v24, 16, v133
	v_and_b32_e32 v25, 0xffff0000, v133
	v_mul_f32_e32 v12, s46, v8
	v_mul_f32_e32 v13, s46, v9
	v_mul_f32_e32 v14, s46, v10
	v_mul_f32_e32 v15, s46, v11
	v_fma_f32 v4, s46, v8, v4
	v_fma_f32 v5, s46, v9, v5
	v_fma_f32 v6, s46, v10, v6
	v_fma_f32 v7, s46, v11, v7
	v_fma_f32 v16, s47, v4, -v12
	v_fma_f32 v17, s47, v5, -v13
	v_fma_f32 v18, s47, v6, -v14
	v_fma_f32 v19, s47, v7, -v15
	v_cvt_pk_bf16_f32 v38, v16, v17
	v_cvt_pk_bf16_f32 v39, v18, v19
	global_store_dwordx2 v0, v[38:39], s[40:41] offset:512
	v_fma_f32 v4, -s48, v22, v4
	v_fma_f32 v5, -s48, v23, v5
	v_fma_f32 v6, -s48, v24, v6
	v_fma_f32 v7, -s48, v25, v7
	v_readlane_b32 s46, v28, 17
	v_readlane_b32 s47, v29, 10
	v_readlane_b32 s48, v28, 10
	s_waitcnt vmcnt(52)
	v_lshlrev_b32_e32 v8, 16, v148
	v_and_b32_e32 v9, 0xffff0000, v148
	v_lshlrev_b32_e32 v10, 16, v149
	v_and_b32_e32 v11, 0xffff0000, v149
	v_lshlrev_b32_e32 v22, 16, v134
	v_and_b32_e32 v23, 0xffff0000, v134
	v_lshlrev_b32_e32 v24, 16, v135
	v_and_b32_e32 v25, 0xffff0000, v135
	v_mul_f32_e32 v12, s46, v8
	v_mul_f32_e32 v13, s46, v9
	v_mul_f32_e32 v14, s46, v10
	v_mul_f32_e32 v15, s46, v11
	v_fma_f32 v4, s46, v8, v4
	v_fma_f32 v5, s46, v9, v5
	v_fma_f32 v6, s46, v10, v6
	v_fma_f32 v7, s46, v11, v7
	v_fma_f32 v16, s47, v4, -v12
	v_fma_f32 v17, s47, v5, -v13
	v_fma_f32 v18, s47, v6, -v14
	v_fma_f32 v19, s47, v7, -v15
	v_cvt_pk_bf16_f32 v20, v16, v17
	v_cvt_pk_bf16_f32 v21, v18, v19
	global_store_dwordx2 v0, v[20:21], s[40:41] offset:1024
	v_fma_f32 v4, -s48, v22, v4
	v_fma_f32 v5, -s48, v23, v5
	v_fma_f32 v6, -s48, v24, v6
	v_fma_f32 v7, -s48, v25, v7
	v_readlane_b32 s46, v28, 18
	v_readlane_b32 s47, v29, 11
	v_readlane_b32 s48, v28, 11
	s_waitcnt vmcnt(52)
	v_lshlrev_b32_e32 v8, 16, v150
	v_and_b32_e32 v9, 0xffff0000, v150
	v_lshlrev_b32_e32 v10, 16, v151
	v_and_b32_e32 v11, 0xffff0000, v151
	v_lshlrev_b32_e32 v22, 16, v136
	v_and_b32_e32 v23, 0xffff0000, v136
	v_lshlrev_b32_e32 v24, 16, v137
	v_and_b32_e32 v25, 0xffff0000, v137
	v_mul_f32_e32 v12, s46, v8
	v_mul_f32_e32 v13, s46, v9
	v_mul_f32_e32 v14, s46, v10
	v_mul_f32_e32 v15, s46, v11
	v_fma_f32 v4, s46, v8, v4
	v_fma_f32 v5, s46, v9, v5
	v_fma_f32 v6, s46, v10, v6
	v_fma_f32 v7, s46, v11, v7
	v_fma_f32 v16, s47, v4, -v12
	v_fma_f32 v17, s47, v5, -v13
	v_fma_f32 v18, s47, v6, -v14
	v_fma_f32 v19, s47, v7, -v15
	v_cvt_pk_bf16_f32 v38, v16, v17
	v_cvt_pk_bf16_f32 v39, v18, v19
	global_store_dwordx2 v0, v[38:39], s[40:41] offset:1536
	v_fma_f32 v4, -s48, v22, v4
	v_fma_f32 v5, -s48, v23, v5
	v_fma_f32 v6, -s48, v24, v6
	v_fma_f32 v7, -s48, v25, v7
	v_readlane_b32 s46, v28, 19
	v_readlane_b32 s47, v29, 12
	v_readlane_b32 s48, v28, 12
	s_waitcnt vmcnt(52)
	v_lshlrev_b32_e32 v8, 16, v152
	v_and_b32_e32 v9, 0xffff0000, v152
	v_lshlrev_b32_e32 v10, 16, v153
	v_and_b32_e32 v11, 0xffff0000, v153
	v_lshlrev_b32_e32 v22, 16, v138
	v_and_b32_e32 v23, 0xffff0000, v138
	v_lshlrev_b32_e32 v24, 16, v139
	v_and_b32_e32 v25, 0xffff0000, v139
	v_mul_f32_e32 v12, s46, v8
	v_mul_f32_e32 v13, s46, v9
	v_mul_f32_e32 v14, s46, v10
	v_mul_f32_e32 v15, s46, v11
	v_fma_f32 v4, s46, v8, v4
	v_fma_f32 v5, s46, v9, v5
	v_fma_f32 v6, s46, v10, v6
	v_fma_f32 v7, s46, v11, v7
	v_fma_f32 v16, s47, v4, -v12
	v_fma_f32 v17, s47, v5, -v13
	v_fma_f32 v18, s47, v6, -v14
	v_fma_f32 v19, s47, v7, -v15
	v_cvt_pk_bf16_f32 v20, v16, v17
	v_cvt_pk_bf16_f32 v21, v18, v19
	global_store_dwordx2 v0, v[20:21], s[40:41] offset:2048
	v_fma_f32 v4, -s48, v22, v4
	v_fma_f32 v5, -s48, v23, v5
	v_fma_f32 v6, -s48, v24, v6
	v_fma_f32 v7, -s48, v25, v7
	v_readlane_b32 s46, v28, 20
	v_readlane_b32 s47, v29, 13
	v_readlane_b32 s48, v28, 13
	s_waitcnt vmcnt(52)
	v_lshlrev_b32_e32 v8, 16, v154
	v_and_b32_e32 v9, 0xffff0000, v154
	v_lshlrev_b32_e32 v10, 16, v155
	v_and_b32_e32 v11, 0xffff0000, v155
	v_lshlrev_b32_e32 v22, 16, v140
	v_and_b32_e32 v23, 0xffff0000, v140
	v_lshlrev_b32_e32 v24, 16, v141
	v_and_b32_e32 v25, 0xffff0000, v141
	v_mul_f32_e32 v12, s46, v8
	v_mul_f32_e32 v13, s46, v9
	v_mul_f32_e32 v14, s46, v10
	v_mul_f32_e32 v15, s46, v11
	v_fma_f32 v4, s46, v8, v4
	v_fma_f32 v5, s46, v9, v5
	v_fma_f32 v6, s46, v10, v6
	v_fma_f32 v7, s46, v11, v7
	v_fma_f32 v16, s47, v4, -v12
	v_fma_f32 v17, s47, v5, -v13
	v_fma_f32 v18, s47, v6, -v14
	v_fma_f32 v19, s47, v7, -v15
	v_cvt_pk_bf16_f32 v38, v16, v17
	v_cvt_pk_bf16_f32 v39, v18, v19
	global_store_dwordx2 v0, v[38:39], s[40:41] offset:2560
	v_fma_f32 v4, -s48, v22, v4
	v_fma_f32 v5, -s48, v23, v5
	v_fma_f32 v6, -s48, v24, v6
	v_fma_f32 v7, -s48, v25, v7
	v_readlane_b32 s46, v28, 21
	v_readlane_b32 s47, v29, 14
	v_readlane_b32 s48, v28, 14
	s_waitcnt vmcnt(52)
	v_lshlrev_b32_e32 v8, 16, v156
	v_and_b32_e32 v9, 0xffff0000, v156
	v_lshlrev_b32_e32 v10, 16, v157
	v_and_b32_e32 v11, 0xffff0000, v157
	v_lshlrev_b32_e32 v22, 16, v142
	v_and_b32_e32 v23, 0xffff0000, v142
	v_lshlrev_b32_e32 v24, 16, v143
	v_and_b32_e32 v25, 0xffff0000, v143
	v_mul_f32_e32 v12, s46, v8
	v_mul_f32_e32 v13, s46, v9
	v_mul_f32_e32 v14, s46, v10
	v_mul_f32_e32 v15, s46, v11
	v_fma_f32 v4, s46, v8, v4
	v_fma_f32 v5, s46, v9, v5
	v_fma_f32 v6, s46, v10, v6
	v_fma_f32 v7, s46, v11, v7
	v_fma_f32 v16, s47, v4, -v12
	v_fma_f32 v17, s47, v5, -v13
	v_fma_f32 v18, s47, v6, -v14
	v_fma_f32 v19, s47, v7, -v15
	v_cvt_pk_bf16_f32 v20, v16, v17
	v_cvt_pk_bf16_f32 v21, v18, v19
	global_store_dwordx2 v0, v[20:21], s[40:41] offset:3072
	v_fma_f32 v4, -s48, v22, v4
	v_fma_f32 v5, -s48, v23, v5
	v_fma_f32 v6, -s48, v24, v6
	v_fma_f32 v7, -s48, v25, v7
	v_readlane_b32 s46, v28, 22
	v_readlane_b32 s47, v29, 15
	v_readlane_b32 s48, v28, 15
	s_waitcnt vmcnt(52)
	v_lshlrev_b32_e32 v8, 16, v158
	v_and_b32_e32 v9, 0xffff0000, v158
	v_lshlrev_b32_e32 v10, 16, v159
	v_and_b32_e32 v11, 0xffff0000, v159
	v_lshlrev_b32_e32 v22, 16, v144
	v_and_b32_e32 v23, 0xffff0000, v144
	v_lshlrev_b32_e32 v24, 16, v145
	v_and_b32_e32 v25, 0xffff0000, v145
	v_mul_f32_e32 v12, s46, v8
	v_mul_f32_e32 v13, s46, v9
	v_mul_f32_e32 v14, s46, v10
	v_mul_f32_e32 v15, s46, v11
	v_fma_f32 v4, s46, v8, v4
	v_fma_f32 v5, s46, v9, v5
	v_fma_f32 v6, s46, v10, v6
	v_fma_f32 v7, s46, v11, v7
	v_fma_f32 v16, s47, v4, -v12
	v_fma_f32 v17, s47, v5, -v13
	v_fma_f32 v18, s47, v6, -v14
	v_fma_f32 v19, s47, v7, -v15
	v_cvt_pk_bf16_f32 v38, v16, v17
	v_cvt_pk_bf16_f32 v39, v18, v19
	global_store_dwordx2 v0, v[38:39], s[40:41] offset:3584
	v_fma_f32 v4, -s48, v22, v4
	v_fma_f32 v5, -s48, v23, v5
	v_fma_f32 v6, -s48, v24, v6
	v_fma_f32 v7, -s48, v25, v7
	v_readlane_b32 s46, v28, 23
	v_readlane_b32 s47, v29, 16
	v_readlane_b32 s48, v28, 16
	s_waitcnt vmcnt(52)
	v_lshlrev_b32_e32 v8, 16, v160
	v_and_b32_e32 v9, 0xffff0000, v160
	v_lshlrev_b32_e32 v10, 16, v161
	v_and_b32_e32 v11, 0xffff0000, v161
	v_lshlrev_b32_e32 v22, 16, v146
	v_and_b32_e32 v23, 0xffff0000, v146
	v_lshlrev_b32_e32 v24, 16, v147
	v_and_b32_e32 v25, 0xffff0000, v147
	v_mul_f32_e32 v12, s46, v8
	v_mul_f32_e32 v13, s46, v9
	v_mul_f32_e32 v14, s46, v10
	v_mul_f32_e32 v15, s46, v11
	v_fma_f32 v4, s46, v8, v4
	v_fma_f32 v5, s46, v9, v5
	v_fma_f32 v6, s46, v10, v6
	v_fma_f32 v7, s46, v11, v7
	v_fma_f32 v16, s47, v4, -v12
	v_fma_f32 v17, s47, v5, -v13
	v_fma_f32 v18, s47, v6, -v14
	v_fma_f32 v19, s47, v7, -v15
	v_cvt_pk_bf16_f32 v20, v16, v17
	v_cvt_pk_bf16_f32 v21, v18, v19
	s_add_u32 s40, s40, 0x1000
	s_addc_u32 s41, s41, 0
	global_store_dwordx2 v0, v[20:21], s[40:41]
	v_fma_f32 v4, -s48, v22, v4
	v_fma_f32 v5, -s48, v23, v5
	v_fma_f32 v6, -s48, v24, v6
	v_fma_f32 v7, -s48, v25, v7
	v_readlane_b32 s46, v28, 24
	v_readlane_b32 s47, v29, 17
	v_readlane_b32 s48, v28, 17
	s_waitcnt vmcnt(52)
	v_lshlrev_b32_e32 v8, 16, v162
	v_and_b32_e32 v9, 0xffff0000, v162
	v_lshlrev_b32_e32 v10, 16, v163
	v_and_b32_e32 v11, 0xffff0000, v163
	v_lshlrev_b32_e32 v22, 16, v148
	v_and_b32_e32 v23, 0xffff0000, v148
	v_lshlrev_b32_e32 v24, 16, v149
	v_and_b32_e32 v25, 0xffff0000, v149
	v_mul_f32_e32 v12, s46, v8
	v_mul_f32_e32 v13, s46, v9
	v_mul_f32_e32 v14, s46, v10
	v_mul_f32_e32 v15, s46, v11
	v_fma_f32 v4, s46, v8, v4
	v_fma_f32 v5, s46, v9, v5
	v_fma_f32 v6, s46, v10, v6
	v_fma_f32 v7, s46, v11, v7
	v_fma_f32 v16, s47, v4, -v12
	v_fma_f32 v17, s47, v5, -v13
	v_fma_f32 v18, s47, v6, -v14
	v_fma_f32 v19, s47, v7, -v15
	v_cvt_pk_bf16_f32 v38, v16, v17
	v_cvt_pk_bf16_f32 v39, v18, v19
	global_store_dwordx2 v0, v[38:39], s[40:41] offset:512
	v_fma_f32 v4, -s48, v22, v4
	v_fma_f32 v5, -s48, v23, v5
	v_fma_f32 v6, -s48, v24, v6
	v_fma_f32 v7, -s48, v25, v7
	v_readlane_b32 s46, v28, 25
	v_readlane_b32 s47, v29, 18
	v_readlane_b32 s48, v28, 18
	s_waitcnt vmcnt(52)
	v_lshlrev_b32_e32 v8, 16, v164
	v_and_b32_e32 v9, 0xffff0000, v164
	v_lshlrev_b32_e32 v10, 16, v165
	v_and_b32_e32 v11, 0xffff0000, v165
	v_lshlrev_b32_e32 v22, 16, v150
	v_and_b32_e32 v23, 0xffff0000, v150
	v_lshlrev_b32_e32 v24, 16, v151
	v_and_b32_e32 v25, 0xffff0000, v151
	v_mul_f32_e32 v12, s46, v8
	v_mul_f32_e32 v13, s46, v9
	v_mul_f32_e32 v14, s46, v10
	v_mul_f32_e32 v15, s46, v11
	v_fma_f32 v4, s46, v8, v4
	v_fma_f32 v5, s46, v9, v5
	v_fma_f32 v6, s46, v10, v6
	v_fma_f32 v7, s46, v11, v7
	v_fma_f32 v16, s47, v4, -v12
	v_fma_f32 v17, s47, v5, -v13
	v_fma_f32 v18, s47, v6, -v14
	v_fma_f32 v19, s47, v7, -v15
	v_cvt_pk_bf16_f32 v20, v16, v17
	v_cvt_pk_bf16_f32 v21, v18, v19
	global_store_dwordx2 v0, v[20:21], s[40:41] offset:1024
	v_fma_f32 v4, -s48, v22, v4
	v_fma_f32 v5, -s48, v23, v5
	v_fma_f32 v6, -s48, v24, v6
	v_fma_f32 v7, -s48, v25, v7
	v_readlane_b32 s46, v28, 26
	v_readlane_b32 s47, v29, 19
	v_readlane_b32 s48, v28, 19
	s_waitcnt vmcnt(52)
	v_lshlrev_b32_e32 v8, 16, v166
	v_and_b32_e32 v9, 0xffff0000, v166
	v_lshlrev_b32_e32 v10, 16, v167
	v_and_b32_e32 v11, 0xffff0000, v167
	v_lshlrev_b32_e32 v22, 16, v152
	v_and_b32_e32 v23, 0xffff0000, v152
	v_lshlrev_b32_e32 v24, 16, v153
	v_and_b32_e32 v25, 0xffff0000, v153
	v_mul_f32_e32 v12, s46, v8
	v_mul_f32_e32 v13, s46, v9
	v_mul_f32_e32 v14, s46, v10
	v_mul_f32_e32 v15, s46, v11
	v_fma_f32 v4, s46, v8, v4
	v_fma_f32 v5, s46, v9, v5
	v_fma_f32 v6, s46, v10, v6
	v_fma_f32 v7, s46, v11, v7
	v_fma_f32 v16, s47, v4, -v12
	v_fma_f32 v17, s47, v5, -v13
	v_fma_f32 v18, s47, v6, -v14
	v_fma_f32 v19, s47, v7, -v15
	v_cvt_pk_bf16_f32 v38, v16, v17
	v_cvt_pk_bf16_f32 v39, v18, v19
	global_store_dwordx2 v0, v[38:39], s[40:41] offset:1536
	v_fma_f32 v4, -s48, v22, v4
	v_fma_f32 v5, -s48, v23, v5
	v_fma_f32 v6, -s48, v24, v6
	v_fma_f32 v7, -s48, v25, v7
	v_readlane_b32 s46, v28, 27
	v_readlane_b32 s47, v29, 20
	v_readlane_b32 s48, v28, 20
	s_waitcnt vmcnt(52)
	v_lshlrev_b32_e32 v8, 16, v168
	v_and_b32_e32 v9, 0xffff0000, v168
	v_lshlrev_b32_e32 v10, 16, v169
	v_and_b32_e32 v11, 0xffff0000, v169
	v_lshlrev_b32_e32 v22, 16, v154
	v_and_b32_e32 v23, 0xffff0000, v154
	v_lshlrev_b32_e32 v24, 16, v155
	v_and_b32_e32 v25, 0xffff0000, v155
	v_mul_f32_e32 v12, s46, v8
	v_mul_f32_e32 v13, s46, v9
	v_mul_f32_e32 v14, s46, v10
	v_mul_f32_e32 v15, s46, v11
	v_fma_f32 v4, s46, v8, v4
	v_fma_f32 v5, s46, v9, v5
	v_fma_f32 v6, s46, v10, v6
	v_fma_f32 v7, s46, v11, v7
	v_fma_f32 v16, s47, v4, -v12
	v_fma_f32 v17, s47, v5, -v13
	v_fma_f32 v18, s47, v6, -v14
	v_fma_f32 v19, s47, v7, -v15
	v_cvt_pk_bf16_f32 v20, v16, v17
	v_cvt_pk_bf16_f32 v21, v18, v19
	global_store_dwordx2 v0, v[20:21], s[40:41] offset:2048
	v_fma_f32 v4, -s48, v22, v4
	v_fma_f32 v5, -s48, v23, v5
	v_fma_f32 v6, -s48, v24, v6
	v_fma_f32 v7, -s48, v25, v7
	v_readlane_b32 s46, v28, 28
	v_readlane_b32 s47, v29, 21
	v_readlane_b32 s48, v28, 21
	s_waitcnt vmcnt(52)
	v_lshlrev_b32_e32 v8, 16, v170
	v_and_b32_e32 v9, 0xffff0000, v170
	v_lshlrev_b32_e32 v10, 16, v171
	v_and_b32_e32 v11, 0xffff0000, v171
	v_lshlrev_b32_e32 v22, 16, v156
	v_and_b32_e32 v23, 0xffff0000, v156
	v_lshlrev_b32_e32 v24, 16, v157
	v_and_b32_e32 v25, 0xffff0000, v157
	v_mul_f32_e32 v12, s46, v8
	v_mul_f32_e32 v13, s46, v9
	v_mul_f32_e32 v14, s46, v10
	v_mul_f32_e32 v15, s46, v11
	v_fma_f32 v4, s46, v8, v4
	v_fma_f32 v5, s46, v9, v5
	v_fma_f32 v6, s46, v10, v6
	v_fma_f32 v7, s46, v11, v7
	v_fma_f32 v16, s47, v4, -v12
	v_fma_f32 v17, s47, v5, -v13
	v_fma_f32 v18, s47, v6, -v14
	v_fma_f32 v19, s47, v7, -v15
	v_cvt_pk_bf16_f32 v38, v16, v17
	v_cvt_pk_bf16_f32 v39, v18, v19
	global_store_dwordx2 v0, v[38:39], s[40:41] offset:2560
	v_fma_f32 v4, -s48, v22, v4
	v_fma_f32 v5, -s48, v23, v5
	v_fma_f32 v6, -s48, v24, v6
	v_fma_f32 v7, -s48, v25, v7
	v_readlane_b32 s46, v28, 29
	v_readlane_b32 s47, v29, 22
	v_readlane_b32 s48, v28, 22
	s_waitcnt vmcnt(52)
	v_lshlrev_b32_e32 v8, 16, v172
	v_and_b32_e32 v9, 0xffff0000, v172
	v_lshlrev_b32_e32 v10, 16, v173
	v_and_b32_e32 v11, 0xffff0000, v173
	v_lshlrev_b32_e32 v22, 16, v158
	v_and_b32_e32 v23, 0xffff0000, v158
	v_lshlrev_b32_e32 v24, 16, v159
	v_and_b32_e32 v25, 0xffff0000, v159
	v_mul_f32_e32 v12, s46, v8
	v_mul_f32_e32 v13, s46, v9
	v_mul_f32_e32 v14, s46, v10
	v_mul_f32_e32 v15, s46, v11
	v_fma_f32 v4, s46, v8, v4
	v_fma_f32 v5, s46, v9, v5
	v_fma_f32 v6, s46, v10, v6
	v_fma_f32 v7, s46, v11, v7
	v_fma_f32 v16, s47, v4, -v12
	v_fma_f32 v17, s47, v5, -v13
	v_fma_f32 v18, s47, v6, -v14
	v_fma_f32 v19, s47, v7, -v15
	v_cvt_pk_bf16_f32 v20, v16, v17
	v_cvt_pk_bf16_f32 v21, v18, v19
	global_store_dwordx2 v0, v[20:21], s[40:41] offset:3072
	v_fma_f32 v4, -s48, v22, v4
	v_fma_f32 v5, -s48, v23, v5
	v_fma_f32 v6, -s48, v24, v6
	v_fma_f32 v7, -s48, v25, v7
	v_readlane_b32 s46, v28, 30
	v_readlane_b32 s47, v29, 23
	v_readlane_b32 s48, v28, 23
	s_waitcnt vmcnt(52)
	v_lshlrev_b32_e32 v8, 16, v174
	v_and_b32_e32 v9, 0xffff0000, v174
	v_lshlrev_b32_e32 v10, 16, v175
	v_and_b32_e32 v11, 0xffff0000, v175
	v_lshlrev_b32_e32 v22, 16, v160
	v_and_b32_e32 v23, 0xffff0000, v160
	v_lshlrev_b32_e32 v24, 16, v161
	v_and_b32_e32 v25, 0xffff0000, v161
	v_mul_f32_e32 v12, s46, v8
	v_mul_f32_e32 v13, s46, v9
	v_mul_f32_e32 v14, s46, v10
	v_mul_f32_e32 v15, s46, v11
	v_fma_f32 v4, s46, v8, v4
	v_fma_f32 v5, s46, v9, v5
	v_fma_f32 v6, s46, v10, v6
	v_fma_f32 v7, s46, v11, v7
	v_fma_f32 v16, s47, v4, -v12
	v_fma_f32 v17, s47, v5, -v13
	v_fma_f32 v18, s47, v6, -v14
	v_fma_f32 v19, s47, v7, -v15
	v_cvt_pk_bf16_f32 v38, v16, v17
	v_cvt_pk_bf16_f32 v39, v18, v19
	global_store_dwordx2 v0, v[38:39], s[40:41] offset:3584
	v_fma_f32 v4, -s48, v22, v4
	v_fma_f32 v5, -s48, v23, v5
	v_fma_f32 v6, -s48, v24, v6
	v_fma_f32 v7, -s48, v25, v7
	v_readlane_b32 s46, v28, 31
	v_readlane_b32 s47, v29, 24
	v_readlane_b32 s48, v28, 24
	s_waitcnt vmcnt(52)
	v_lshlrev_b32_e32 v8, 16, v176
	v_and_b32_e32 v9, 0xffff0000, v176
	v_lshlrev_b32_e32 v10, 16, v177
	v_and_b32_e32 v11, 0xffff0000, v177
	v_lshlrev_b32_e32 v22, 16, v162
	v_and_b32_e32 v23, 0xffff0000, v162
	v_lshlrev_b32_e32 v24, 16, v163
	v_and_b32_e32 v25, 0xffff0000, v163
	v_mul_f32_e32 v12, s46, v8
	v_mul_f32_e32 v13, s46, v9
	v_mul_f32_e32 v14, s46, v10
	v_mul_f32_e32 v15, s46, v11
	v_fma_f32 v4, s46, v8, v4
	v_fma_f32 v5, s46, v9, v5
	v_fma_f32 v6, s46, v10, v6
	v_fma_f32 v7, s46, v11, v7
	v_fma_f32 v16, s47, v4, -v12
	v_fma_f32 v17, s47, v5, -v13
	v_fma_f32 v18, s47, v6, -v14
	v_fma_f32 v19, s47, v7, -v15
	v_cvt_pk_bf16_f32 v20, v16, v17
	v_cvt_pk_bf16_f32 v21, v18, v19
	s_add_u32 s40, s40, 0x1000
	s_addc_u32 s41, s41, 0
	global_store_dwordx2 v0, v[20:21], s[40:41]
	v_fma_f32 v4, -s48, v22, v4
	v_fma_f32 v5, -s48, v23, v5
	v_fma_f32 v6, -s48, v24, v6
	v_fma_f32 v7, -s48, v25, v7
	v_readlane_b32 s46, v28, 32
	v_readlane_b32 s47, v29, 25
	v_readlane_b32 s48, v28, 25
	s_waitcnt vmcnt(52)
	v_lshlrev_b32_e32 v8, 16, v178
	v_and_b32_e32 v9, 0xffff0000, v178
	v_lshlrev_b32_e32 v10, 16, v179
	v_and_b32_e32 v11, 0xffff0000, v179
	v_lshlrev_b32_e32 v22, 16, v164
	v_and_b32_e32 v23, 0xffff0000, v164
	v_lshlrev_b32_e32 v24, 16, v165
	v_and_b32_e32 v25, 0xffff0000, v165
	v_mul_f32_e32 v12, s46, v8
	v_mul_f32_e32 v13, s46, v9
	v_mul_f32_e32 v14, s46, v10
	v_mul_f32_e32 v15, s46, v11
	v_fma_f32 v4, s46, v8, v4
	v_fma_f32 v5, s46, v9, v5
	v_fma_f32 v6, s46, v10, v6
	v_fma_f32 v7, s46, v11, v7
	v_fma_f32 v16, s47, v4, -v12
	v_fma_f32 v17, s47, v5, -v13
	v_fma_f32 v18, s47, v6, -v14
	v_fma_f32 v19, s47, v7, -v15
	v_cvt_pk_bf16_f32 v38, v16, v17
	v_cvt_pk_bf16_f32 v39, v18, v19
	global_store_dwordx2 v0, v[38:39], s[40:41] offset:512
	v_fma_f32 v4, -s48, v22, v4
	v_fma_f32 v5, -s48, v23, v5
	v_fma_f32 v6, -s48, v24, v6
	v_fma_f32 v7, -s48, v25, v7
	v_readlane_b32 s46, v28, 33
	v_readlane_b32 s47, v29, 26
	v_readlane_b32 s48, v28, 26
	s_waitcnt vmcnt(52)
	v_lshlrev_b32_e32 v8, 16, v180
	v_and_b32_e32 v9, 0xffff0000, v180
	v_lshlrev_b32_e32 v10, 16, v181
	v_and_b32_e32 v11, 0xffff0000, v181
	v_lshlrev_b32_e32 v22, 16, v166
	v_and_b32_e32 v23, 0xffff0000, v166
	v_lshlrev_b32_e32 v24, 16, v167
	v_and_b32_e32 v25, 0xffff0000, v167
	v_mul_f32_e32 v12, s46, v8
	v_mul_f32_e32 v13, s46, v9
	v_mul_f32_e32 v14, s46, v10
	v_mul_f32_e32 v15, s46, v11
	v_fma_f32 v4, s46, v8, v4
	v_fma_f32 v5, s46, v9, v5
	v_fma_f32 v6, s46, v10, v6
	v_fma_f32 v7, s46, v11, v7
	v_fma_f32 v16, s47, v4, -v12
	v_fma_f32 v17, s47, v5, -v13
	v_fma_f32 v18, s47, v6, -v14
	v_fma_f32 v19, s47, v7, -v15
	v_cvt_pk_bf16_f32 v20, v16, v17
	v_cvt_pk_bf16_f32 v21, v18, v19
	global_store_dwordx2 v0, v[20:21], s[40:41] offset:1024
	v_fma_f32 v4, -s48, v22, v4
	v_fma_f32 v5, -s48, v23, v5
	v_fma_f32 v6, -s48, v24, v6
	v_fma_f32 v7, -s48, v25, v7
	v_readlane_b32 s46, v28, 34
	v_readlane_b32 s47, v29, 27
	v_readlane_b32 s48, v28, 27
	s_waitcnt vmcnt(52)
	v_lshlrev_b32_e32 v8, 16, v182
	v_and_b32_e32 v9, 0xffff0000, v182
	v_lshlrev_b32_e32 v10, 16, v183
	v_and_b32_e32 v11, 0xffff0000, v183
	v_lshlrev_b32_e32 v22, 16, v168
	v_and_b32_e32 v23, 0xffff0000, v168
	v_lshlrev_b32_e32 v24, 16, v169
	v_and_b32_e32 v25, 0xffff0000, v169
	v_mul_f32_e32 v12, s46, v8
	v_mul_f32_e32 v13, s46, v9
	v_mul_f32_e32 v14, s46, v10
	v_mul_f32_e32 v15, s46, v11
	v_fma_f32 v4, s46, v8, v4
	v_fma_f32 v5, s46, v9, v5
	v_fma_f32 v6, s46, v10, v6
	v_fma_f32 v7, s46, v11, v7
	v_fma_f32 v16, s47, v4, -v12
	v_fma_f32 v17, s47, v5, -v13
	v_fma_f32 v18, s47, v6, -v14
	v_fma_f32 v19, s47, v7, -v15
	v_cvt_pk_bf16_f32 v38, v16, v17
	v_cvt_pk_bf16_f32 v39, v18, v19
	global_store_dwordx2 v0, v[38:39], s[40:41] offset:1536
	v_fma_f32 v4, -s48, v22, v4
	v_fma_f32 v5, -s48, v23, v5
	v_fma_f32 v6, -s48, v24, v6
	v_fma_f32 v7, -s48, v25, v7
	v_readlane_b32 s46, v28, 35
	v_readlane_b32 s47, v29, 28
	v_readlane_b32 s48, v28, 28
	s_waitcnt vmcnt(52)
	v_lshlrev_b32_e32 v8, 16, v184
	v_and_b32_e32 v9, 0xffff0000, v184
	v_lshlrev_b32_e32 v10, 16, v185
	v_and_b32_e32 v11, 0xffff0000, v185
	v_lshlrev_b32_e32 v22, 16, v170
	v_and_b32_e32 v23, 0xffff0000, v170
	v_lshlrev_b32_e32 v24, 16, v171
	v_and_b32_e32 v25, 0xffff0000, v171
	v_mul_f32_e32 v12, s46, v8
	v_mul_f32_e32 v13, s46, v9
	v_mul_f32_e32 v14, s46, v10
	v_mul_f32_e32 v15, s46, v11
	v_fma_f32 v4, s46, v8, v4
	v_fma_f32 v5, s46, v9, v5
	v_fma_f32 v6, s46, v10, v6
	v_fma_f32 v7, s46, v11, v7
	v_fma_f32 v16, s47, v4, -v12
	v_fma_f32 v17, s47, v5, -v13
	v_fma_f32 v18, s47, v6, -v14
	v_fma_f32 v19, s47, v7, -v15
	v_cvt_pk_bf16_f32 v20, v16, v17
	v_cvt_pk_bf16_f32 v21, v18, v19
	global_store_dwordx2 v0, v[20:21], s[40:41] offset:2048
	v_fma_f32 v4, -s48, v22, v4
	v_fma_f32 v5, -s48, v23, v5
	v_fma_f32 v6, -s48, v24, v6
	v_fma_f32 v7, -s48, v25, v7
	v_readlane_b32 s46, v28, 36
	v_readlane_b32 s47, v29, 29
	v_readlane_b32 s48, v28, 29
	s_waitcnt vmcnt(52)
	v_lshlrev_b32_e32 v8, 16, v186
	v_and_b32_e32 v9, 0xffff0000, v186
	v_lshlrev_b32_e32 v10, 16, v187
	v_and_b32_e32 v11, 0xffff0000, v187
	v_lshlrev_b32_e32 v22, 16, v172
	v_and_b32_e32 v23, 0xffff0000, v172
	v_lshlrev_b32_e32 v24, 16, v173
	v_and_b32_e32 v25, 0xffff0000, v173
	v_mul_f32_e32 v12, s46, v8
	v_mul_f32_e32 v13, s46, v9
	v_mul_f32_e32 v14, s46, v10
	v_mul_f32_e32 v15, s46, v11
	v_fma_f32 v4, s46, v8, v4
	v_fma_f32 v5, s46, v9, v5
	v_fma_f32 v6, s46, v10, v6
	v_fma_f32 v7, s46, v11, v7
	v_fma_f32 v16, s47, v4, -v12
	v_fma_f32 v17, s47, v5, -v13
	v_fma_f32 v18, s47, v6, -v14
	v_fma_f32 v19, s47, v7, -v15
	v_cvt_pk_bf16_f32 v38, v16, v17
	v_cvt_pk_bf16_f32 v39, v18, v19
	global_store_dwordx2 v0, v[38:39], s[40:41] offset:2560
	v_fma_f32 v4, -s48, v22, v4
	v_fma_f32 v5, -s48, v23, v5
	v_fma_f32 v6, -s48, v24, v6
	v_fma_f32 v7, -s48, v25, v7
	v_readlane_b32 s46, v28, 37
	v_readlane_b32 s47, v29, 30
	v_readlane_b32 s48, v28, 30
	s_waitcnt vmcnt(52)
	v_lshlrev_b32_e32 v8, 16, v188
	v_and_b32_e32 v9, 0xffff0000, v188
	v_lshlrev_b32_e32 v10, 16, v189
	v_and_b32_e32 v11, 0xffff0000, v189
	v_lshlrev_b32_e32 v22, 16, v174
	v_and_b32_e32 v23, 0xffff0000, v174
	v_lshlrev_b32_e32 v24, 16, v175
	v_and_b32_e32 v25, 0xffff0000, v175
	v_mul_f32_e32 v12, s46, v8
	v_mul_f32_e32 v13, s46, v9
	v_mul_f32_e32 v14, s46, v10
	v_mul_f32_e32 v15, s46, v11
	v_fma_f32 v4, s46, v8, v4
	v_fma_f32 v5, s46, v9, v5
	v_fma_f32 v6, s46, v10, v6
	v_fma_f32 v7, s46, v11, v7
	v_fma_f32 v16, s47, v4, -v12
	v_fma_f32 v17, s47, v5, -v13
	v_fma_f32 v18, s47, v6, -v14
	v_fma_f32 v19, s47, v7, -v15
	v_cvt_pk_bf16_f32 v20, v16, v17
	v_cvt_pk_bf16_f32 v21, v18, v19
	global_store_dwordx2 v0, v[20:21], s[40:41] offset:3072
	v_fma_f32 v4, -s48, v22, v4
	v_fma_f32 v5, -s48, v23, v5
	v_fma_f32 v6, -s48, v24, v6
	v_fma_f32 v7, -s48, v25, v7
	v_readlane_b32 s46, v28, 38
	v_readlane_b32 s47, v29, 31
	v_readlane_b32 s48, v28, 31
	s_waitcnt vmcnt(51)
	v_lshlrev_b32_e32 v8, 16, v190
	v_and_b32_e32 v9, 0xffff0000, v190
	v_lshlrev_b32_e32 v10, 16, v191
	v_and_b32_e32 v11, 0xffff0000, v191
	v_lshlrev_b32_e32 v22, 16, v176
	v_and_b32_e32 v23, 0xffff0000, v176
	v_lshlrev_b32_e32 v24, 16, v177
	v_and_b32_e32 v25, 0xffff0000, v177
	v_mul_f32_e32 v12, s46, v8
	v_mul_f32_e32 v13, s46, v9
	v_mul_f32_e32 v14, s46, v10
	v_mul_f32_e32 v15, s46, v11
	v_fma_f32 v4, s46, v8, v4
	v_fma_f32 v5, s46, v9, v5
	v_fma_f32 v6, s46, v10, v6
	v_fma_f32 v7, s46, v11, v7
	v_fma_f32 v16, s47, v4, -v12
	v_fma_f32 v17, s47, v5, -v13
	v_fma_f32 v18, s47, v6, -v14
	v_fma_f32 v19, s47, v7, -v15
	v_cvt_pk_bf16_f32 v38, v16, v17
	v_cvt_pk_bf16_f32 v39, v18, v19
	global_store_dwordx2 v0, v[38:39], s[40:41] offset:3584
	v_fma_f32 v4, -s48, v22, v4
	v_fma_f32 v5, -s48, v23, v5
	v_fma_f32 v6, -s48, v24, v6
	v_fma_f32 v7, -s48, v25, v7
	s_branch .Lpool_done
.Lpool_hi:
	s_add_i32 s19, s2, 0
	s_bfe_u32 s0, s19, 0x30004
	s_and_b32 s1, s19, 15
	s_lshl_b32 s1, s1, 3
	s_add_i32 s1, s1, s18
	s_lshl_b32 s28, s1, 5
	s_sub_i32 s29, s28, 3
	s_max_i32 s3, s29, 0
	s_lshl_b32 s6, s0, 23
	s_add_u32 s6, s70, s6
	s_addc_u32 s7, s71, 0
	s_add_u32 s6, s6, 0x200
	s_addc_u32 s7, s7, 0
	s_lshl_b32 s8, s3, 11
	s_add_u32 s20, s6, s8
	s_addc_u32 s21, s7, 0
	s_lshl_b32 s8, s28, 11
	s_add_u32 s22, s6, s8
	s_addc_u32 s23, s7, 0
	s_lshl_b32 s6, s0, 21
	s_lshl_b32 s8, s28, 9
	s_add_u32 s6, s6, s8
	s_add_u32 s6, s6, 0xf940000
	s_add_u32 s24, s72, s6
	s_addc_u32 s25, s73, 0
	s_lshl_b32 s6, s0, 14
	s_add_u32 s6, s6, 0x48a0000
	s_add_u32 s26, s72, s6
	s_addc_u32 s27, s73, 0
	v_add_u32_e32 v2, s29, v1
	v_max_i32_e32 v3, 0, v2
	s_add_i32 s6, s28, 31
	v_min_i32_e32 v3, s6, v3
	v_lshlrev_b32_e32 v3, 2, v3
	global_load_dword v26, v3, s[26:27]
	v_mov_b32_e32 v30, v2
	s_add_i32 s19, s2, 256
	s_bfe_u32 s0, s19, 0x30004
	s_and_b32 s1, s19, 15
	s_lshl_b32 s1, s1, 3
	s_add_i32 s1, s1, s18
	s_lshl_b32 s44, s1, 5
	s_sub_i32 s45, s44, 15
	s_max_i32 s3, s45, 0
	s_lshl_b32 s6, s0, 23
	s_add_u32 s6, s70, s6
	s_addc_u32 s7, s71, 0
	s_add_u32 s6, s6, 0x600
	s_addc_u32 s7, s7, 0
	s_lshl_b32 s8, s3, 11
	s_add_u32 s36, s6, s8
	s_addc_u32 s37, s7, 0
	s_lshl_b32 s8, s44, 11
	s_add_u32 s38, s6, s8
	s_addc_u32 s39, s7, 0
	s_lshl_b32 s6, s0, 21
	s_lshl_b32 s8, s44, 9
	s_add_u32 s6, s6, s8
	s_add_u32 s6, s6, 0x11940000
	s_add_u32 s40, s72, s6
	s_addc_u32 s41, s73, 0
	s_lshl_b32 s6, s0, 14
	s_add_u32 s6, s6, 0x48a0000
	s_add_u32 s42, s72, s6
	s_addc_u32 s43, s73, 0
	v_add_u32_e32 v2, s45, v1
	v_max_i32_e32 v3, 0, v2
	s_add_i32 s6, s44, 31
	v_min_i32_e32 v3, s6, v3
	v_lshlrev_b32_e32 v3, 2, v3
	global_load_dword v28, v3, s[42:43]
	v_mov_b32_e32 v31, v2
	global_load_dwordx2 v[44:45], v0, s[20:21]
	global_load_dwordx2 v[46:47], v0, s[20:21] offset:2048
	s_add_u32 s20, s20, 0x1000
	s_addc_u32 s21, s21, 0
	global_load_dwordx2 v[48:49], v0, s[20:21]
	global_load_dwordx2 v[50:51], v0, s[22:23]
	global_load_dwordx2 v[52:53], v0, s[22:23] offset:2048
	s_add_u32 s22, s22, 0x1000
	s_addc_u32 s23, s23, 0
	global_load_dwordx2 v[54:55], v0, s[22:23]
	global_load_dwordx2 v[56:57], v0, s[22:23] offset:2048
	s_add_u32 s22, s22, 0x1000
	s_addc_u32 s23, s23, 0
	global_load_dwordx2 v[58:59], v0, s[22:23]
	global_load_dwordx2 v[60:61], v0, s[22:23] offset:2048
	s_add_u32 s22, s22, 0x1000
	s_addc_u32 s23, s23, 0
	global_load_dwordx2 v[62:63], v0, s[22:23]
	global_load_dwordx2 v[64:65], v0, s[22:23] offset:2048
	s_add_u32 s22, s22, 0x1000
	s_addc_u32 s23, s23, 0
	global_load_dwordx2 v[66:67], v0, s[22:23]
	global_load_dwordx2 v[68:69], v0, s[22:23] offset:2048
	s_add_u32 s22, s22, 0x1000
	s_addc_u32 s23, s23, 0
	global_load_dwordx2 v[70:71], v0, s[22:23]
	global_load_dwordx2 v[72:73], v0, s[22:23] offset:2048
	s_add_u32 s22, s22, 0x1000
	s_addc_u32 s23, s23, 0
	global_load_dwordx2 v[74:75], v0, s[22:23]
	global_load_dwordx2 v[76:77], v0, s[22:23] offset:2048
	s_add_u32 s22, s22, 0x1000
	s_addc_u32 s23, s23, 0
	global_load_dwordx2 v[78:79], v0, s[22:23]
	global_load_dwordx2 v[80:81], v0, s[22:23] offset:2048
	s_add_u32 s22, s22, 0x1000
	s_addc_u32 s23, s23, 0
	global_load_dwordx2 v[82:83], v0, s[22:23]
	global_load_dwordx2 v[84:85], v0, s[22:23] offset:2048
	s_add_u32 s22, s22, 0x1000
	s_addc_u32 s23, s23, 0
	global_load_dwordx2 v[86:87], v0, s[22:23]
	global_load_dwordx2 v[88:89], v0, s[22:23] offset:2048
	s_add_u32 s22, s22, 0x1000
	s_addc_u32 s23, s23, 0
	global_load_dwordx2 v[90:91], v0, s[22:23]
	global_load_dwordx2 v[92:93], v0, s[22:23] offset:2048
	s_add_u32 s22, s22, 0x1000
	s_addc_u32 s23, s23, 0
	global_load_dwordx2 v[94:95], v0, s[22:23]
	global_load_dwordx2 v[96:97], v0, s[22:23] offset:2048
	s_add_u32 s22, s22, 0x1000
	s_addc_u32 s23, s23, 0
	global_load_dwordx2 v[98:99], v0, s[22:23]
	global_load_dwordx2 v[100:101], v0, s[22:23] offset:2048
	s_add_u32 s22, s22, 0x1000
	s_addc_u32 s23, s23, 0
	global_load_dwordx2 v[102:103], v0, s[22:23]
	global_load_dwordx2 v[104:105], v0, s[22:23] offset:2048
	s_add_u32 s22, s22, 0x1000
	s_addc_u32 s23, s23, 0
	global_load_dwordx2 v[106:107], v0, s[22:23]
	global_load_dwordx2 v[108:109], v0, s[22:23] offset:2048
	s_add_u32 s22, s22, 0x1000
	s_addc_u32 s23, s23, 0
	global_load_dwordx2 v[110:111], v0, s[22:23]
	global_load_dwordx2 v[112:113], v0, s[22:23] offset:2048
	global_load_dwordx2 v[114:115], v0, s[36:37]
	global_load_dwordx2 v[116:117], v0, s[36:37] offset:2048
	s_add_u32 s36, s36, 0x1000
	s_addc_u32 s37, s37, 0
	global_load_dwordx2 v[118:119], v0, s[36:37]
	global_load_dwordx2 v[120:121], v0, s[36:37] offset:2048
	s_add_u32 s36, s36, 0x1000
	s_addc_u32 s37, s37, 0
	global_load_dwordx2 v[122:123], v0, s[36:37]
	global_load_dwordx2 v[124:125], v0, s[36:37] offset:2048
	s_add_u32 s36, s36, 0x1000
	s_addc_u32 s37, s37, 0
	global_load_dwordx2 v[126:127], v0, s[36:37]
	global_load_dwordx2 v[128:129], v0, s[36:37] offset:2048
	s_add_u32 s36, s36, 0x1000
	s_addc_u32 s37, s37, 0
	global_load_dwordx2 v[130:131], v0, s[36:37]
	global_load_dwordx2 v[132:133], v0, s[36:37] offset:2048
	s_add_u32 s36, s36, 0x1000
	s_addc_u32 s37, s37, 0
	global_load_dwordx2 v[134:135], v0, s[36:37]
	global_load_dwordx2 v[136:137], v0, s[36:37] offset:2048
	s_add_u32 s36, s36, 0x1000
	s_addc_u32 s37, s37, 0
	global_load_dwordx2 v[138:139], v0, s[36:37]
	global_load_dwordx2 v[140:141], v0, s[36:37] offset:2048
	s_add_u32 s36, s36, 0x1000
	s_addc_u32 s37, s37, 0
	global_load_dwordx2 v[142:143], v0, s[36:37]
	global_load_dwordx2 v[144:145], v0, s[38:39]
	s_waitcnt vmcnt(51)
	v_mov_b32_e32 v2, 0x358637bd
	v_fmac_f32_e32 v2, 0x3a800000, v26
	s_mov_b32 s6, 0x800000
	v_mul_f32_e32 v3, 0x4b800000, v2
	v_cmp_gt_f32_e32 vcc, s6, v2
	s_nop 1
	v_cndmask_b32_e32 v2, v2, v3, vcc
	v_rsq_f32_e32 v2, v2
	s_nop 0
	v_mul_f32_e32 v3, 0x45800000, v2
	v_cndmask_b32_e32 v26, v2, v3, vcc
	v_cmp_gt_i32_e32 vcc, 0, v30
	s_nop 1
	v_cndmask_b32_e64 v26, v26, 0, vcc
	v_add_u32_e32 v2, s28, v1
	v_add_u32_e32 v2, 1, v2
	v_min_u32_e32 v2, 4, v2
	v_cvt_f32_u32_e32 v2, v2
	v_div_scale_f32 v32, s[6:7], v2, v2, 1.0
	v_rcp_f32_e32 v33, v32
	v_div_scale_f32 v34, vcc, 1.0, v2, 1.0
	v_fma_f32 v35, -v32, v33, 1.0
	v_fmac_f32_e32 v33, v35, v33
	v_mul_f32_e32 v35, v34, v33
	v_fma_f32 v36, -v32, v35, v34
	v_fmac_f32_e32 v35, v36, v33
	v_fma_f32 v32, -v32, v35, v34
	v_div_fmas_f32 v32, v32, v33, v35
	v_div_fixup_f32 v27, v32, v2, 1.0
	v_mov_b32_e32 v2, 0x358637bd
	v_fmac_f32_e32 v2, 0x3a800000, v28
	s_mov_b32 s6, 0x800000
	v_mul_f32_e32 v3, 0x4b800000, v2
	v_cmp_gt_f32_e32 vcc, s6, v2
	s_nop 1
	v_cndmask_b32_e32 v2, v2, v3, vcc
	v_rsq_f32_e32 v2, v2
	s_nop 0
	v_mul_f32_e32 v3, 0x45800000, v2
	v_cndmask_b32_e32 v28, v2, v3, vcc
	v_cmp_gt_i32_e32 vcc, 0, v31
	s_nop 1
	v_cndmask_b32_e64 v28, v28, 0, vcc
	v_add_u32_e32 v2, s44, v1
	v_add_u32_e32 v2, 1, v2
	v_min_u32_e32 v2, 16, v2
	v_cvt_f32_u32_e32 v2, v2
	v_div_scale_f32 v32, s[6:7], v2, v2, 1.0
	v_rcp_f32_e32 v33, v32
	v_div_scale_f32 v34, vcc, 1.0, v2, 1.0
	v_fma_f32 v35, -v32, v33, 1.0
	v_fmac_f32_e32 v33, v35, v33
	v_mul_f32_e32 v35, v34, v33
	v_fma_f32 v36, -v32, v35, v34
	v_fmac_f32_e32 v35, v36, v33
	v_fma_f32 v32, -v32, v35, v34
	v_div_fmas_f32 v32, v32, v33, v35
	v_div_fixup_f32 v29, v32, v2, 1.0
	s_nop 0
	v_mov_b32_e32 v4, 0
	v_mov_b32_e32 v5, 0
	v_mov_b32_e32 v6, 0
	v_mov_b32_e32 v7, 0
	v_readlane_b32 s46, v26, 0
	s_waitcnt vmcnt(50)
	v_lshlrev_b32_e32 v8, 16, v44
	v_and_b32_e32 v9, 0xffff0000, v44
	v_lshlrev_b32_e32 v10, 16, v45
	v_and_b32_e32 v11, 0xffff0000, v45
	v_fma_f32 v4, s46, v8, v4
	v_fma_f32 v5, s46, v9, v5
	v_fma_f32 v6, s46, v10, v6
	v_fma_f32 v7, s46, v11, v7
	v_readlane_b32 s46, v26, 1
	s_waitcnt vmcnt(49)
	v_lshlrev_b32_e32 v8, 16, v46
	v_and_b32_e32 v9, 0xffff0000, v46
	v_lshlrev_b32_e32 v10, 16, v47
	v_and_b32_e32 v11, 0xffff0000, v47
	v_fma_f32 v4, s46, v8, v4
	v_fma_f32 v5, s46, v9, v5
	v_fma_f32 v6, s46, v10, v6
	v_fma_f32 v7, s46, v11, v7
	v_readlane_b32 s46, v26, 2
	s_waitcnt vmcnt(48)
	v_lshlrev_b32_e32 v8, 16, v48
	v_and_b32_e32 v9, 0xffff0000, v48
	v_lshlrev_b32_e32 v10, 16, v49
	v_and_b32_e32 v11, 0xffff0000, v49
	v_fma_f32 v4, s46, v8, v4
	v_fma_f32 v5, s46, v9, v5
	v_fma_f32 v6, s46, v10, v6
	v_fma_f32 v7, s46, v11, v7
	v_readlane_b32 s46, v26, 3
	v_readlane_b32 s47, v27, 0
	v_readlane_b32 s48, v26, 0
	s_waitcnt vmcnt(47)
	v_lshlrev_b32_e32 v8, 16, v50
	v_and_b32_e32 v9, 0xffff0000, v50
	v_lshlrev_b32_e32 v10, 16, v51
	v_and_b32_e32 v11, 0xffff0000, v51
	v_lshlrev_b32_e32 v22, 16, v44
	v_and_b32_e32 v23, 0xffff0000, v44
	v_lshlrev_b32_e32 v24, 16, v45
	v_and_b32_e32 v25, 0xffff0000, v45
	v_mul_f32_e32 v12, s46, v8
	v_mul_f32_e32 v13, s46, v9
	v_mul_f32_e32 v14, s46, v10
	v_mul_f32_e32 v15, s46, v11
	v_fma_f32 v4, s46, v8, v4
	v_fma_f32 v5, s46, v9, v5
	v_fma_f32 v6, s46, v10, v6
	v_fma_f32 v7, s46, v11, v7
	v_fma_f32 v16, s47, v4, -v12
	v_fma_f32 v17, s47, v5, -v13
	v_fma_f32 v18, s47, v6, -v14
	v_fma_f32 v19, s47, v7, -v15
	v_cvt_pk_bf16_f32 v20, v16, v17
	v_cvt_pk_bf16_f32 v21, v18, v19
	global_store_dwordx2 v0, v[20:21], s[24:25]
	global_load_dwordx2 v[146:147], v0, s[38:39] offset:2048
	s_add_u32 s38, s38, 0x1000
	s_addc_u32 s39, s39, 0
	global_load_dwordx2 v[148:149], v0, s[38:39]
	v_fma_f32 v4, -s48, v22, v4
	v_fma_f32 v5, -s48, v23, v5
	v_fma_f32 v6, -s48, v24, v6
	v_fma_f32 v7, -s48, v25, v7
	v_readlane_b32 s46, v26, 4
	v_readlane_b32 s47, v27, 1
	v_readlane_b32 s48, v26, 1
	s_waitcnt vmcnt(49)
	v_lshlrev_b32_e32 v8, 16, v52
	v_and_b32_e32 v9, 0xffff0000, v52
	v_lshlrev_b32_e32 v10, 16, v53
	v_and_b32_e32 v11, 0xffff0000, v53
	v_lshlrev_b32_e32 v22, 16, v46
	v_and_b32_e32 v23, 0xffff0000, v46
	v_lshlrev_b32_e32 v24, 16, v47
	v_and_b32_e32 v25, 0xffff0000, v47
	v_mul_f32_e32 v12, s46, v8
	v_mul_f32_e32 v13, s46, v9
	v_mul_f32_e32 v14, s46, v10
	v_mul_f32_e32 v15, s46, v11
	v_fma_f32 v4, s46, v8, v4
	v_fma_f32 v5, s46, v9, v5
	v_fma_f32 v6, s46, v10, v6
	v_fma_f32 v7, s46, v11, v7
	v_fma_f32 v16, s47, v4, -v12
	v_fma_f32 v17, s47, v5, -v13
	v_fma_f32 v18, s47, v6, -v14
	v_fma_f32 v19, s47, v7, -v15
	v_cvt_pk_bf16_f32 v38, v16, v17
	v_cvt_pk_bf16_f32 v39, v18, v19
	global_store_dwordx2 v0, v[38:39], s[24:25] offset:512
	global_load_dwordx2 v[150:151], v0, s[38:39] offset:2048
	s_add_u32 s38, s38, 0x1000
	s_addc_u32 s39, s39, 0
	global_load_dwordx2 v[152:153], v0, s[38:39]
	v_fma_f32 v4, -s48, v22, v4
	v_fma_f32 v5, -s48, v23, v5
	v_fma_f32 v6, -s48, v24, v6
	v_fma_f32 v7, -s48, v25, v7
	v_readlane_b32 s46, v26, 5
	v_readlane_b32 s47, v27, 2
	v_readlane_b32 s48, v26, 2
	s_waitcnt vmcnt(51)
	v_lshlrev_b32_e32 v8, 16, v54
	v_and_b32_e32 v9, 0xffff0000, v54
	v_lshlrev_b32_e32 v10, 16, v55
	v_and_b32_e32 v11, 0xffff0000, v55
	v_lshlrev_b32_e32 v22, 16, v48
	v_and_b32_e32 v23, 0xffff0000, v48
	v_lshlrev_b32_e32 v24, 16, v49
	v_and_b32_e32 v25, 0xffff0000, v49
	v_mul_f32_e32 v12, s46, v8
	v_mul_f32_e32 v13, s46, v9
	v_mul_f32_e32 v14, s46, v10
	v_mul_f32_e32 v15, s46, v11
	v_fma_f32 v4, s46, v8, v4
	v_fma_f32 v5, s46, v9, v5
	v_fma_f32 v6, s46, v10, v6
	v_fma_f32 v7, s46, v11, v7
	v_fma_f32 v16, s47, v4, -v12
	v_fma_f32 v17, s47, v5, -v13
	v_fma_f32 v18, s47, v6, -v14
	v_fma_f32 v19, s47, v7, -v15
	v_cvt_pk_bf16_f32 v20, v16, v17
	v_cvt_pk_bf16_f32 v21, v18, v19
	global_store_dwordx2 v0, v[20:21], s[24:25] offset:1024
	global_load_dwordx2 v[154:155], v0, s[38:39] offset:2048
	s_add_u32 s38, s38, 0x1000
	s_addc_u32 s39, s39, 0
	global_load_dwordx2 v[156:157], v0, s[38:39]
	v_fma_f32 v4, -s48, v22, v4
	v_fma_f32 v5, -s48, v23, v5
	v_fma_f32 v6, -s48, v24, v6
	v_fma_f32 v7, -s48, v25, v7
	v_readlane_b32 s46, v26, 6
	v_readlane_b32 s47, v27, 3
	v_readlane_b32 s48, v26, 3
	s_waitcnt vmcnt(52)
	v_lshlrev_b32_e32 v8, 16, v56
	v_and_b32_e32 v9, 0xffff0000, v56
	v_lshlrev_b32_e32 v10, 16, v57
	v_and_b32_e32 v11, 0xffff0000, v57
	v_lshlrev_b32_e32 v22, 16, v50
	v_and_b32_e32 v23, 0xffff0000, v50
	v_lshlrev_b32_e32 v24, 16, v51
	v_and_b32_e32 v25, 0xffff0000, v51
	v_mul_f32_e32 v12, s46, v8
	v_mul_f32_e32 v13, s46, v9
	v_mul_f32_e32 v14, s46, v10
	v_mul_f32_e32 v15, s46, v11
	v_fma_f32 v4, s46, v8, v4
	v_fma_f32 v5, s46, v9, v5
	v_fma_f32 v6, s46, v10, v6
	v_fma_f32 v7, s46, v11, v7
	v_fma_f32 v16, s47, v4, -v12
	v_fma_f32 v17, s47, v5, -v13
	v_fma_f32 v18, s47, v6, -v14
	v_fma_f32 v19, s47, v7, -v15
	v_cvt_pk_bf16_f32 v38, v16, v17
	v_cvt_pk_bf16_f32 v39, v18, v19
	global_store_dwordx2 v0, v[38:39], s[24:25] offset:1536
	global_load_dwordx2 v[158:159], v0, s[38:39] offset:2048
	s_add_u32 s38, s38, 0x1000
	s_addc_u32 s39, s39, 0
	global_load_dwordx2 v[160:161], v0, s[38:39]
	v_fma_f32 v4, -s48, v22, v4
	v_fma_f32 v5, -s48, v23, v5
	v_fma_f32 v6, -s48, v24, v6
	v_fma_f32 v7, -s48, v25, v7
	v_readlane_b32 s46, v26, 7
	v_readlane_b32 s47, v27, 4
	v_readlane_b32 s48, v26, 4
	s_waitcnt vmcnt(52)
	v_lshlrev_b32_e32 v8, 16, v58
	v_and_b32_e32 v9, 0xffff0000, v58
	v_lshlrev_b32_e32 v10, 16, v59
	v_and_b32_e32 v11, 0xffff0000, v59
	v_lshlrev_b32_e32 v22, 16, v52
	v_and_b32_e32 v23, 0xffff0000, v52
	v_lshlrev_b32_e32 v24, 16, v53
	v_and_b32_e32 v25, 0xffff0000, v53
	v_mul_f32_e32 v12, s46, v8
	v_mul_f32_e32 v13, s46, v9
	v_mul_f32_e32 v14, s46, v10
	v_mul_f32_e32 v15, s46, v11
	v_fma_f32 v4, s46, v8, v4
	v_fma_f32 v5, s46, v9, v5
	v_fma_f32 v6, s46, v10, v6
	v_fma_f32 v7, s46, v11, v7
	v_fma_f32 v16, s47, v4, -v12
	v_fma_f32 v17, s47, v5, -v13
	v_fma_f32 v18, s47, v6, -v14
	v_fma_f32 v19, s47, v7, -v15
	v_cvt_pk_bf16_f32 v20, v16, v17
	v_cvt_pk_bf16_f32 v21, v18, v19
	global_store_dwordx2 v0, v[20:21], s[24:25] offset:2048
	global_load_dwordx2 v[162:163], v0, s[38:39] offset:2048
	s_add_u32 s38, s38, 0x1000
	s_addc_u32 s39, s39, 0
	global_load_dwordx2 v[164:165], v0, s[38:39]
	v_fma_f32 v4, -s48, v22, v4
	v_fma_f32 v5, -s48, v23, v5
	v_fma_f32 v6, -s48, v24, v6
	v_fma_f32 v7, -s48, v25, v7
	v_readlane_b32 s46, v26, 8
	v_readlane_b32 s47, v27, 5
	v_readlane_b32 s48, v26, 5
	s_waitcnt vmcnt(52)
	v_lshlrev_b32_e32 v8, 16, v60
	v_and_b32_e32 v9, 0xffff0000, v60
	v_lshlrev_b32_e32 v10, 16, v61
	v_and_b32_e32 v11, 0xffff0000, v61
	v_lshlrev_b32_e32 v22, 16, v54
	v_and_b32_e32 v23, 0xffff0000, v54
	v_lshlrev_b32_e32 v24, 16, v55
	v_and_b32_e32 v25, 0xffff0000, v55
	v_mul_f32_e32 v12, s46, v8
	v_mul_f32_e32 v13, s46, v9
	v_mul_f32_e32 v14, s46, v10
	v_mul_f32_e32 v15, s46, v11
	v_fma_f32 v4, s46, v8, v4
	v_fma_f32 v5, s46, v9, v5
	v_fma_f32 v6, s46, v10, v6
	v_fma_f32 v7, s46, v11, v7
	v_fma_f32 v16, s47, v4, -v12
	v_fma_f32 v17, s47, v5, -v13
	v_fma_f32 v18, s47, v6, -v14
	v_fma_f32 v19, s47, v7, -v15
	v_cvt_pk_bf16_f32 v38, v16, v17
	v_cvt_pk_bf16_f32 v39, v18, v19
	global_store_dwordx2 v0, v[38:39], s[24:25] offset:2560
	global_load_dwordx2 v[166:167], v0, s[38:39] offset:2048
	s_add_u32 s38, s38, 0x1000
	s_addc_u32 s39, s39, 0
	global_load_dwordx2 v[168:169], v0, s[38:39]
	v_fma_f32 v4, -s48, v22, v4
	v_fma_f32 v5, -s48, v23, v5
	v_fma_f32 v6, -s48, v24, v6
	v_fma_f32 v7, -s48, v25, v7
	v_readlane_b32 s46, v26, 9
	v_readlane_b32 s47, v27, 6
	v_readlane_b32 s48, v26, 6
	s_waitcnt vmcnt(52)
	v_lshlrev_b32_e32 v8, 16, v62
	v_and_b32_e32 v9, 0xffff0000, v62
	v_lshlrev_b32_e32 v10, 16, v63
	v_and_b32_e32 v11, 0xffff0000, v63
	v_lshlrev_b32_e32 v22, 16, v56
	v_and_b32_e32 v23, 0xffff0000, v56
	v_lshlrev_b32_e32 v24, 16, v57
	v_and_b32_e32 v25, 0xffff0000, v57
	v_mul_f32_e32 v12, s46, v8
	v_mul_f32_e32 v13, s46, v9
	v_mul_f32_e32 v14, s46, v10
	v_mul_f32_e32 v15, s46, v11
	v_fma_f32 v4, s46, v8, v4
	v_fma_f32 v5, s46, v9, v5
	v_fma_f32 v6, s46, v10, v6
	v_fma_f32 v7, s46, v11, v7
	v_fma_f32 v16, s47, v4, -v12
	v_fma_f32 v17, s47, v5, -v13
	v_fma_f32 v18, s47, v6, -v14
	v_fma_f32 v19, s47, v7, -v15
	v_cvt_pk_bf16_f32 v20, v16, v17
	v_cvt_pk_bf16_f32 v21, v18, v19
	global_store_dwordx2 v0, v[20:21], s[24:25] offset:3072
	global_load_dwordx2 v[170:171], v0, s[38:39] offset:2048
	s_add_u32 s38, s38, 0x1000
	s_addc_u32 s39, s39, 0
	global_load_dwordx2 v[172:173], v0, s[38:39]
	v_fma_f32 v4, -s48, v22, v4
	v_fma_f32 v5, -s48, v23, v5
	v_fma_f32 v6, -s48, v24, v6
	v_fma_f32 v7, -s48, v25, v7
	v_readlane_b32 s46, v26, 10
	v_readlane_b32 s47, v27, 7
	v_readlane_b32 s48, v26, 7
	s_waitcnt vmcnt(52)
	v_lshlrev_b32_e32 v8, 16, v64
	v_and_b32_e32 v9, 0xffff0000, v64
	v_lshlrev_b32_e32 v10, 16, v65
	v_and_b32_e32 v11, 0xffff0000, v65
	v_lshlrev_b32_e32 v22, 16, v58
	v_and_b32_e32 v23, 0xffff0000, v58
	v_lshlrev_b32_e32 v24, 16, v59
	v_and_b32_e32 v25, 0xffff0000, v59
	v_mul_f32_e32 v12, s46, v8
	v_mul_f32_e32 v13, s46, v9
	v_mul_f32_e32 v14, s46, v10
	v_mul_f32_e32 v15, s46, v11
	v_fma_f32 v4, s46, v8, v4
	v_fma_f32 v5, s46, v9, v5
	v_fma_f32 v6, s46, v10, v6
	v_fma_f32 v7, s46, v11, v7
	v_fma_f32 v16, s47, v4, -v12
	v_fma_f32 v17, s47, v5, -v13
	v_fma_f32 v18, s47, v6, -v14
	v_fma_f32 v19, s47, v7, -v15
	v_cvt_pk_bf16_f32 v38, v16, v17
	v_cvt_pk_bf16_f32 v39, v18, v19
	global_store_dwordx2 v0, v[38:39], s[24:25] offset:3584
	global_load_dwordx2 v[174:175], v0, s[38:39] offset:2048
	s_add_u32 s38, s38, 0x1000
	s_addc_u32 s39, s39, 0
	global_load_dwordx2 v[176:177], v0, s[38:39]
	v_fma_f32 v4, -s48, v22, v4
	v_fma_f32 v5, -s48, v23, v5
	v_fma_f32 v6, -s48, v24, v6
	v_fma_f32 v7, -s48, v25, v7
	v_readlane_b32 s46, v26, 11
	v_readlane_b32 s47, v27, 8
	v_readlane_b32 s48, v26, 8
	s_waitcnt vmcnt(52)
	v_lshlrev_b32_e32 v8, 16, v66
	v_and_b32_e32 v9, 0xffff0000, v66
	v_lshlrev_b32_e32 v10, 16, v67
	v_and_b32_e32 v11, 0xffff0000, v67
	v_lshlrev_b32_e32 v22, 16, v60
	v_and_b32_e32 v23, 0xffff0000, v60
	v_lshlrev_b32_e32 v24, 16, v61
	v_and_b32_e32 v25, 0xffff0000, v61
	v_mul_f32_e32 v12, s46, v8
	v_mul_f32_e32 v13, s46, v9
	v_mul_f32_e32 v14, s46, v10
	v_mul_f32_e32 v15, s46, v11
	v_fma_f32 v4, s46, v8, v4
	v_fma_f32 v5, s46, v9, v5
	v_fma_f32 v6, s46, v10, v6
	v_fma_f32 v7, s46, v11, v7
	v_fma_f32 v16, s47, v4, -v12
	v_fma_f32 v17, s47, v5, -v13
	v_fma_f32 v18, s47, v6, -v14
	v_fma_f32 v19, s47, v7, -v15
	v_cvt_pk_bf16_f32 v20, v16, v17
	v_cvt_pk_bf16_f32 v21, v18, v19
	s_add_u32 s24, s24, 0x1000
	s_addc_u32 s25, s25, 0
	global_store_dwordx2 v0, v[20:21], s[24:25]
	global_load_dwordx2 v[178:179], v0, s[38:39] offset:2048
	s_add_u32 s38, s38, 0x1000
	s_addc_u32 s39, s39, 0
	global_load_dwordx2 v[180:181], v0, s[38:39]
	v_fma_f32 v4, -s48, v22, v4
	v_fma_f32 v5, -s48, v23, v5
	v_fma_f32 v6, -s48, v24, v6
	v_fma_f32 v7, -s48, v25, v7
	v_readlane_b32 s46, v26, 12
	v_readlane_b32 s47, v27, 9
	v_readlane_b32 s48, v26, 9
	s_waitcnt vmcnt(52)
	v_lshlrev_b32_e32 v8, 16, v68
	v_and_b32_e32 v9, 0xffff0000, v68
	v_lshlrev_b32_e32 v10, 16, v69
	v_and_b32_e32 v11, 0xffff0000, v69
	v_lshlrev_b32_e32 v22, 16, v62
	v_and_b32_e32 v23, 0xffff0000, v62
	v_lshlrev_b32_e32 v24, 16, v63
	v_and_b32_e32 v25, 0xffff0000, v63
	v_mul_f32_e32 v12, s46, v8
	v_mul_f32_e32 v13, s46, v9
	v_mul_f32_e32 v14, s46, v10
	v_mul_f32_e32 v15, s46, v11
	v_fma_f32 v4, s46, v8, v4
	v_fma_f32 v5, s46, v9, v5
	v_fma_f32 v6, s46, v10, v6
	v_fma_f32 v7, s46, v11, v7
	v_fma_f32 v16, s47, v4, -v12
	v_fma_f32 v17, s47, v5, -v13
	v_fma_f32 v18, s47, v6, -v14
	v_fma_f32 v19, s47, v7, -v15
	v_cvt_pk_bf16_f32 v38, v16, v17
	v_cvt_pk_bf16_f32 v39, v18, v19
	global_store_dwordx2 v0, v[38:39], s[24:25] offset:512
	global_load_dwordx2 v[182:183], v0, s[38:39] offset:2048
	s_add_u32 s38, s38, 0x1000
	s_addc_u32 s39, s39, 0
	global_load_dwordx2 v[184:185], v0, s[38:39]
	v_fma_f32 v4, -s48, v22, v4
	v_fma_f32 v5, -s48, v23, v5
	v_fma_f32 v6, -s48, v24, v6
	v_fma_f32 v7, -s48, v25, v7
	v_readlane_b32 s46, v26, 13
	v_readlane_b32 s47, v27, 10
	v_readlane_b32 s48, v26, 10
	s_waitcnt vmcnt(52)
	v_lshlrev_b32_e32 v8, 16, v70
	v_and_b32_e32 v9, 0xffff0000, v70
	v_lshlrev_b32_e32 v10, 16, v71
	v_and_b32_e32 v11, 0xffff0000, v71
	v_lshlrev_b32_e32 v22, 16, v64
	v_and_b32_e32 v23, 0xffff0000, v64
	v_lshlrev_b32_e32 v24, 16, v65
	v_and_b32_e32 v25, 0xffff0000, v65
	v_mul_f32_e32 v12, s46, v8
	v_mul_f32_e32 v13, s46, v9
	v_mul_f32_e32 v14, s46, v10
	v_mul_f32_e32 v15, s46, v11
	v_fma_f32 v4, s46, v8, v4
	v_fma_f32 v5, s46, v9, v5
	v_fma_f32 v6, s46, v10, v6
	v_fma_f32 v7, s46, v11, v7
	v_fma_f32 v16, s47, v4, -v12
	v_fma_f32 v17, s47, v5, -v13
	v_fma_f32 v18, s47, v6, -v14
	v_fma_f32 v19, s47, v7, -v15
	v_cvt_pk_bf16_f32 v20, v16, v17
	v_cvt_pk_bf16_f32 v21, v18, v19
	global_store_dwordx2 v0, v[20:21], s[24:25] offset:1024
	global_load_dwordx2 v[186:187], v0, s[38:39] offset:2048
	s_add_u32 s38, s38, 0x1000
	s_addc_u32 s39, s39, 0
	global_load_dwordx2 v[188:189], v0, s[38:39]
	v_fma_f32 v4, -s48, v22, v4
	v_fma_f32 v5, -s48, v23, v5
	v_fma_f32 v6, -s48, v24, v6
	v_fma_f32 v7, -s48, v25, v7
	v_readlane_b32 s46, v26, 14
	v_readlane_b32 s47, v27, 11
	v_readlane_b32 s48, v26, 11
	s_waitcnt vmcnt(52)
	v_lshlrev_b32_e32 v8, 16, v72
	v_and_b32_e32 v9, 0xffff0000, v72
	v_lshlrev_b32_e32 v10, 16, v73
	v_and_b32_e32 v11, 0xffff0000, v73
	v_lshlrev_b32_e32 v22, 16, v66
	v_and_b32_e32 v23, 0xffff0000, v66
	v_lshlrev_b32_e32 v24, 16, v67
	v_and_b32_e32 v25, 0xffff0000, v67
	v_mul_f32_e32 v12, s46, v8
	v_mul_f32_e32 v13, s46, v9
	v_mul_f32_e32 v14, s46, v10
	v_mul_f32_e32 v15, s46, v11
	v_fma_f32 v4, s46, v8, v4
	v_fma_f32 v5, s46, v9, v5
	v_fma_f32 v6, s46, v10, v6
	v_fma_f32 v7, s46, v11, v7
	v_fma_f32 v16, s47, v4, -v12
	v_fma_f32 v17, s47, v5, -v13
	v_fma_f32 v18, s47, v6, -v14
	v_fma_f32 v19, s47, v7, -v15
	v_cvt_pk_bf16_f32 v38, v16, v17
	v_cvt_pk_bf16_f32 v39, v18, v19
	global_store_dwordx2 v0, v[38:39], s[24:25] offset:1536
	global_load_dwordx2 v[190:191], v0, s[38:39] offset:2048
	s_add_u32 s38, s38, 0x1000
	s_addc_u32 s39, s39, 0
	global_load_dwordx2 v[194:195], v0, s[38:39]
	v_fma_f32 v4, -s48, v22, v4
	v_fma_f32 v5, -s48, v23, v5
	v_fma_f32 v6, -s48, v24, v6
	v_fma_f32 v7, -s48, v25, v7
	v_readlane_b32 s46, v26, 15
	v_readlane_b32 s47, v27, 12
	v_readlane_b32 s48, v26, 12
	s_waitcnt vmcnt(52)
	v_lshlrev_b32_e32 v8, 16, v74
	v_and_b32_e32 v9, 0xffff0000, v74
	v_lshlrev_b32_e32 v10, 16, v75
	v_and_b32_e32 v11, 0xffff0000, v75
	v_lshlrev_b32_e32 v22, 16, v68
	v_and_b32_e32 v23, 0xffff0000, v68
	v_lshlrev_b32_e32 v24, 16, v69
	v_and_b32_e32 v25, 0xffff0000, v69
	v_mul_f32_e32 v12, s46, v8
	v_mul_f32_e32 v13, s46, v9
	v_mul_f32_e32 v14, s46, v10
	v_mul_f32_e32 v15, s46, v11
	v_fma_f32 v4, s46, v8, v4
	v_fma_f32 v5, s46, v9, v5
	v_fma_f32 v6, s46, v10, v6
	v_fma_f32 v7, s46, v11, v7
	v_fma_f32 v16, s47, v4, -v12
	v_fma_f32 v17, s47, v5, -v13
	v_fma_f32 v18, s47, v6, -v14
	v_fma_f32 v19, s47, v7, -v15
	v_cvt_pk_bf16_f32 v20, v16, v17
	v_cvt_pk_bf16_f32 v21, v18, v19
	global_store_dwordx2 v0, v[20:21], s[24:25] offset:2048
	global_load_dwordx2 v[196:197], v0, s[38:39] offset:2048
	s_add_u32 s38, s38, 0x1000
	s_addc_u32 s39, s39, 0
	global_load_dwordx2 v[198:199], v0, s[38:39]
	v_fma_f32 v4, -s48, v22, v4
	v_fma_f32 v5, -s48, v23, v5
	v_fma_f32 v6, -s48, v24, v6
	v_fma_f32 v7, -s48, v25, v7
	v_readlane_b32 s46, v26, 16
	v_readlane_b32 s47, v27, 13
	v_readlane_b32 s48, v26, 13
	s_waitcnt vmcnt(52)
	v_lshlrev_b32_e32 v8, 16, v76
	v_and_b32_e32 v9, 0xffff0000, v76
	v_lshlrev_b32_e32 v10, 16, v77
	v_and_b32_e32 v11, 0xffff0000, v77
	v_lshlrev_b32_e32 v22, 16, v70
	v_and_b32_e32 v23, 0xffff0000, v70
	v_lshlrev_b32_e32 v24, 16, v71
	v_and_b32_e32 v25, 0xffff0000, v71
	v_mul_f32_e32 v12, s46, v8
	v_mul_f32_e32 v13, s46, v9
	v_mul_f32_e32 v14, s46, v10
	v_mul_f32_e32 v15, s46, v11
	v_fma_f32 v4, s46, v8, v4
	v_fma_f32 v5, s46, v9, v5
	v_fma_f32 v6, s46, v10, v6
	v_fma_f32 v7, s46, v11, v7
	v_fma_f32 v16, s47, v4, -v12
	v_fma_f32 v17, s47, v5, -v13
	v_fma_f32 v18, s47, v6, -v14
	v_fma_f32 v19, s47, v7, -v15
	v_cvt_pk_bf16_f32 v38, v16, v17
	v_cvt_pk_bf16_f32 v39, v18, v19
	global_store_dwordx2 v0, v[38:39], s[24:25] offset:2560
	global_load_dwordx2 v[200:201], v0, s[38:39] offset:2048
	s_add_u32 s38, s38, 0x1000
	s_addc_u32 s39, s39, 0
	global_load_dwordx2 v[202:203], v0, s[38:39]
	v_fma_f32 v4, -s48, v22, v4
	v_fma_f32 v5, -s48, v23, v5
	v_fma_f32 v6, -s48, v24, v6
	v_fma_f32 v7, -s48, v25, v7
	v_readlane_b32 s46, v26, 17
	v_readlane_b32 s47, v27, 14
	v_readlane_b32 s48, v26, 14
	s_waitcnt vmcnt(52)
	v_lshlrev_b32_e32 v8, 16, v78
	v_and_b32_e32 v9, 0xffff0000, v78
	v_lshlrev_b32_e32 v10, 16, v79
	v_and_b32_e32 v11, 0xffff0000, v79
	v_lshlrev_b32_e32 v22, 16, v72
	v_and_b32_e32 v23, 0xffff0000, v72
	v_lshlrev_b32_e32 v24, 16, v73
	v_and_b32_e32 v25, 0xffff0000, v73
	v_mul_f32_e32 v12, s46, v8
	v_mul_f32_e32 v13, s46, v9
	v_mul_f32_e32 v14, s46, v10
	v_mul_f32_e32 v15, s46, v11
	v_fma_f32 v4, s46, v8, v4
	v_fma_f32 v5, s46, v9, v5
	v_fma_f32 v6, s46, v10, v6
	v_fma_f32 v7, s46, v11, v7
	v_fma_f32 v16, s47, v4, -v12
	v_fma_f32 v17, s47, v5, -v13
	v_fma_f32 v18, s47, v6, -v14
	v_fma_f32 v19, s47, v7, -v15
	v_cvt_pk_bf16_f32 v20, v16, v17
	v_cvt_pk_bf16_f32 v21, v18, v19
	global_store_dwordx2 v0, v[20:21], s[24:25] offset:3072
	global_load_dwordx2 v[204:205], v0, s[38:39] offset:2048
	s_add_u32 s38, s38, 0x1000
	s_addc_u32 s39, s39, 0
	global_load_dwordx2 v[206:207], v0, s[38:39]
	v_fma_f32 v4, -s48, v22, v4
	v_fma_f32 v5, -s48, v23, v5
	v_fma_f32 v6, -s48, v24, v6
	v_fma_f32 v7, -s48, v25, v7
	v_readlane_b32 s46, v26, 18
	v_readlane_b32 s47, v27, 15
	v_readlane_b32 s48, v26, 15
	s_waitcnt vmcnt(52)
	v_lshlrev_b32_e32 v8, 16, v80
	v_and_b32_e32 v9, 0xffff0000, v80
	v_lshlrev_b32_e32 v10, 16, v81
	v_and_b32_e32 v11, 0xffff0000, v81
	v_lshlrev_b32_e32 v22, 16, v74
	v_and_b32_e32 v23, 0xffff0000, v74
	v_lshlrev_b32_e32 v24, 16, v75
	v_and_b32_e32 v25, 0xffff0000, v75
	v_mul_f32_e32 v12, s46, v8
	v_mul_f32_e32 v13, s46, v9
	v_mul_f32_e32 v14, s46, v10
	v_mul_f32_e32 v15, s46, v11
	v_fma_f32 v4, s46, v8, v4
	v_fma_f32 v5, s46, v9, v5
	v_fma_f32 v6, s46, v10, v6
	v_fma_f32 v7, s46, v11, v7
	v_fma_f32 v16, s47, v4, -v12
	v_fma_f32 v17, s47, v5, -v13
	v_fma_f32 v18, s47, v6, -v14
	v_fma_f32 v19, s47, v7, -v15
	v_cvt_pk_bf16_f32 v38, v16, v17
	v_cvt_pk_bf16_f32 v39, v18, v19
	global_store_dwordx2 v0, v[38:39], s[24:25] offset:3584
	global_load_dwordx2 v[208:209], v0, s[38:39] offset:2048
	v_fma_f32 v4, -s48, v22, v4
	v_fma_f32 v5, -s48, v23, v5
	v_fma_f32 v6, -s48, v24, v6
	v_fma_f32 v7, -s48, v25, v7
	v_readlane_b32 s46, v26, 19
	v_readlane_b32 s47, v27, 16
	v_readlane_b32 s48, v26, 16
	s_waitcnt vmcnt(52)
	v_lshlrev_b32_e32 v8, 16, v82
	v_and_b32_e32 v9, 0xffff0000, v82
	v_lshlrev_b32_e32 v10, 16, v83
	v_and_b32_e32 v11, 0xffff0000, v83
	v_lshlrev_b32_e32 v22, 16, v76
	v_and_b32_e32 v23, 0xffff0000, v76
	v_lshlrev_b32_e32 v24, 16, v77
	v_and_b32_e32 v25, 0xffff0000, v77
	v_mul_f32_e32 v12, s46, v8
	v_mul_f32_e32 v13, s46, v9
	v_mul_f32_e32 v14, s46, v10
	v_mul_f32_e32 v15, s46, v11
	v_fma_f32 v4, s46, v8, v4
	v_fma_f32 v5, s46, v9, v5
	v_fma_f32 v6, s46, v10, v6
	v_fma_f32 v7, s46, v11, v7
	v_fma_f32 v16, s47, v4, -v12
	v_fma_f32 v17, s47, v5, -v13
	v_fma_f32 v18, s47, v6, -v14
	v_fma_f32 v19, s47, v7, -v15
	v_cvt_pk_bf16_f32 v20, v16, v17
	v_cvt_pk_bf16_f32 v21, v18, v19
	s_add_u32 s24, s24, 0x1000
	s_addc_u32 s25, s25, 0
	global_store_dwordx2 v0, v[20:21], s[24:25]
	v_fma_f32 v4, -s48, v22, v4
	v_fma_f32 v5, -s48, v23, v5
	v_fma_f32 v6, -s48, v24, v6
	v_fma_f32 v7, -s48, v25, v7
	v_readlane_b32 s46, v26, 20
	v_readlane_b32 s47, v27, 17
	v_readlane_b32 s48, v26, 17
	s_waitcnt vmcnt(52)
	v_lshlrev_b32_e32 v8, 16, v84
	v_and_b32_e32 v9, 0xffff0000, v84
	v_lshlrev_b32_e32 v10, 16, v85
	v_and_b32_e32 v11, 0xffff0000, v85
	v_lshlrev_b32_e32 v22, 16, v78
	v_and_b32_e32 v23, 0xffff0000, v78
	v_lshlrev_b32_e32 v24, 16, v79
	v_and_b32_e32 v25, 0xffff0000, v79
	v_mul_f32_e32 v12, s46, v8
	v_mul_f32_e32 v13, s46, v9
	v_mul_f32_e32 v14, s46, v10
	v_mul_f32_e32 v15, s46, v11
	v_fma_f32 v4, s46, v8, v4
	v_fma_f32 v5, s46, v9, v5
	v_fma_f32 v6, s46, v10, v6
	v_fma_f32 v7, s46, v11, v7
	v_fma_f32 v16, s47, v4, -v12
	v_fma_f32 v17, s47, v5, -v13
	v_fma_f32 v18, s47, v6, -v14
	v_fma_f32 v19, s47, v7, -v15
	v_cvt_pk_bf16_f32 v38, v16, v17
	v_cvt_pk_bf16_f32 v39, v18, v19
	global_store_dwordx2 v0, v[38:39], s[24:25] offset:512
	v_fma_f32 v4, -s48, v22, v4
	v_fma_f32 v5, -s48, v23, v5
	v_fma_f32 v6, -s48, v24, v6
	v_fma_f32 v7, -s48, v25, v7
	v_readlane_b32 s46, v26, 21
	v_readlane_b32 s47, v27, 18
	v_readlane_b32 s48, v26, 18
	s_waitcnt vmcnt(52)
	v_lshlrev_b32_e32 v8, 16, v86
	v_and_b32_e32 v9, 0xffff0000, v86
	v_lshlrev_b32_e32 v10, 16, v87
	v_and_b32_e32 v11, 0xffff0000, v87
	v_lshlrev_b32_e32 v22, 16, v80
	v_and_b32_e32 v23, 0xffff0000, v80
	v_lshlrev_b32_e32 v24, 16, v81
	v_and_b32_e32 v25, 0xffff0000, v81
	v_mul_f32_e32 v12, s46, v8
	v_mul_f32_e32 v13, s46, v9
	v_mul_f32_e32 v14, s46, v10
	v_mul_f32_e32 v15, s46, v11
	v_fma_f32 v4, s46, v8, v4
	v_fma_f32 v5, s46, v9, v5
	v_fma_f32 v6, s46, v10, v6
	v_fma_f32 v7, s46, v11, v7
	v_fma_f32 v16, s47, v4, -v12
	v_fma_f32 v17, s47, v5, -v13
	v_fma_f32 v18, s47, v6, -v14
	v_fma_f32 v19, s47, v7, -v15
	v_cvt_pk_bf16_f32 v20, v16, v17
	v_cvt_pk_bf16_f32 v21, v18, v19
	global_store_dwordx2 v0, v[20:21], s[24:25] offset:1024
	v_fma_f32 v4, -s48, v22, v4
	v_fma_f32 v5, -s48, v23, v5
	v_fma_f32 v6, -s48, v24, v6
	v_fma_f32 v7, -s48, v25, v7
	v_readlane_b32 s46, v26, 22
	v_readlane_b32 s47, v27, 19
	v_readlane_b32 s48, v26, 19
	s_waitcnt vmcnt(52)
	v_lshlrev_b32_e32 v8, 16, v88
	v_and_b32_e32 v9, 0xffff0000, v88
	v_lshlrev_b32_e32 v10, 16, v89
	v_and_b32_e32 v11, 0xffff0000, v89
	v_lshlrev_b32_e32 v22, 16, v82
	v_and_b32_e32 v23, 0xffff0000, v82
	v_lshlrev_b32_e32 v24, 16, v83
	v_and_b32_e32 v25, 0xffff0000, v83
	v_mul_f32_e32 v12, s46, v8
	v_mul_f32_e32 v13, s46, v9
	v_mul_f32_e32 v14, s46, v10
	v_mul_f32_e32 v15, s46, v11
	v_fma_f32 v4, s46, v8, v4
	v_fma_f32 v5, s46, v9, v5
	v_fma_f32 v6, s46, v10, v6
	v_fma_f32 v7, s46, v11, v7
	v_fma_f32 v16, s47, v4, -v12
	v_fma_f32 v17, s47, v5, -v13
	v_fma_f32 v18, s47, v6, -v14
	v_fma_f32 v19, s47, v7, -v15
	v_cvt_pk_bf16_f32 v38, v16, v17
	v_cvt_pk_bf16_f32 v39, v18, v19
	global_store_dwordx2 v0, v[38:39], s[24:25] offset:1536
	v_fma_f32 v4, -s48, v22, v4
	v_fma_f32 v5, -s48, v23, v5
	v_fma_f32 v6, -s48, v24, v6
	v_fma_f32 v7, -s48, v25, v7
	v_readlane_b32 s46, v26, 23
	v_readlane_b32 s47, v27, 20
	v_readlane_b32 s48, v26, 20
	s_waitcnt vmcnt(52)
	v_lshlrev_b32_e32 v8, 16, v90
	v_and_b32_e32 v9, 0xffff0000, v90
	v_lshlrev_b32_e32 v10, 16, v91
	v_and_b32_e32 v11, 0xffff0000, v91
	v_lshlrev_b32_e32 v22, 16, v84
	v_and_b32_e32 v23, 0xffff0000, v84
	v_lshlrev_b32_e32 v24, 16, v85
	v_and_b32_e32 v25, 0xffff0000, v85
	v_mul_f32_e32 v12, s46, v8
	v_mul_f32_e32 v13, s46, v9
	v_mul_f32_e32 v14, s46, v10
	v_mul_f32_e32 v15, s46, v11
	v_fma_f32 v4, s46, v8, v4
	v_fma_f32 v5, s46, v9, v5
	v_fma_f32 v6, s46, v10, v6
	v_fma_f32 v7, s46, v11, v7
	v_fma_f32 v16, s47, v4, -v12
	v_fma_f32 v17, s47, v5, -v13
	v_fma_f32 v18, s47, v6, -v14
	v_fma_f32 v19, s47, v7, -v15
	v_cvt_pk_bf16_f32 v20, v16, v17
	v_cvt_pk_bf16_f32 v21, v18, v19
	global_store_dwordx2 v0, v[20:21], s[24:25] offset:2048
	v_fma_f32 v4, -s48, v22, v4
	v_fma_f32 v5, -s48, v23, v5
	v_fma_f32 v6, -s48, v24, v6
	v_fma_f32 v7, -s48, v25, v7
	v_readlane_b32 s46, v26, 24
	v_readlane_b32 s47, v27, 21
	v_readlane_b32 s48, v26, 21
	s_waitcnt vmcnt(52)
	v_lshlrev_b32_e32 v8, 16, v92
	v_and_b32_e32 v9, 0xffff0000, v92
	v_lshlrev_b32_e32 v10, 16, v93
	v_and_b32_e32 v11, 0xffff0000, v93
	v_lshlrev_b32_e32 v22, 16, v86
	v_and_b32_e32 v23, 0xffff0000, v86
	v_lshlrev_b32_e32 v24, 16, v87
	v_and_b32_e32 v25, 0xffff0000, v87
	v_mul_f32_e32 v12, s46, v8
	v_mul_f32_e32 v13, s46, v9
	v_mul_f32_e32 v14, s46, v10
	v_mul_f32_e32 v15, s46, v11
	v_fma_f32 v4, s46, v8, v4
	v_fma_f32 v5, s46, v9, v5
	v_fma_f32 v6, s46, v10, v6
	v_fma_f32 v7, s46, v11, v7
	v_fma_f32 v16, s47, v4, -v12
	v_fma_f32 v17, s47, v5, -v13
	v_fma_f32 v18, s47, v6, -v14
	v_fma_f32 v19, s47, v7, -v15
	v_cvt_pk_bf16_f32 v38, v16, v17
	v_cvt_pk_bf16_f32 v39, v18, v19
	global_store_dwordx2 v0, v[38:39], s[24:25] offset:2560
	v_fma_f32 v4, -s48, v22, v4
	v_fma_f32 v5, -s48, v23, v5
	v_fma_f32 v6, -s48, v24, v6
	v_fma_f32 v7, -s48, v25, v7
	v_readlane_b32 s46, v26, 25
	v_readlane_b32 s47, v27, 22
	v_readlane_b32 s48, v26, 22
	s_waitcnt vmcnt(52)
	v_lshlrev_b32_e32 v8, 16, v94
	v_and_b32_e32 v9, 0xffff0000, v94
	v_lshlrev_b32_e32 v10, 16, v95
	v_and_b32_e32 v11, 0xffff0000, v95
	v_lshlrev_b32_e32 v22, 16, v88
	v_and_b32_e32 v23, 0xffff0000, v88
	v_lshlrev_b32_e32 v24, 16, v89
	v_and_b32_e32 v25, 0xffff0000, v89
	v_mul_f32_e32 v12, s46, v8
	v_mul_f32_e32 v13, s46, v9
	v_mul_f32_e32 v14, s46, v10
	v_mul_f32_e32 v15, s46, v11
	v_fma_f32 v4, s46, v8, v4
	v_fma_f32 v5, s46, v9, v5
	v_fma_f32 v6, s46, v10, v6
	v_fma_f32 v7, s46, v11, v7
	v_fma_f32 v16, s47, v4, -v12
	v_fma_f32 v17, s47, v5, -v13
	v_fma_f32 v18, s47, v6, -v14
	v_fma_f32 v19, s47, v7, -v15
	v_cvt_pk_bf16_f32 v20, v16, v17
	v_cvt_pk_bf16_f32 v21, v18, v19
	global_store_dwordx2 v0, v[20:21], s[24:25] offset:3072
	v_fma_f32 v4, -s48, v22, v4
	v_fma_f32 v5, -s48, v23, v5
	v_fma_f32 v6, -s48, v24, v6
	v_fma_f32 v7, -s48, v25, v7
	v_readlane_b32 s46, v26, 26
	v_readlane_b32 s47, v27, 23
	v_readlane_b32 s48, v26, 23
	s_waitcnt vmcnt(52)
	v_lshlrev_b32_e32 v8, 16, v96
	v_and_b32_e32 v9, 0xffff0000, v96
	v_lshlrev_b32_e32 v10, 16, v97
	v_and_b32_e32 v11, 0xffff0000, v97
	v_lshlrev_b32_e32 v22, 16, v90
	v_and_b32_e32 v23, 0xffff0000, v90
	v_lshlrev_b32_e32 v24, 16, v91
	v_and_b32_e32 v25, 0xffff0000, v91
	v_mul_f32_e32 v12, s46, v8
	v_mul_f32_e32 v13, s46, v9
	v_mul_f32_e32 v14, s46, v10
	v_mul_f32_e32 v15, s46, v11
	v_fma_f32 v4, s46, v8, v4
	v_fma_f32 v5, s46, v9, v5
	v_fma_f32 v6, s46, v10, v6
	v_fma_f32 v7, s46, v11, v7
	v_fma_f32 v16, s47, v4, -v12
	v_fma_f32 v17, s47, v5, -v13
	v_fma_f32 v18, s47, v6, -v14
	v_fma_f32 v19, s47, v7, -v15
	v_cvt_pk_bf16_f32 v38, v16, v17
	v_cvt_pk_bf16_f32 v39, v18, v19
	global_store_dwordx2 v0, v[38:39], s[24:25] offset:3584
	v_fma_f32 v4, -s48, v22, v4
	v_fma_f32 v5, -s48, v23, v5
	v_fma_f32 v6, -s48, v24, v6
	v_fma_f32 v7, -s48, v25, v7
	v_readlane_b32 s46, v26, 27
	v_readlane_b32 s47, v27, 24
	v_readlane_b32 s48, v26, 24
	s_waitcnt vmcnt(52)
	v_lshlrev_b32_e32 v8, 16, v98
	v_and_b32_e32 v9, 0xffff0000, v98
	v_lshlrev_b32_e32 v10, 16, v99
	v_and_b32_e32 v11, 0xffff0000, v99
	v_lshlrev_b32_e32 v22, 16, v92
	v_and_b32_e32 v23, 0xffff0000, v92
	v_lshlrev_b32_e32 v24, 16, v93
	v_and_b32_e32 v25, 0xffff0000, v93
	v_mul_f32_e32 v12, s46, v8
	v_mul_f32_e32 v13, s46, v9
	v_mul_f32_e32 v14, s46, v10
	v_mul_f32_e32 v15, s46, v11
	v_fma_f32 v4, s46, v8, v4
	v_fma_f32 v5, s46, v9, v5
	v_fma_f32 v6, s46, v10, v6
	v_fma_f32 v7, s46, v11, v7
	v_fma_f32 v16, s47, v4, -v12
	v_fma_f32 v17, s47, v5, -v13
	v_fma_f32 v18, s47, v6, -v14
	v_fma_f32 v19, s47, v7, -v15
	v_cvt_pk_bf16_f32 v20, v16, v17
	v_cvt_pk_bf16_f32 v21, v18, v19
	s_add_u32 s24, s24, 0x1000
	s_addc_u32 s25, s25, 0
	global_store_dwordx2 v0, v[20:21], s[24:25]
	v_fma_f32 v4, -s48, v22, v4
	v_fma_f32 v5, -s48, v23, v5
	v_fma_f32 v6, -s48, v24, v6
	v_fma_f32 v7, -s48, v25, v7
	v_readlane_b32 s46, v26, 28
	v_readlane_b32 s47, v27, 25
	v_readlane_b32 s48, v26, 25
	s_waitcnt vmcnt(52)
	v_lshlrev_b32_e32 v8, 16, v100
	v_and_b32_e32 v9, 0xffff0000, v100
	v_lshlrev_b32_e32 v10, 16, v101
	v_and_b32_e32 v11, 0xffff0000, v101
	v_lshlrev_b32_e32 v22, 16, v94
	v_and_b32_e32 v23, 0xffff0000, v94
	v_lshlrev_b32_e32 v24, 16, v95
	v_and_b32_e32 v25, 0xffff0000, v95
	v_mul_f32_e32 v12, s46, v8
	v_mul_f32_e32 v13, s46, v9
	v_mul_f32_e32 v14, s46, v10
	v_mul_f32_e32 v15, s46, v11
	v_fma_f32 v4, s46, v8, v4
	v_fma_f32 v5, s46, v9, v5
	v_fma_f32 v6, s46, v10, v6
	v_fma_f32 v7, s46, v11, v7
	v_fma_f32 v16, s47, v4, -v12
	v_fma_f32 v17, s47, v5, -v13
	v_fma_f32 v18, s47, v6, -v14
	v_fma_f32 v19, s47, v7, -v15
	v_cvt_pk_bf16_f32 v38, v16, v17
	v_cvt_pk_bf16_f32 v39, v18, v19
	global_store_dwordx2 v0, v[38:39], s[24:25] offset:512
	v_fma_f32 v4, -s48, v22, v4
	v_fma_f32 v5, -s48, v23, v5
	v_fma_f32 v6, -s48, v24, v6
	v_fma_f32 v7, -s48, v25, v7
	v_readlane_b32 s46, v26, 29
	v_readlane_b32 s47, v27, 26
	v_readlane_b32 s48, v26, 26
	s_waitcnt vmcnt(52)
	v_lshlrev_b32_e32 v8, 16, v102
	v_and_b32_e32 v9, 0xffff0000, v102
	v_lshlrev_b32_e32 v10, 16, v103
	v_and_b32_e32 v11, 0xffff0000, v103
	v_lshlrev_b32_e32 v22, 16, v96
	v_and_b32_e32 v23, 0xffff0000, v96
	v_lshlrev_b32_e32 v24, 16, v97
	v_and_b32_e32 v25, 0xffff0000, v97
	v_mul_f32_e32 v12, s46, v8
	v_mul_f32_e32 v13, s46, v9
	v_mul_f32_e32 v14, s46, v10
	v_mul_f32_e32 v15, s46, v11
	v_fma_f32 v4, s46, v8, v4
	v_fma_f32 v5, s46, v9, v5
	v_fma_f32 v6, s46, v10, v6
	v_fma_f32 v7, s46, v11, v7
	v_fma_f32 v16, s47, v4, -v12
	v_fma_f32 v17, s47, v5, -v13
	v_fma_f32 v18, s47, v6, -v14
	v_fma_f32 v19, s47, v7, -v15
	v_cvt_pk_bf16_f32 v20, v16, v17
	v_cvt_pk_bf16_f32 v21, v18, v19
	global_store_dwordx2 v0, v[20:21], s[24:25] offset:1024
	v_fma_f32 v4, -s48, v22, v4
	v_fma_f32 v5, -s48, v23, v5
	v_fma_f32 v6, -s48, v24, v6
	v_fma_f32 v7, -s48, v25, v7
	v_readlane_b32 s46, v26, 30
	v_readlane_b32 s47, v27, 27
	v_readlane_b32 s48, v26, 27
	s_waitcnt vmcnt(52)
	v_lshlrev_b32_e32 v8, 16, v104
	v_and_b32_e32 v9, 0xffff0000, v104
	v_lshlrev_b32_e32 v10, 16, v105
	v_and_b32_e32 v11, 0xffff0000, v105
	v_lshlrev_b32_e32 v22, 16, v98
	v_and_b32_e32 v23, 0xffff0000, v98
	v_lshlrev_b32_e32 v24, 16, v99
	v_and_b32_e32 v25, 0xffff0000, v99
	v_mul_f32_e32 v12, s46, v8
	v_mul_f32_e32 v13, s46, v9
	v_mul_f32_e32 v14, s46, v10
	v_mul_f32_e32 v15, s46, v11
	v_fma_f32 v4, s46, v8, v4
	v_fma_f32 v5, s46, v9, v5
	v_fma_f32 v6, s46, v10, v6
	v_fma_f32 v7, s46, v11, v7
	v_fma_f32 v16, s47, v4, -v12
	v_fma_f32 v17, s47, v5, -v13
	v_fma_f32 v18, s47, v6, -v14
	v_fma_f32 v19, s47, v7, -v15
	v_cvt_pk_bf16_f32 v38, v16, v17
	v_cvt_pk_bf16_f32 v39, v18, v19
	global_store_dwordx2 v0, v[38:39], s[24:25] offset:1536
	v_fma_f32 v4, -s48, v22, v4
	v_fma_f32 v5, -s48, v23, v5
	v_fma_f32 v6, -s48, v24, v6
	v_fma_f32 v7, -s48, v25, v7
	v_readlane_b32 s46, v26, 31
	v_readlane_b32 s47, v27, 28
	v_readlane_b32 s48, v26, 28
	s_waitcnt vmcnt(52)
	v_lshlrev_b32_e32 v8, 16, v106
	v_and_b32_e32 v9, 0xffff0000, v106
	v_lshlrev_b32_e32 v10, 16, v107
	v_and_b32_e32 v11, 0xffff0000, v107
	v_lshlrev_b32_e32 v22, 16, v100
	v_and_b32_e32 v23, 0xffff0000, v100
	v_lshlrev_b32_e32 v24, 16, v101
	v_and_b32_e32 v25, 0xffff0000, v101
	v_mul_f32_e32 v12, s46, v8
	v_mul_f32_e32 v13, s46, v9
	v_mul_f32_e32 v14, s46, v10
	v_mul_f32_e32 v15, s46, v11
	v_fma_f32 v4, s46, v8, v4
	v_fma_f32 v5, s46, v9, v5
	v_fma_f32 v6, s46, v10, v6
	v_fma_f32 v7, s46, v11, v7
	v_fma_f32 v16, s47, v4, -v12
	v_fma_f32 v17, s47, v5, -v13
	v_fma_f32 v18, s47, v6, -v14
	v_fma_f32 v19, s47, v7, -v15
	v_cvt_pk_bf16_f32 v20, v16, v17
	v_cvt_pk_bf16_f32 v21, v18, v19
	global_store_dwordx2 v0, v[20:21], s[24:25] offset:2048
	v_fma_f32 v4, -s48, v22, v4
	v_fma_f32 v5, -s48, v23, v5
	v_fma_f32 v6, -s48, v24, v6
	v_fma_f32 v7, -s48, v25, v7
	v_readlane_b32 s46, v26, 32
	v_readlane_b32 s47, v27, 29
	v_readlane_b32 s48, v26, 29
	s_waitcnt vmcnt(52)
	v_lshlrev_b32_e32 v8, 16, v108
	v_and_b32_e32 v9, 0xffff0000, v108
	v_lshlrev_b32_e32 v10, 16, v109
	v_and_b32_e32 v11, 0xffff0000, v109
	v_lshlrev_b32_e32 v22, 16, v102
	v_and_b32_e32 v23, 0xffff0000, v102
	v_lshlrev_b32_e32 v24, 16, v103
	v_and_b32_e32 v25, 0xffff0000, v103
	v_mul_f32_e32 v12, s46, v8
	v_mul_f32_e32 v13, s46, v9
	v_mul_f32_e32 v14, s46, v10
	v_mul_f32_e32 v15, s46, v11
	v_fma_f32 v4, s46, v8, v4
	v_fma_f32 v5, s46, v9, v5
	v_fma_f32 v6, s46, v10, v6
	v_fma_f32 v7, s46, v11, v7
	v_fma_f32 v16, s47, v4, -v12
	v_fma_f32 v17, s47, v5, -v13
	v_fma_f32 v18, s47, v6, -v14
	v_fma_f32 v19, s47, v7, -v15
	v_cvt_pk_bf16_f32 v38, v16, v17
	v_cvt_pk_bf16_f32 v39, v18, v19
	global_store_dwordx2 v0, v[38:39], s[24:25] offset:2560
	v_fma_f32 v4, -s48, v22, v4
	v_fma_f32 v5, -s48, v23, v5
	v_fma_f32 v6, -s48, v24, v6
	v_fma_f32 v7, -s48, v25, v7
	v_readlane_b32 s46, v26, 33
	v_readlane_b32 s47, v27, 30
	v_readlane_b32 s48, v26, 30
	s_waitcnt vmcnt(52)
	v_lshlrev_b32_e32 v8, 16, v110
	v_and_b32_e32 v9, 0xffff0000, v110
	v_lshlrev_b32_e32 v10, 16, v111
	v_and_b32_e32 v11, 0xffff0000, v111
	v_lshlrev_b32_e32 v22, 16, v104
	v_and_b32_e32 v23, 0xffff0000, v104
	v_lshlrev_b32_e32 v24, 16, v105
	v_and_b32_e32 v25, 0xffff0000, v105
	v_mul_f32_e32 v12, s46, v8
	v_mul_f32_e32 v13, s46, v9
	v_mul_f32_e32 v14, s46, v10
	v_mul_f32_e32 v15, s46, v11
	v_fma_f32 v4, s46, v8, v4
	v_fma_f32 v5, s46, v9, v5
	v_fma_f32 v6, s46, v10, v6
	v_fma_f32 v7, s46, v11, v7
	v_fma_f32 v16, s47, v4, -v12
	v_fma_f32 v17, s47, v5, -v13
	v_fma_f32 v18, s47, v6, -v14
	v_fma_f32 v19, s47, v7, -v15
	v_cvt_pk_bf16_f32 v20, v16, v17
	v_cvt_pk_bf16_f32 v21, v18, v19
	global_store_dwordx2 v0, v[20:21], s[24:25] offset:3072
	v_fma_f32 v4, -s48, v22, v4
	v_fma_f32 v5, -s48, v23, v5
	v_fma_f32 v6, -s48, v24, v6
	v_fma_f32 v7, -s48, v25, v7
	v_readlane_b32 s46, v26, 34
	v_readlane_b32 s47, v27, 31
	v_readlane_b32 s48, v26, 31
	s_waitcnt vmcnt(52)
	v_lshlrev_b32_e32 v8, 16, v112
	v_and_b32_e32 v9, 0xffff0000, v112
	v_lshlrev_b32_e32 v10, 16, v113
	v_and_b32_e32 v11, 0xffff0000, v113
	v_lshlrev_b32_e32 v22, 16, v106
	v_and_b32_e32 v23, 0xffff0000, v106
	v_lshlrev_b32_e32 v24, 16, v107
	v_and_b32_e32 v25, 0xffff0000, v107
	v_mul_f32_e32 v12, s46, v8
	v_mul_f32_e32 v13, s46, v9
	v_mul_f32_e32 v14, s46, v10
	v_mul_f32_e32 v15, s46, v11
	v_fma_f32 v4, s46, v8, v4
	v_fma_f32 v5, s46, v9, v5
	v_fma_f32 v6, s46, v10, v6
	v_fma_f32 v7, s46, v11, v7
	v_fma_f32 v16, s47, v4, -v12
	v_fma_f32 v17, s47, v5, -v13
	v_fma_f32 v18, s47, v6, -v14
	v_fma_f32 v19, s47, v7, -v15
	v_cvt_pk_bf16_f32 v38, v16, v17
	v_cvt_pk_bf16_f32 v39, v18, v19
	global_store_dwordx2 v0, v[38:39], s[24:25] offset:3584
	v_fma_f32 v4, -s48, v22, v4
	v_fma_f32 v5, -s48, v23, v5
	v_fma_f32 v6, -s48, v24, v6
	v_fma_f32 v7, -s48, v25, v7
	v_mov_b32_e32 v4, 0
	v_mov_b32_e32 v5, 0
	v_mov_b32_e32 v6, 0
	v_mov_b32_e32 v7, 0
	v_readlane_b32 s46, v28, 0
	s_waitcnt vmcnt(52)
	v_lshlrev_b32_e32 v8, 16, v114
	v_and_b32_e32 v9, 0xffff0000, v114
	v_lshlrev_b32_e32 v10, 16, v115
	v_and_b32_e32 v11, 0xffff0000, v115
	v_fma_f32 v4, s46, v8, v4
	v_fma_f32 v5, s46, v9, v5
	v_fma_f32 v6, s46, v10, v6
	v_fma_f32 v7, s46, v11, v7
	v_readlane_b32 s46, v28, 1
	s_waitcnt vmcnt(52)
	v_lshlrev_b32_e32 v8, 16, v116
	v_and_b32_e32 v9, 0xffff0000, v116
	v_lshlrev_b32_e32 v10, 16, v117
	v_and_b32_e32 v11, 0xffff0000, v117
	v_fma_f32 v4, s46, v8, v4
	v_fma_f32 v5, s46, v9, v5
	v_fma_f32 v6, s46, v10, v6
	v_fma_f32 v7, s46, v11, v7
	v_readlane_b32 s46, v28, 2
	s_waitcnt vmcnt(52)
	v_lshlrev_b32_e32 v8, 16, v118
	v_and_b32_e32 v9, 0xffff0000, v118
	v_lshlrev_b32_e32 v10, 16, v119
	v_and_b32_e32 v11, 0xffff0000, v119
	v_fma_f32 v4, s46, v8, v4
	v_fma_f32 v5, s46, v9, v5
	v_fma_f32 v6, s46, v10, v6
	v_fma_f32 v7, s46, v11, v7
	v_readlane_b32 s46, v28, 3
	s_waitcnt vmcnt(52)
	v_lshlrev_b32_e32 v8, 16, v120
	v_and_b32_e32 v9, 0xffff0000, v120
	v_lshlrev_b32_e32 v10, 16, v121
	v_and_b32_e32 v11, 0xffff0000, v121
	v_fma_f32 v4, s46, v8, v4
	v_fma_f32 v5, s46, v9, v5
	v_fma_f32 v6, s46, v10, v6
	v_fma_f32 v7, s46, v11, v7
	v_readlane_b32 s46, v28, 4
	s_waitcnt vmcnt(52)
	v_lshlrev_b32_e32 v8, 16, v122
	v_and_b32_e32 v9, 0xffff0000, v122
	v_lshlrev_b32_e32 v10, 16, v123
	v_and_b32_e32 v11, 0xffff0000, v123
	v_fma_f32 v4, s46, v8, v4
	v_fma_f32 v5, s46, v9, v5
	v_fma_f32 v6, s46, v10, v6
	v_fma_f32 v7, s46, v11, v7
	v_readlane_b32 s46, v28, 5
	s_waitcnt vmcnt(52)
	v_lshlrev_b32_e32 v8, 16, v124
	v_and_b32_e32 v9, 0xffff0000, v124
	v_lshlrev_b32_e32 v10, 16, v125
	v_and_b32_e32 v11, 0xffff0000, v125
	v_fma_f32 v4, s46, v8, v4
	v_fma_f32 v5, s46, v9, v5
	v_fma_f32 v6, s46, v10, v6
	v_fma_f32 v7, s46, v11, v7
	v_readlane_b32 s46, v28, 6
	s_waitcnt vmcnt(52)
	v_lshlrev_b32_e32 v8, 16, v126
	v_and_b32_e32 v9, 0xffff0000, v126
	v_lshlrev_b32_e32 v10, 16, v127
	v_and_b32_e32 v11, 0xffff0000, v127
	v_fma_f32 v4, s46, v8, v4
	v_fma_f32 v5, s46, v9, v5
	v_fma_f32 v6, s46, v10, v6
	v_fma_f32 v7, s46, v11, v7
	v_readlane_b32 s46, v28, 7
	s_waitcnt vmcnt(52)
	v_lshlrev_b32_e32 v8, 16, v128
	v_and_b32_e32 v9, 0xffff0000, v128
	v_lshlrev_b32_e32 v10, 16, v129
	v_and_b32_e32 v11, 0xffff0000, v129
	v_fma_f32 v4, s46, v8, v4
	v_fma_f32 v5, s46, v9, v5
	v_fma_f32 v6, s46, v10, v6
	v_fma_f32 v7, s46, v11, v7
	v_readlane_b32 s46, v28, 8
	s_waitcnt vmcnt(52)
	v_lshlrev_b32_e32 v8, 16, v130
	v_and_b32_e32 v9, 0xffff0000, v130
	v_lshlrev_b32_e32 v10, 16, v131
	v_and_b32_e32 v11, 0xffff0000, v131
	v_fma_f32 v4, s46, v8, v4
	v_fma_f32 v5, s46, v9, v5
	v_fma_f32 v6, s46, v10, v6
	v_fma_f32 v7, s46, v11, v7
	v_readlane_b32 s46, v28, 9
	s_waitcnt vmcnt(52)
	v_lshlrev_b32_e32 v8, 16, v132
	v_and_b32_e32 v9, 0xffff0000, v132
	v_lshlrev_b32_e32 v10, 16, v133
	v_and_b32_e32 v11, 0xffff0000, v133
	v_fma_f32 v4, s46, v8, v4
	v_fma_f32 v5, s46, v9, v5
	v_fma_f32 v6, s46, v10, v6
	v_fma_f32 v7, s46, v11, v7
	v_readlane_b32 s46, v28, 10
	s_waitcnt vmcnt(52)
	v_lshlrev_b32_e32 v8, 16, v134
	v_and_b32_e32 v9, 0xffff0000, v134
	v_lshlrev_b32_e32 v10, 16, v135
	v_and_b32_e32 v11, 0xffff0000, v135
	v_fma_f32 v4, s46, v8, v4
	v_fma_f32 v5, s46, v9, v5
	v_fma_f32 v6, s46, v10, v6
	v_fma_f32 v7, s46, v11, v7
	v_readlane_b32 s46, v28, 11
	s_waitcnt vmcnt(52)
	v_lshlrev_b32_e32 v8, 16, v136
	v_and_b32_e32 v9, 0xffff0000, v136
	v_lshlrev_b32_e32 v10, 16, v137
	v_and_b32_e32 v11, 0xffff0000, v137
	v_fma_f32 v4, s46, v8, v4
	v_fma_f32 v5, s46, v9, v5
	v_fma_f32 v6, s46, v10, v6
	v_fma_f32 v7, s46, v11, v7
	v_readlane_b32 s46, v28, 12
	s_waitcnt vmcnt(52)
	v_lshlrev_b32_e32 v8, 16, v138
	v_and_b32_e32 v9, 0xffff0000, v138
	v_lshlrev_b32_e32 v10, 16, v139
	v_and_b32_e32 v11, 0xffff0000, v139
	v_fma_f32 v4, s46, v8, v4
	v_fma_f32 v5, s46, v9, v5
	v_fma_f32 v6, s46, v10, v6
	v_fma_f32 v7, s46, v11, v7
	v_readlane_b32 s46, v28, 13
	s_waitcnt vmcnt(52)
	v_lshlrev_b32_e32 v8, 16, v140
	v_and_b32_e32 v9, 0xffff0000, v140
	v_lshlrev_b32_e32 v10, 16, v141
	v_and_b32_e32 v11, 0xffff0000, v141
	v_fma_f32 v4, s46, v8, v4
	v_fma_f32 v5, s46, v9, v5
	v_fma_f32 v6, s46, v10, v6
	v_fma_f32 v7, s46, v11, v7
	v_readlane_b32 s46, v28, 14
	s_waitcnt vmcnt(52)
	v_lshlrev_b32_e32 v8, 16, v142
	v_and_b32_e32 v9, 0xffff0000, v142
	v_lshlrev_b32_e32 v10, 16, v143
	v_and_b32_e32 v11, 0xffff0000, v143
	v_fma_f32 v4, s46, v8, v4
	v_fma_f32 v5, s46, v9, v5
	v_fma_f32 v6, s46, v10, v6
	v_fma_f32 v7, s46, v11, v7
	v_readlane_b32 s46, v28, 15
	v_readlane_b32 s47, v29, 0
	v_readlane_b32 s48, v28, 0
	s_waitcnt vmcnt(52)
	v_lshlrev_b32_e32 v8, 16, v144
	v_and_b32_e32 v9, 0xffff0000, v144
	v_lshlrev_b32_e32 v10, 16, v145
	v_and_b32_e32 v11, 0xffff0000, v145
	v_lshlrev_b32_e32 v22, 16, v114
	v_and_b32_e32 v23, 0xffff0000, v114
	v_lshlrev_b32_e32 v24, 16, v115
	v_and_b32_e32 v25, 0xffff0000, v115
	v_mul_f32_e32 v12, s46, v8
	v_mul_f32_e32 v13, s46, v9
	v_mul_f32_e32 v14, s46, v10
	v_mul_f32_e32 v15, s46, v11
	v_fma_f32 v4, s46, v8, v4
	v_fma_f32 v5, s46, v9, v5
	v_fma_f32 v6, s46, v10, v6
	v_fma_f32 v7, s46, v11, v7
	v_fma_f32 v16, s47, v4, -v12
	v_fma_f32 v17, s47, v5, -v13
	v_fma_f32 v18, s47, v6, -v14
	v_fma_f32 v19, s47, v7, -v15
	v_cvt_pk_bf16_f32 v20, v16, v17
	v_cvt_pk_bf16_f32 v21, v18, v19
	global_store_dwordx2 v0, v[20:21], s[40:41]
	v_fma_f32 v4, -s48, v22, v4
	v_fma_f32 v5, -s48, v23, v5
	v_fma_f32 v6, -s48, v24, v6
	v_fma_f32 v7, -s48, v25, v7
	v_readlane_b32 s46, v28, 16
	v_readlane_b32 s47, v29, 1
	v_readlane_b32 s48, v28, 1
	s_waitcnt vmcnt(52)
	v_lshlrev_b32_e32 v8, 16, v146
	v_and_b32_e32 v9, 0xffff0000, v146
	v_lshlrev_b32_e32 v10, 16, v147
	v_and_b32_e32 v11, 0xffff0000, v147
	v_lshlrev_b32_e32 v22, 16, v116
	v_and_b32_e32 v23, 0xffff0000, v116
	v_lshlrev_b32_e32 v24, 16, v117
	v_and_b32_e32 v25, 0xffff0000, v117
	v_mul_f32_e32 v12, s46, v8
	v_mul_f32_e32 v13, s46, v9
	v_mul_f32_e32 v14, s46, v10
	v_mul_f32_e32 v15, s46, v11
	v_fma_f32 v4, s46, v8, v4
	v_fma_f32 v5, s46, v9, v5
	v_fma_f32 v6, s46, v10, v6
	v_fma_f32 v7, s46, v11, v7
	v_fma_f32 v16, s47, v4, -v12
	v_fma_f32 v17, s47, v5, -v13
	v_fma_f32 v18, s47, v6, -v14
	v_fma_f32 v19, s47, v7, -v15
	v_cvt_pk_bf16_f32 v38, v16, v17
	v_cvt_pk_bf16_f32 v39, v18, v19
	global_store_dwordx2 v0, v[38:39], s[40:41] offset:512
	v_fma_f32 v4, -s48, v22, v4
	v_fma_f32 v5, -s48, v23, v5
	v_fma_f32 v6, -s48, v24, v6
	v_fma_f32 v7, -s48, v25, v7
	v_readlane_b32 s46, v28, 17
	v_readlane_b32 s47, v29, 2
	v_readlane_b32 s48, v28, 2
	s_waitcnt vmcnt(52)
	v_lshlrev_b32_e32 v8, 16, v148
	v_and_b32_e32 v9, 0xffff0000, v148
	v_lshlrev_b32_e32 v10, 16, v149
	v_and_b32_e32 v11, 0xffff0000, v149
	v_lshlrev_b32_e32 v22, 16, v118
	v_and_b32_e32 v23, 0xffff0000, v118
	v_lshlrev_b32_e32 v24, 16, v119
	v_and_b32_e32 v25, 0xffff0000, v119
	v_mul_f32_e32 v12, s46, v8
	v_mul_f32_e32 v13, s46, v9
	v_mul_f32_e32 v14, s46, v10
	v_mul_f32_e32 v15, s46, v11
	v_fma_f32 v4, s46, v8, v4
	v_fma_f32 v5, s46, v9, v5
	v_fma_f32 v6, s46, v10, v6
	v_fma_f32 v7, s46, v11, v7
	v_fma_f32 v16, s47, v4, -v12
	v_fma_f32 v17, s47, v5, -v13
	v_fma_f32 v18, s47, v6, -v14
	v_fma_f32 v19, s47, v7, -v15
	v_cvt_pk_bf16_f32 v20, v16, v17
	v_cvt_pk_bf16_f32 v21, v18, v19
	global_store_dwordx2 v0, v[20:21], s[40:41] offset:1024
	v_fma_f32 v4, -s48, v22, v4
	v_fma_f32 v5, -s48, v23, v5
	v_fma_f32 v6, -s48, v24, v6
	v_fma_f32 v7, -s48, v25, v7
	v_readlane_b32 s46, v28, 18
	v_readlane_b32 s47, v29, 3
	v_readlane_b32 s48, v28, 3
	s_waitcnt vmcnt(52)
	v_lshlrev_b32_e32 v8, 16, v150
	v_and_b32_e32 v9, 0xffff0000, v150
	v_lshlrev_b32_e32 v10, 16, v151
	v_and_b32_e32 v11, 0xffff0000, v151
	v_lshlrev_b32_e32 v22, 16, v120
	v_and_b32_e32 v23, 0xffff0000, v120
	v_lshlrev_b32_e32 v24, 16, v121
	v_and_b32_e32 v25, 0xffff0000, v121
	v_mul_f32_e32 v12, s46, v8
	v_mul_f32_e32 v13, s46, v9
	v_mul_f32_e32 v14, s46, v10
	v_mul_f32_e32 v15, s46, v11
	v_fma_f32 v4, s46, v8, v4
	v_fma_f32 v5, s46, v9, v5
	v_fma_f32 v6, s46, v10, v6
	v_fma_f32 v7, s46, v11, v7
	v_fma_f32 v16, s47, v4, -v12
	v_fma_f32 v17, s47, v5, -v13
	v_fma_f32 v18, s47, v6, -v14
	v_fma_f32 v19, s47, v7, -v15
	v_cvt_pk_bf16_f32 v38, v16, v17
	v_cvt_pk_bf16_f32 v39, v18, v19
	global_store_dwordx2 v0, v[38:39], s[40:41] offset:1536
	v_fma_f32 v4, -s48, v22, v4
	v_fma_f32 v5, -s48, v23, v5
	v_fma_f32 v6, -s48, v24, v6
	v_fma_f32 v7, -s48, v25, v7
	v_readlane_b32 s46, v28, 19
	v_readlane_b32 s47, v29, 4
	v_readlane_b32 s48, v28, 4
	s_waitcnt vmcnt(52)
	v_lshlrev_b32_e32 v8, 16, v152
	v_and_b32_e32 v9, 0xffff0000, v152
	v_lshlrev_b32_e32 v10, 16, v153
	v_and_b32_e32 v11, 0xffff0000, v153
	v_lshlrev_b32_e32 v22, 16, v122
	v_and_b32_e32 v23, 0xffff0000, v122
	v_lshlrev_b32_e32 v24, 16, v123
	v_and_b32_e32 v25, 0xffff0000, v123
	v_mul_f32_e32 v12, s46, v8
	v_mul_f32_e32 v13, s46, v9
	v_mul_f32_e32 v14, s46, v10
	v_mul_f32_e32 v15, s46, v11
	v_fma_f32 v4, s46, v8, v4
	v_fma_f32 v5, s46, v9, v5
	v_fma_f32 v6, s46, v10, v6
	v_fma_f32 v7, s46, v11, v7
	v_fma_f32 v16, s47, v4, -v12
	v_fma_f32 v17, s47, v5, -v13
	v_fma_f32 v18, s47, v6, -v14
	v_fma_f32 v19, s47, v7, -v15
	v_cvt_pk_bf16_f32 v20, v16, v17
	v_cvt_pk_bf16_f32 v21, v18, v19
	global_store_dwordx2 v0, v[20:21], s[40:41] offset:2048
	v_fma_f32 v4, -s48, v22, v4
	v_fma_f32 v5, -s48, v23, v5
	v_fma_f32 v6, -s48, v24, v6
	v_fma_f32 v7, -s48, v25, v7
	v_readlane_b32 s46, v28, 20
	v_readlane_b32 s47, v29, 5
	v_readlane_b32 s48, v28, 5
	s_waitcnt vmcnt(52)
	v_lshlrev_b32_e32 v8, 16, v154
	v_and_b32_e32 v9, 0xffff0000, v154
	v_lshlrev_b32_e32 v10, 16, v155
	v_and_b32_e32 v11, 0xffff0000, v155
	v_lshlrev_b32_e32 v22, 16, v124
	v_and_b32_e32 v23, 0xffff0000, v124
	v_lshlrev_b32_e32 v24, 16, v125
	v_and_b32_e32 v25, 0xffff0000, v125
	v_mul_f32_e32 v12, s46, v8
	v_mul_f32_e32 v13, s46, v9
	v_mul_f32_e32 v14, s46, v10
	v_mul_f32_e32 v15, s46, v11
	v_fma_f32 v4, s46, v8, v4
	v_fma_f32 v5, s46, v9, v5
	v_fma_f32 v6, s46, v10, v6
	v_fma_f32 v7, s46, v11, v7
	v_fma_f32 v16, s47, v4, -v12
	v_fma_f32 v17, s47, v5, -v13
	v_fma_f32 v18, s47, v6, -v14
	v_fma_f32 v19, s47, v7, -v15
	v_cvt_pk_bf16_f32 v38, v16, v17
	v_cvt_pk_bf16_f32 v39, v18, v19
	global_store_dwordx2 v0, v[38:39], s[40:41] offset:2560
	v_fma_f32 v4, -s48, v22, v4
	v_fma_f32 v5, -s48, v23, v5
	v_fma_f32 v6, -s48, v24, v6
	v_fma_f32 v7, -s48, v25, v7
	v_readlane_b32 s46, v28, 21
	v_readlane_b32 s47, v29, 6
	v_readlane_b32 s48, v28, 6
	s_waitcnt vmcnt(52)
	v_lshlrev_b32_e32 v8, 16, v156
	v_and_b32_e32 v9, 0xffff0000, v156
	v_lshlrev_b32_e32 v10, 16, v157
	v_and_b32_e32 v11, 0xffff0000, v157
	v_lshlrev_b32_e32 v22, 16, v126
	v_and_b32_e32 v23, 0xffff0000, v126
	v_lshlrev_b32_e32 v24, 16, v127
	v_and_b32_e32 v25, 0xffff0000, v127
	v_mul_f32_e32 v12, s46, v8
	v_mul_f32_e32 v13, s46, v9
	v_mul_f32_e32 v14, s46, v10
	v_mul_f32_e32 v15, s46, v11
	v_fma_f32 v4, s46, v8, v4
	v_fma_f32 v5, s46, v9, v5
	v_fma_f32 v6, s46, v10, v6
	v_fma_f32 v7, s46, v11, v7
	v_fma_f32 v16, s47, v4, -v12
	v_fma_f32 v17, s47, v5, -v13
	v_fma_f32 v18, s47, v6, -v14
	v_fma_f32 v19, s47, v7, -v15
	v_cvt_pk_bf16_f32 v20, v16, v17
	v_cvt_pk_bf16_f32 v21, v18, v19
	global_store_dwordx2 v0, v[20:21], s[40:41] offset:3072
	v_fma_f32 v4, -s48, v22, v4
	v_fma_f32 v5, -s48, v23, v5
	v_fma_f32 v6, -s48, v24, v6
	v_fma_f32 v7, -s48, v25, v7
	v_readlane_b32 s46, v28, 22
	v_readlane_b32 s47, v29, 7
	v_readlane_b32 s48, v28, 7
	s_waitcnt vmcnt(52)
	v_lshlrev_b32_e32 v8, 16, v158
	v_and_b32_e32 v9, 0xffff0000, v158
	v_lshlrev_b32_e32 v10, 16, v159
	v_and_b32_e32 v11, 0xffff0000, v159
	v_lshlrev_b32_e32 v22, 16, v128
	v_and_b32_e32 v23, 0xffff0000, v128
	v_lshlrev_b32_e32 v24, 16, v129
	v_and_b32_e32 v25, 0xffff0000, v129
	v_mul_f32_e32 v12, s46, v8
	v_mul_f32_e32 v13, s46, v9
	v_mul_f32_e32 v14, s46, v10
	v_mul_f32_e32 v15, s46, v11
	v_fma_f32 v4, s46, v8, v4
	v_fma_f32 v5, s46, v9, v5
	v_fma_f32 v6, s46, v10, v6
	v_fma_f32 v7, s46, v11, v7
	v_fma_f32 v16, s47, v4, -v12
	v_fma_f32 v17, s47, v5, -v13
	v_fma_f32 v18, s47, v6, -v14
	v_fma_f32 v19, s47, v7, -v15
	v_cvt_pk_bf16_f32 v38, v16, v17
	v_cvt_pk_bf16_f32 v39, v18, v19
	global_store_dwordx2 v0, v[38:39], s[40:41] offset:3584
	v_fma_f32 v4, -s48, v22, v4
	v_fma_f32 v5, -s48, v23, v5
	v_fma_f32 v6, -s48, v24, v6
	v_fma_f32 v7, -s48, v25, v7
	v_readlane_b32 s46, v28, 23
	v_readlane_b32 s47, v29, 8
	v_readlane_b32 s48, v28, 8
	s_waitcnt vmcnt(52)
	v_lshlrev_b32_e32 v8, 16, v160
	v_and_b32_e32 v9, 0xffff0000, v160
	v_lshlrev_b32_e32 v10, 16, v161
	v_and_b32_e32 v11, 0xffff0000, v161
	v_lshlrev_b32_e32 v22, 16, v130
	v_and_b32_e32 v23, 0xffff0000, v130
	v_lshlrev_b32_e32 v24, 16, v131
	v_and_b32_e32 v25, 0xffff0000, v131
	v_mul_f32_e32 v12, s46, v8
	v_mul_f32_e32 v13, s46, v9
	v_mul_f32_e32 v14, s46, v10
	v_mul_f32_e32 v15, s46, v11
	v_fma_f32 v4, s46, v8, v4
	v_fma_f32 v5, s46, v9, v5
	v_fma_f32 v6, s46, v10, v6
	v_fma_f32 v7, s46, v11, v7
	v_fma_f32 v16, s47, v4, -v12
	v_fma_f32 v17, s47, v5, -v13
	v_fma_f32 v18, s47, v6, -v14
	v_fma_f32 v19, s47, v7, -v15
	v_cvt_pk_bf16_f32 v20, v16, v17
	v_cvt_pk_bf16_f32 v21, v18, v19
	s_add_u32 s40, s40, 0x1000
	s_addc_u32 s41, s41, 0
	global_store_dwordx2 v0, v[20:21], s[40:41]
	v_fma_f32 v4, -s48, v22, v4
	v_fma_f32 v5, -s48, v23, v5
	v_fma_f32 v6, -s48, v24, v6
	v_fma_f32 v7, -s48, v25, v7
	v_readlane_b32 s46, v28, 24
	v_readlane_b32 s47, v29, 9
	v_readlane_b32 s48, v28, 9
	s_waitcnt vmcnt(52)
	v_lshlrev_b32_e32 v8, 16, v162
	v_and_b32_e32 v9, 0xffff0000, v162
	v_lshlrev_b32_e32 v10, 16, v163
	v_and_b32_e32 v11, 0xffff0000, v163
	v_lshlrev_b32_e32 v22, 16, v132
	v_and_b32_e32 v23, 0xffff0000, v132
	v_lshlrev_b32_e32 v24, 16, v133
	v_and_b32_e32 v25, 0xffff0000, v133
	v_mul_f32_e32 v12, s46, v8
	v_mul_f32_e32 v13, s46, v9
	v_mul_f32_e32 v14, s46, v10
	v_mul_f32_e32 v15, s46, v11
	v_fma_f32 v4, s46, v8, v4
	v_fma_f32 v5, s46, v9, v5
	v_fma_f32 v6, s46, v10, v6
	v_fma_f32 v7, s46, v11, v7
	v_fma_f32 v16, s47, v4, -v12
	v_fma_f32 v17, s47, v5, -v13
	v_fma_f32 v18, s47, v6, -v14
	v_fma_f32 v19, s47, v7, -v15
	v_cvt_pk_bf16_f32 v38, v16, v17
	v_cvt_pk_bf16_f32 v39, v18, v19
	global_store_dwordx2 v0, v[38:39], s[40:41] offset:512
	v_fma_f32 v4, -s48, v22, v4
	v_fma_f32 v5, -s48, v23, v5
	v_fma_f32 v6, -s48, v24, v6
	v_fma_f32 v7, -s48, v25, v7
	v_readlane_b32 s46, v28, 25
	v_readlane_b32 s47, v29, 10
	v_readlane_b32 s48, v28, 10
	s_waitcnt vmcnt(52)
	v_lshlrev_b32_e32 v8, 16, v164
	v_and_b32_e32 v9, 0xffff0000, v164
	v_lshlrev_b32_e32 v10, 16, v165
	v_and_b32_e32 v11, 0xffff0000, v165
	v_lshlrev_b32_e32 v22, 16, v134
	v_and_b32_e32 v23, 0xffff0000, v134
	v_lshlrev_b32_e32 v24, 16, v135
	v_and_b32_e32 v25, 0xffff0000, v135
	v_mul_f32_e32 v12, s46, v8
	v_mul_f32_e32 v13, s46, v9
	v_mul_f32_e32 v14, s46, v10
	v_mul_f32_e32 v15, s46, v11
	v_fma_f32 v4, s46, v8, v4
	v_fma_f32 v5, s46, v9, v5
	v_fma_f32 v6, s46, v10, v6
	v_fma_f32 v7, s46, v11, v7
	v_fma_f32 v16, s47, v4, -v12
	v_fma_f32 v17, s47, v5, -v13
	v_fma_f32 v18, s47, v6, -v14
	v_fma_f32 v19, s47, v7, -v15
	v_cvt_pk_bf16_f32 v20, v16, v17
	v_cvt_pk_bf16_f32 v21, v18, v19
	global_store_dwordx2 v0, v[20:21], s[40:41] offset:1024
	v_fma_f32 v4, -s48, v22, v4
	v_fma_f32 v5, -s48, v23, v5
	v_fma_f32 v6, -s48, v24, v6
	v_fma_f32 v7, -s48, v25, v7
	v_readlane_b32 s46, v28, 26
	v_readlane_b32 s47, v29, 11
	v_readlane_b32 s48, v28, 11
	s_waitcnt vmcnt(52)
	v_lshlrev_b32_e32 v8, 16, v166
	v_and_b32_e32 v9, 0xffff0000, v166
	v_lshlrev_b32_e32 v10, 16, v167
	v_and_b32_e32 v11, 0xffff0000, v167
	v_lshlrev_b32_e32 v22, 16, v136
	v_and_b32_e32 v23, 0xffff0000, v136
	v_lshlrev_b32_e32 v24, 16, v137
	v_and_b32_e32 v25, 0xffff0000, v137
	v_mul_f32_e32 v12, s46, v8
	v_mul_f32_e32 v13, s46, v9
	v_mul_f32_e32 v14, s46, v10
	v_mul_f32_e32 v15, s46, v11
	v_fma_f32 v4, s46, v8, v4
	v_fma_f32 v5, s46, v9, v5
	v_fma_f32 v6, s46, v10, v6
	v_fma_f32 v7, s46, v11, v7
	v_fma_f32 v16, s47, v4, -v12
	v_fma_f32 v17, s47, v5, -v13
	v_fma_f32 v18, s47, v6, -v14
	v_fma_f32 v19, s47, v7, -v15
	v_cvt_pk_bf16_f32 v38, v16, v17
	v_cvt_pk_bf16_f32 v39, v18, v19
	global_store_dwordx2 v0, v[38:39], s[40:41] offset:1536
	v_fma_f32 v4, -s48, v22, v4
	v_fma_f32 v5, -s48, v23, v5
	v_fma_f32 v6, -s48, v24, v6
	v_fma_f32 v7, -s48, v25, v7
	v_readlane_b32 s46, v28, 27
	v_readlane_b32 s47, v29, 12
	v_readlane_b32 s48, v28, 12
	s_waitcnt vmcnt(52)
	v_lshlrev_b32_e32 v8, 16, v168
	v_and_b32_e32 v9, 0xffff0000, v168
	v_lshlrev_b32_e32 v10, 16, v169
	v_and_b32_e32 v11, 0xffff0000, v169
	v_lshlrev_b32_e32 v22, 16, v138
	v_and_b32_e32 v23, 0xffff0000, v138
	v_lshlrev_b32_e32 v24, 16, v139
	v_and_b32_e32 v25, 0xffff0000, v139
	v_mul_f32_e32 v12, s46, v8
	v_mul_f32_e32 v13, s46, v9
	v_mul_f32_e32 v14, s46, v10
	v_mul_f32_e32 v15, s46, v11
	v_fma_f32 v4, s46, v8, v4
	v_fma_f32 v5, s46, v9, v5
	v_fma_f32 v6, s46, v10, v6
	v_fma_f32 v7, s46, v11, v7
	v_fma_f32 v16, s47, v4, -v12
	v_fma_f32 v17, s47, v5, -v13
	v_fma_f32 v18, s47, v6, -v14
	v_fma_f32 v19, s47, v7, -v15
	v_cvt_pk_bf16_f32 v20, v16, v17
	v_cvt_pk_bf16_f32 v21, v18, v19
	global_store_dwordx2 v0, v[20:21], s[40:41] offset:2048
	v_fma_f32 v4, -s48, v22, v4
	v_fma_f32 v5, -s48, v23, v5
	v_fma_f32 v6, -s48, v24, v6
	v_fma_f32 v7, -s48, v25, v7
	v_readlane_b32 s46, v28, 28
	v_readlane_b32 s47, v29, 13
	v_readlane_b32 s48, v28, 13
	s_waitcnt vmcnt(52)
	v_lshlrev_b32_e32 v8, 16, v170
	v_and_b32_e32 v9, 0xffff0000, v170
	v_lshlrev_b32_e32 v10, 16, v171
	v_and_b32_e32 v11, 0xffff0000, v171
	v_lshlrev_b32_e32 v22, 16, v140
	v_and_b32_e32 v23, 0xffff0000, v140
	v_lshlrev_b32_e32 v24, 16, v141
	v_and_b32_e32 v25, 0xffff0000, v141
	v_mul_f32_e32 v12, s46, v8
	v_mul_f32_e32 v13, s46, v9
	v_mul_f32_e32 v14, s46, v10
	v_mul_f32_e32 v15, s46, v11
	v_fma_f32 v4, s46, v8, v4
	v_fma_f32 v5, s46, v9, v5
	v_fma_f32 v6, s46, v10, v6
	v_fma_f32 v7, s46, v11, v7
	v_fma_f32 v16, s47, v4, -v12
	v_fma_f32 v17, s47, v5, -v13
	v_fma_f32 v18, s47, v6, -v14
	v_fma_f32 v19, s47, v7, -v15
	v_cvt_pk_bf16_f32 v38, v16, v17
	v_cvt_pk_bf16_f32 v39, v18, v19
	global_store_dwordx2 v0, v[38:39], s[40:41] offset:2560
	v_fma_f32 v4, -s48, v22, v4
	v_fma_f32 v5, -s48, v23, v5
	v_fma_f32 v6, -s48, v24, v6
	v_fma_f32 v7, -s48, v25, v7
	v_readlane_b32 s46, v28, 29
	v_readlane_b32 s47, v29, 14
	v_readlane_b32 s48, v28, 14
	s_waitcnt vmcnt(52)
	v_lshlrev_b32_e32 v8, 16, v172
	v_and_b32_e32 v9, 0xffff0000, v172
	v_lshlrev_b32_e32 v10, 16, v173
	v_and_b32_e32 v11, 0xffff0000, v173
	v_lshlrev_b32_e32 v22, 16, v142
	v_and_b32_e32 v23, 0xffff0000, v142
	v_lshlrev_b32_e32 v24, 16, v143
	v_and_b32_e32 v25, 0xffff0000, v143
	v_mul_f32_e32 v12, s46, v8
	v_mul_f32_e32 v13, s46, v9
	v_mul_f32_e32 v14, s46, v10
	v_mul_f32_e32 v15, s46, v11
	v_fma_f32 v4, s46, v8, v4
	v_fma_f32 v5, s46, v9, v5
	v_fma_f32 v6, s46, v10, v6
	v_fma_f32 v7, s46, v11, v7
	v_fma_f32 v16, s47, v4, -v12
	v_fma_f32 v17, s47, v5, -v13
	v_fma_f32 v18, s47, v6, -v14
	v_fma_f32 v19, s47, v7, -v15
	v_cvt_pk_bf16_f32 v20, v16, v17
	v_cvt_pk_bf16_f32 v21, v18, v19
	global_store_dwordx2 v0, v[20:21], s[40:41] offset:3072
	v_fma_f32 v4, -s48, v22, v4
	v_fma_f32 v5, -s48, v23, v5
	v_fma_f32 v6, -s48, v24, v6
	v_fma_f32 v7, -s48, v25, v7
	v_readlane_b32 s46, v28, 30
	v_readlane_b32 s47, v29, 15
	v_readlane_b32 s48, v28, 15
	s_waitcnt vmcnt(52)
	v_lshlrev_b32_e32 v8, 16, v174
	v_and_b32_e32 v9, 0xffff0000, v174
	v_lshlrev_b32_e32 v10, 16, v175
	v_and_b32_e32 v11, 0xffff0000, v175
	v_lshlrev_b32_e32 v22, 16, v144
	v_and_b32_e32 v23, 0xffff0000, v144
	v_lshlrev_b32_e32 v24, 16, v145
	v_and_b32_e32 v25, 0xffff0000, v145
	v_mul_f32_e32 v12, s46, v8
	v_mul_f32_e32 v13, s46, v9
	v_mul_f32_e32 v14, s46, v10
	v_mul_f32_e32 v15, s46, v11
	v_fma_f32 v4, s46, v8, v4
	v_fma_f32 v5, s46, v9, v5
	v_fma_f32 v6, s46, v10, v6
	v_fma_f32 v7, s46, v11, v7
	v_fma_f32 v16, s47, v4, -v12
	v_fma_f32 v17, s47, v5, -v13
	v_fma_f32 v18, s47, v6, -v14
	v_fma_f32 v19, s47, v7, -v15
	v_cvt_pk_bf16_f32 v38, v16, v17
	v_cvt_pk_bf16_f32 v39, v18, v19
	global_store_dwordx2 v0, v[38:39], s[40:41] offset:3584
	v_fma_f32 v4, -s48, v22, v4
	v_fma_f32 v5, -s48, v23, v5
	v_fma_f32 v6, -s48, v24, v6
	v_fma_f32 v7, -s48, v25, v7
	v_readlane_b32 s46, v28, 31
	v_readlane_b32 s47, v29, 16
	v_readlane_b32 s48, v28, 16
	s_waitcnt vmcnt(52)
	v_lshlrev_b32_e32 v8, 16, v176
	v_and_b32_e32 v9, 0xffff0000, v176
	v_lshlrev_b32_e32 v10, 16, v177
	v_and_b32_e32 v11, 0xffff0000, v177
	v_lshlrev_b32_e32 v22, 16, v146
	v_and_b32_e32 v23, 0xffff0000, v146
	v_lshlrev_b32_e32 v24, 16, v147
	v_and_b32_e32 v25, 0xffff0000, v147
	v_mul_f32_e32 v12, s46, v8
	v_mul_f32_e32 v13, s46, v9
	v_mul_f32_e32 v14, s46, v10
	v_mul_f32_e32 v15, s46, v11
	v_fma_f32 v4, s46, v8, v4
	v_fma_f32 v5, s46, v9, v5
	v_fma_f32 v6, s46, v10, v6
	v_fma_f32 v7, s46, v11, v7
	v_fma_f32 v16, s47, v4, -v12
	v_fma_f32 v17, s47, v5, -v13
	v_fma_f32 v18, s47, v6, -v14
	v_fma_f32 v19, s47, v7, -v15
	v_cvt_pk_bf16_f32 v20, v16, v17
	v_cvt_pk_bf16_f32 v21, v18, v19
	s_add_u32 s40, s40, 0x1000
	s_addc_u32 s41, s41, 0
	global_store_dwordx2 v0, v[20:21], s[40:41]
	v_fma_f32 v4, -s48, v22, v4
	v_fma_f32 v5, -s48, v23, v5
	v_fma_f32 v6, -s48, v24, v6
	v_fma_f32 v7, -s48, v25, v7
	v_readlane_b32 s46, v28, 32
	v_readlane_b32 s47, v29, 17
	v_readlane_b32 s48, v28, 17
	s_waitcnt vmcnt(52)
	v_lshlrev_b32_e32 v8, 16, v178
	v_and_b32_e32 v9, 0xffff0000, v178
	v_lshlrev_b32_e32 v10, 16, v179
	v_and_b32_e32 v11, 0xffff0000, v179
	v_lshlrev_b32_e32 v22, 16, v148
	v_and_b32_e32 v23, 0xffff0000, v148
	v_lshlrev_b32_e32 v24, 16, v149
	v_and_b32_e32 v25, 0xffff0000, v149
	v_mul_f32_e32 v12, s46, v8
	v_mul_f32_e32 v13, s46, v9
	v_mul_f32_e32 v14, s46, v10
	v_mul_f32_e32 v15, s46, v11
	v_fma_f32 v4, s46, v8, v4
	v_fma_f32 v5, s46, v9, v5
	v_fma_f32 v6, s46, v10, v6
	v_fma_f32 v7, s46, v11, v7
	v_fma_f32 v16, s47, v4, -v12
	v_fma_f32 v17, s47, v5, -v13
	v_fma_f32 v18, s47, v6, -v14
	v_fma_f32 v19, s47, v7, -v15
	v_cvt_pk_bf16_f32 v38, v16, v17
	v_cvt_pk_bf16_f32 v39, v18, v19
	global_store_dwordx2 v0, v[38:39], s[40:41] offset:512
	v_fma_f32 v4, -s48, v22, v4
	v_fma_f32 v5, -s48, v23, v5
	v_fma_f32 v6, -s48, v24, v6
	v_fma_f32 v7, -s48, v25, v7
	v_readlane_b32 s46, v28, 33
	v_readlane_b32 s47, v29, 18
	v_readlane_b32 s48, v28, 18
	s_waitcnt vmcnt(52)
	v_lshlrev_b32_e32 v8, 16, v180
	v_and_b32_e32 v9, 0xffff0000, v180
	v_lshlrev_b32_e32 v10, 16, v181
	v_and_b32_e32 v11, 0xffff0000, v181
	v_lshlrev_b32_e32 v22, 16, v150
	v_and_b32_e32 v23, 0xffff0000, v150
	v_lshlrev_b32_e32 v24, 16, v151
	v_and_b32_e32 v25, 0xffff0000, v151
	v_mul_f32_e32 v12, s46, v8
	v_mul_f32_e32 v13, s46, v9
	v_mul_f32_e32 v14, s46, v10
	v_mul_f32_e32 v15, s46, v11
	v_fma_f32 v4, s46, v8, v4
	v_fma_f32 v5, s46, v9, v5
	v_fma_f32 v6, s46, v10, v6
	v_fma_f32 v7, s46, v11, v7
	v_fma_f32 v16, s47, v4, -v12
	v_fma_f32 v17, s47, v5, -v13
	v_fma_f32 v18, s47, v6, -v14
	v_fma_f32 v19, s47, v7, -v15
	v_cvt_pk_bf16_f32 v20, v16, v17
	v_cvt_pk_bf16_f32 v21, v18, v19
	global_store_dwordx2 v0, v[20:21], s[40:41] offset:1024
	v_fma_f32 v4, -s48, v22, v4
	v_fma_f32 v5, -s48, v23, v5
	v_fma_f32 v6, -s48, v24, v6
	v_fma_f32 v7, -s48, v25, v7
	v_readlane_b32 s46, v28, 34
	v_readlane_b32 s47, v29, 19
	v_readlane_b32 s48, v28, 19
	s_waitcnt vmcnt(52)
	v_lshlrev_b32_e32 v8, 16, v182
	v_and_b32_e32 v9, 0xffff0000, v182
	v_lshlrev_b32_e32 v10, 16, v183
	v_and_b32_e32 v11, 0xffff0000, v183
	v_lshlrev_b32_e32 v22, 16, v152
	v_and_b32_e32 v23, 0xffff0000, v152
	v_lshlrev_b32_e32 v24, 16, v153
	v_and_b32_e32 v25, 0xffff0000, v153
	v_mul_f32_e32 v12, s46, v8
	v_mul_f32_e32 v13, s46, v9
	v_mul_f32_e32 v14, s46, v10
	v_mul_f32_e32 v15, s46, v11
	v_fma_f32 v4, s46, v8, v4
	v_fma_f32 v5, s46, v9, v5
	v_fma_f32 v6, s46, v10, v6
	v_fma_f32 v7, s46, v11, v7
	v_fma_f32 v16, s47, v4, -v12
	v_fma_f32 v17, s47, v5, -v13
	v_fma_f32 v18, s47, v6, -v14
	v_fma_f32 v19, s47, v7, -v15
	v_cvt_pk_bf16_f32 v38, v16, v17
	v_cvt_pk_bf16_f32 v39, v18, v19
	global_store_dwordx2 v0, v[38:39], s[40:41] offset:1536
	v_fma_f32 v4, -s48, v22, v4
	v_fma_f32 v5, -s48, v23, v5
	v_fma_f32 v6, -s48, v24, v6
	v_fma_f32 v7, -s48, v25, v7
	v_readlane_b32 s46, v28, 35
	v_readlane_b32 s47, v29, 20
	v_readlane_b32 s48, v28, 20
	s_waitcnt vmcnt(52)
	v_lshlrev_b32_e32 v8, 16, v184
	v_and_b32_e32 v9, 0xffff0000, v184
	v_lshlrev_b32_e32 v10, 16, v185
	v_and_b32_e32 v11, 0xffff0000, v185
	v_lshlrev_b32_e32 v22, 16, v154
	v_and_b32_e32 v23, 0xffff0000, v154
	v_lshlrev_b32_e32 v24, 16, v155
	v_and_b32_e32 v25, 0xffff0000, v155
	v_mul_f32_e32 v12, s46, v8
	v_mul_f32_e32 v13, s46, v9
	v_mul_f32_e32 v14, s46, v10
	v_mul_f32_e32 v15, s46, v11
	v_fma_f32 v4, s46, v8, v4
	v_fma_f32 v5, s46, v9, v5
	v_fma_f32 v6, s46, v10, v6
	v_fma_f32 v7, s46, v11, v7
	v_fma_f32 v16, s47, v4, -v12
	v_fma_f32 v17, s47, v5, -v13
	v_fma_f32 v18, s47, v6, -v14
	v_fma_f32 v19, s47, v7, -v15
	v_cvt_pk_bf16_f32 v20, v16, v17
	v_cvt_pk_bf16_f32 v21, v18, v19
	global_store_dwordx2 v0, v[20:21], s[40:41] offset:2048
	v_fma_f32 v4, -s48, v22, v4
	v_fma_f32 v5, -s48, v23, v5
	v_fma_f32 v6, -s48, v24, v6
	v_fma_f32 v7, -s48, v25, v7
	v_readlane_b32 s46, v28, 36
	v_readlane_b32 s47, v29, 21
	v_readlane_b32 s48, v28, 21
	s_waitcnt vmcnt(52)
	v_lshlrev_b32_e32 v8, 16, v186
	v_and_b32_e32 v9, 0xffff0000, v186
	v_lshlrev_b32_e32 v10, 16, v187
	v_and_b32_e32 v11, 0xffff0000, v187
	v_lshlrev_b32_e32 v22, 16, v156
	v_and_b32_e32 v23, 0xffff0000, v156
	v_lshlrev_b32_e32 v24, 16, v157
	v_and_b32_e32 v25, 0xffff0000, v157
	v_mul_f32_e32 v12, s46, v8
	v_mul_f32_e32 v13, s46, v9
	v_mul_f32_e32 v14, s46, v10
	v_mul_f32_e32 v15, s46, v11
	v_fma_f32 v4, s46, v8, v4
	v_fma_f32 v5, s46, v9, v5
	v_fma_f32 v6, s46, v10, v6
	v_fma_f32 v7, s46, v11, v7
	v_fma_f32 v16, s47, v4, -v12
	v_fma_f32 v17, s47, v5, -v13
	v_fma_f32 v18, s47, v6, -v14
	v_fma_f32 v19, s47, v7, -v15
	v_cvt_pk_bf16_f32 v38, v16, v17
	v_cvt_pk_bf16_f32 v39, v18, v19
	global_store_dwordx2 v0, v[38:39], s[40:41] offset:2560
	v_fma_f32 v4, -s48, v22, v4
	v_fma_f32 v5, -s48, v23, v5
	v_fma_f32 v6, -s48, v24, v6
	v_fma_f32 v7, -s48, v25, v7
	v_readlane_b32 s46, v28, 37
	v_readlane_b32 s47, v29, 22
	v_readlane_b32 s48, v28, 22
	s_waitcnt vmcnt(52)
	v_lshlrev_b32_e32 v8, 16, v188
	v_and_b32_e32 v9, 0xffff0000, v188
	v_lshlrev_b32_e32 v10, 16, v189
	v_and_b32_e32 v11, 0xffff0000, v189
	v_lshlrev_b32_e32 v22, 16, v158
	v_and_b32_e32 v23, 0xffff0000, v158
	v_lshlrev_b32_e32 v24, 16, v159
	v_and_b32_e32 v25, 0xffff0000, v159
	v_mul_f32_e32 v12, s46, v8
	v_mul_f32_e32 v13, s46, v9
	v_mul_f32_e32 v14, s46, v10
	v_mul_f32_e32 v15, s46, v11
	v_fma_f32 v4, s46, v8, v4
	v_fma_f32 v5, s46, v9, v5
	v_fma_f32 v6, s46, v10, v6
	v_fma_f32 v7, s46, v11, v7
	v_fma_f32 v16, s47, v4, -v12
	v_fma_f32 v17, s47, v5, -v13
	v_fma_f32 v18, s47, v6, -v14
	v_fma_f32 v19, s47, v7, -v15
	v_cvt_pk_bf16_f32 v20, v16, v17
	v_cvt_pk_bf16_f32 v21, v18, v19
	global_store_dwordx2 v0, v[20:21], s[40:41] offset:3072
	v_fma_f32 v4, -s48, v22, v4
	v_fma_f32 v5, -s48, v23, v5
	v_fma_f32 v6, -s48, v24, v6
	v_fma_f32 v7, -s48, v25, v7
	v_readlane_b32 s46, v28, 38
	v_readlane_b32 s47, v29, 23
	v_readlane_b32 s48, v28, 23
	s_waitcnt vmcnt(51)
	v_lshlrev_b32_e32 v8, 16, v190
	v_and_b32_e32 v9, 0xffff0000, v190
	v_lshlrev_b32_e32 v10, 16, v191
	v_and_b32_e32 v11, 0xffff0000, v191
	v_lshlrev_b32_e32 v22, 16, v160
	v_and_b32_e32 v23, 0xffff0000, v160
	v_lshlrev_b32_e32 v24, 16, v161
	v_and_b32_e32 v25, 0xffff0000, v161
	v_mul_f32_e32 v12, s46, v8
	v_mul_f32_e32 v13, s46, v9
	v_mul_f32_e32 v14, s46, v10
	v_mul_f32_e32 v15, s46, v11
	v_fma_f32 v4, s46, v8, v4
	v_fma_f32 v5, s46, v9, v5
	v_fma_f32 v6, s46, v10, v6
	v_fma_f32 v7, s46, v11, v7
	v_fma_f32 v16, s47, v4, -v12
	v_fma_f32 v17, s47, v5, -v13
	v_fma_f32 v18, s47, v6, -v14
	v_fma_f32 v19, s47, v7, -v15
	v_cvt_pk_bf16_f32 v38, v16, v17
	v_cvt_pk_bf16_f32 v39, v18, v19
	global_store_dwordx2 v0, v[38:39], s[40:41] offset:3584
	v_fma_f32 v4, -s48, v22, v4
	v_fma_f32 v5, -s48, v23, v5
	v_fma_f32 v6, -s48, v24, v6
	v_fma_f32 v7, -s48, v25, v7
	v_readlane_b32 s46, v28, 39
	v_readlane_b32 s47, v29, 24
	v_readlane_b32 s48, v28, 24
	s_waitcnt vmcnt(51)
	v_lshlrev_b32_e32 v8, 16, v194
	v_and_b32_e32 v9, 0xffff0000, v194
	v_lshlrev_b32_e32 v10, 16, v195
	v_and_b32_e32 v11, 0xffff0000, v195
	v_lshlrev_b32_e32 v22, 16, v162
	v_and_b32_e32 v23, 0xffff0000, v162
	v_lshlrev_b32_e32 v24, 16, v163
	v_and_b32_e32 v25, 0xffff0000, v163
	v_mul_f32_e32 v12, s46, v8
	v_mul_f32_e32 v13, s46, v9
	v_mul_f32_e32 v14, s46, v10
	v_mul_f32_e32 v15, s46, v11
	v_fma_f32 v4, s46, v8, v4
	v_fma_f32 v5, s46, v9, v5
	v_fma_f32 v6, s46, v10, v6
	v_fma_f32 v7, s46, v11, v7
	v_fma_f32 v16, s47, v4, -v12
	v_fma_f32 v17, s47, v5, -v13
	v_fma_f32 v18, s47, v6, -v14
	v_fma_f32 v19, s47, v7, -v15
	v_cvt_pk_bf16_f32 v20, v16, v17
	v_cvt_pk_bf16_f32 v21, v18, v19
	s_add_u32 s40, s40, 0x1000
	s_addc_u32 s41, s41, 0
	global_store_dwordx2 v0, v[20:21], s[40:41]
	v_fma_f32 v4, -s48, v22, v4
	v_fma_f32 v5, -s48, v23, v5
	v_fma_f32 v6, -s48, v24, v6
	v_fma_f32 v7, -s48, v25, v7
	v_readlane_b32 s46, v28, 40
	v_readlane_b32 s47, v29, 25
	v_readlane_b32 s48, v28, 25
	s_waitcnt vmcnt(50)
	v_lshlrev_b32_e32 v8, 16, v196
	v_and_b32_e32 v9, 0xffff0000, v196
	v_lshlrev_b32_e32 v10, 16, v197
	v_and_b32_e32 v11, 0xffff0000, v197
	v_lshlrev_b32_e32 v22, 16, v164
	v_and_b32_e32 v23, 0xffff0000, v164
	v_lshlrev_b32_e32 v24, 16, v165
	v_and_b32_e32 v25, 0xffff0000, v165
	v_mul_f32_e32 v12, s46, v8
	v_mul_f32_e32 v13, s46, v9
	v_mul_f32_e32 v14, s46, v10
	v_mul_f32_e32 v15, s46, v11
	v_fma_f32 v4, s46, v8, v4
	v_fma_f32 v5, s46, v9, v5
	v_fma_f32 v6, s46, v10, v6
	v_fma_f32 v7, s46, v11, v7
	v_fma_f32 v16, s47, v4, -v12
	v_fma_f32 v17, s47, v5, -v13
	v_fma_f32 v18, s47, v6, -v14
	v_fma_f32 v19, s47, v7, -v15
	v_cvt_pk_bf16_f32 v38, v16, v17
	v_cvt_pk_bf16_f32 v39, v18, v19
	global_store_dwordx2 v0, v[38:39], s[40:41] offset:512
	v_fma_f32 v4, -s48, v22, v4
	v_fma_f32 v5, -s48, v23, v5
	v_fma_f32 v6, -s48, v24, v6
	v_fma_f32 v7, -s48, v25, v7
	v_readlane_b32 s46, v28, 41
	v_readlane_b32 s47, v29, 26
	v_readlane_b32 s48, v28, 26
	s_waitcnt vmcnt(50)
	v_lshlrev_b32_e32 v8, 16, v198
	v_and_b32_e32 v9, 0xffff0000, v198
	v_lshlrev_b32_e32 v10, 16, v199
	v_and_b32_e32 v11, 0xffff0000, v199
	v_lshlrev_b32_e32 v22, 16, v166
	v_and_b32_e32 v23, 0xffff0000, v166
	v_lshlrev_b32_e32 v24, 16, v167
	v_and_b32_e32 v25, 0xffff0000, v167
	v_mul_f32_e32 v12, s46, v8
	v_mul_f32_e32 v13, s46, v9
	v_mul_f32_e32 v14, s46, v10
	v_mul_f32_e32 v15, s46, v11
	v_fma_f32 v4, s46, v8, v4
	v_fma_f32 v5, s46, v9, v5
	v_fma_f32 v6, s46, v10, v6
	v_fma_f32 v7, s46, v11, v7
	v_fma_f32 v16, s47, v4, -v12
	v_fma_f32 v17, s47, v5, -v13
	v_fma_f32 v18, s47, v6, -v14
	v_fma_f32 v19, s47, v7, -v15
	v_cvt_pk_bf16_f32 v20, v16, v17
	v_cvt_pk_bf16_f32 v21, v18, v19
	global_store_dwordx2 v0, v[20:21], s[40:41] offset:1024
	v_fma_f32 v4, -s48, v22, v4
	v_fma_f32 v5, -s48, v23, v5
	v_fma_f32 v6, -s48, v24, v6
	v_fma_f32 v7, -s48, v25, v7
	v_readlane_b32 s46, v28, 42
	v_readlane_b32 s47, v29, 27
	v_readlane_b32 s48, v28, 27
	s_waitcnt vmcnt(49)
	v_lshlrev_b32_e32 v8, 16, v200
	v_and_b32_e32 v9, 0xffff0000, v200
	v_lshlrev_b32_e32 v10, 16, v201
	v_and_b32_e32 v11, 0xffff0000, v201
	v_lshlrev_b32_e32 v22, 16, v168
	v_and_b32_e32 v23, 0xffff0000, v168
	v_lshlrev_b32_e32 v24, 16, v169
	v_and_b32_e32 v25, 0xffff0000, v169
	v_mul_f32_e32 v12, s46, v8
	v_mul_f32_e32 v13, s46, v9
	v_mul_f32_e32 v14, s46, v10
	v_mul_f32_e32 v15, s46, v11
	v_fma_f32 v4, s46, v8, v4
	v_fma_f32 v5, s46, v9, v5
	v_fma_f32 v6, s46, v10, v6
	v_fma_f32 v7, s46, v11, v7
	v_fma_f32 v16, s47, v4, -v12
	v_fma_f32 v17, s47, v5, -v13
	v_fma_f32 v18, s47, v6, -v14
	v_fma_f32 v19, s47, v7, -v15
	v_cvt_pk_bf16_f32 v38, v16, v17
	v_cvt_pk_bf16_f32 v39, v18, v19
	global_store_dwordx2 v0, v[38:39], s[40:41] offset:1536
	v_fma_f32 v4, -s48, v22, v4
	v_fma_f32 v5, -s48, v23, v5
	v_fma_f32 v6, -s48, v24, v6
	v_fma_f32 v7, -s48, v25, v7
	v_readlane_b32 s46, v28, 43
	v_readlane_b32 s47, v29, 28
	v_readlane_b32 s48, v28, 28
	s_waitcnt vmcnt(49)
	v_lshlrev_b32_e32 v8, 16, v202
	v_and_b32_e32 v9, 0xffff0000, v202
	v_lshlrev_b32_e32 v10, 16, v203
	v_and_b32_e32 v11, 0xffff0000, v203
	v_lshlrev_b32_e32 v22, 16, v170
	v_and_b32_e32 v23, 0xffff0000, v170
	v_lshlrev_b32_e32 v24, 16, v171
	v_and_b32_e32 v25, 0xffff0000, v171
	v_mul_f32_e32 v12, s46, v8
	v_mul_f32_e32 v13, s46, v9
	v_mul_f32_e32 v14, s46, v10
	v_mul_f32_e32 v15, s46, v11
	v_fma_f32 v4, s46, v8, v4
	v_fma_f32 v5, s46, v9, v5
	v_fma_f32 v6, s46, v10, v6
	v_fma_f32 v7, s46, v11, v7
	v_fma_f32 v16, s47, v4, -v12
	v_fma_f32 v17, s47, v5, -v13
	v_fma_f32 v18, s47, v6, -v14
	v_fma_f32 v19, s47, v7, -v15
	v_cvt_pk_bf16_f32 v20, v16, v17
	v_cvt_pk_bf16_f32 v21, v18, v19
	global_store_dwordx2 v0, v[20:21], s[40:41] offset:2048
	v_fma_f32 v4, -s48, v22, v4
	v_fma_f32 v5, -s48, v23, v5
	v_fma_f32 v6, -s48, v24, v6
	v_fma_f32 v7, -s48, v25, v7
	v_readlane_b32 s46, v28, 44
	v_readlane_b32 s47, v29, 29
	v_readlane_b32 s48, v28, 29
	s_waitcnt vmcnt(48)
	v_lshlrev_b32_e32 v8, 16, v204
	v_and_b32_e32 v9, 0xffff0000, v204
	v_lshlrev_b32_e32 v10, 16, v205
	v_and_b32_e32 v11, 0xffff0000, v205
	v_lshlrev_b32_e32 v22, 16, v172
	v_and_b32_e32 v23, 0xffff0000, v172
	v_lshlrev_b32_e32 v24, 16, v173
	v_and_b32_e32 v25, 0xffff0000, v173
	v_mul_f32_e32 v12, s46, v8
	v_mul_f32_e32 v13, s46, v9
	v_mul_f32_e32 v14, s46, v10
	v_mul_f32_e32 v15, s46, v11
	v_fma_f32 v4, s46, v8, v4
	v_fma_f32 v5, s46, v9, v5
	v_fma_f32 v6, s46, v10, v6
	v_fma_f32 v7, s46, v11, v7
	v_fma_f32 v16, s47, v4, -v12
	v_fma_f32 v17, s47, v5, -v13
	v_fma_f32 v18, s47, v6, -v14
	v_fma_f32 v19, s47, v7, -v15
	v_cvt_pk_bf16_f32 v38, v16, v17
	v_cvt_pk_bf16_f32 v39, v18, v19
	global_store_dwordx2 v0, v[38:39], s[40:41] offset:2560
	v_fma_f32 v4, -s48, v22, v4
	v_fma_f32 v5, -s48, v23, v5
	v_fma_f32 v6, -s48, v24, v6
	v_fma_f32 v7, -s48, v25, v7
	v_readlane_b32 s46, v28, 45
	v_readlane_b32 s47, v29, 30
	v_readlane_b32 s48, v28, 30
	s_waitcnt vmcnt(48)
	v_lshlrev_b32_e32 v8, 16, v206
	v_and_b32_e32 v9, 0xffff0000, v206
	v_lshlrev_b32_e32 v10, 16, v207
	v_and_b32_e32 v11, 0xffff0000, v207
	v_lshlrev_b32_e32 v22, 16, v174
	v_and_b32_e32 v23, 0xffff0000, v174
	v_lshlrev_b32_e32 v24, 16, v175
	v_and_b32_e32 v25, 0xffff0000, v175
	v_mul_f32_e32 v12, s46, v8
	v_mul_f32_e32 v13, s46, v9
	v_mul_f32_e32 v14, s46, v10
	v_mul_f32_e32 v15, s46, v11
	v_fma_f32 v4, s46, v8, v4
	v_fma_f32 v5, s46, v9, v5
	v_fma_f32 v6, s46, v10, v6
	v_fma_f32 v7, s46, v11, v7
	v_fma_f32 v16, s47, v4, -v12
	v_fma_f32 v17, s47, v5, -v13
	v_fma_f32 v18, s47, v6, -v14
	v_fma_f32 v19, s47, v7, -v15
	v_cvt_pk_bf16_f32 v20, v16, v17
	v_cvt_pk_bf16_f32 v21, v18, v19
	global_store_dwordx2 v0, v[20:21], s[40:41] offset:3072
	v_fma_f32 v4, -s48, v22, v4
	v_fma_f32 v5, -s48, v23, v5
	v_fma_f32 v6, -s48, v24, v6
	v_fma_f32 v7, -s48, v25, v7
	v_readlane_b32 s46, v28, 46
	v_readlane_b32 s47, v29, 31
	v_readlane_b32 s48, v28, 31
	s_waitcnt vmcnt(47)
	v_lshlrev_b32_e32 v8, 16, v208
	v_and_b32_e32 v9, 0xffff0000, v208
	v_lshlrev_b32_e32 v10, 16, v209
	v_and_b32_e32 v11, 0xffff0000, v209
	v_lshlrev_b32_e32 v22, 16, v176
	v_and_b32_e32 v23, 0xffff0000, v176
	v_lshlrev_b32_e32 v24, 16, v177
	v_and_b32_e32 v25, 0xffff0000, v177
	v_mul_f32_e32 v12, s46, v8
	v_mul_f32_e32 v13, s46, v9
	v_mul_f32_e32 v14, s46, v10
	v_mul_f32_e32 v15, s46, v11
	v_fma_f32 v4, s46, v8, v4
	v_fma_f32 v5, s46, v9, v5
	v_fma_f32 v6, s46, v10, v6
	v_fma_f32 v7, s46, v11, v7
	v_fma_f32 v16, s47, v4, -v12
	v_fma_f32 v17, s47, v5, -v13
	v_fma_f32 v18, s47, v6, -v14
	v_fma_f32 v19, s47, v7, -v15
	v_cvt_pk_bf16_f32 v38, v16, v17
	v_cvt_pk_bf16_f32 v39, v18, v19
	global_store_dwordx2 v0, v[38:39], s[40:41] offset:3584
	v_fma_f32 v4, -s48, v22, v4
	v_fma_f32 v5, -s48, v23, v5
	v_fma_f32 v6, -s48, v24, v6
	v_fma_f32 v7, -s48, v25, v7
.Lpool_done:
	v_lshlrev_b32_e32 v40, 2, v192
.LBB0_1177:
	s_waitcnt vmcnt(0)
	s_movk_i32 s6, 0x100
	s_andn2_b64 vcc, exec, s[4:5]
	v_readfirstlane_b32 s4, v192
	s_waitcnt vmcnt(0)
	s_barrier
	s_cbranch_vccnz .LBB0_1212
	v_lshrrev_b32_e32 v0, 5, v192
	v_lshrrev_b32_e32 v2, 1, v192
	v_and_b32_e32 v0, 4, v0
	v_bfe_u32 v1, v192, 2, 2
	v_and_b32_e32 v2, 24, v2
	v_or3_b32 v0, v0, v1, v2
	v_lshlrev_b32_e32 v1, 4, v192
	v_add_u32_e32 v2, 0x2000, v1
	v_lshrrev_b32_e32 v2, 7, v2
	v_and_b32_e32 v4, 32, v192
	s_add_u32 s3, s72, 0xe940000
	s_movk_i32 s20, 0xe0
	v_bitop3_b32 v12, v1, v4, 48 bitop3:0x6c
	v_and_b32_e32 v13, 64, v192
	v_and_b32_e32 v14, 0xf0, v2
	v_bfe_u32 v15, v192, 2, 4
	s_addc_u32 s40, s73, 0
	v_and_or_b32 v3, v2, s20, v0
	v_or_b32_e32 v1, v12, v13
	v_or_b32_e32 v2, v14, v15
	s_add_u32 s41, s72, 0x2b80000
	v_lshrrev_b32_e32 v1, 1, v1
	v_mul_lo_u32 v2, s6, v2
	s_addc_u32 s42, s73, 0
	s_ashr_i32 s7, s6, 31
	v_add_lshl_u32 v154, v2, v1, 1
	v_lshrrev_b32_e32 v2, 3, v192
	s_movk_i32 s20, 0x60
	s_lshl_b64 s[18:19], s[6:7], 9
	v_and_or_b32 v0, v2, s20, v0
	s_ashr_i32 s20, s2, 31
	s_mul_i32 s20, s18, s20
	s_mul_hi_u32 s21, s18, s2
	s_add_i32 s22, s21, s20
	s_lshr_b64 s[20:21], s[6:7], 23
	s_ashr_i32 s64, s2, 7
	s_mul_i32 s21, s20, s2
	s_add_i32 s22, s22, s21
	s_ashr_i32 s21, s64, 31
	s_mul_i32 s21, s18, s21
	s_mul_hi_u32 s24, s18, s64
	s_lshr_b32 s5, s4, 6
	s_add_i32 s21, s24, s21
	s_mul_i32 s20, s20, s64
	s_lshr_b32 s9, s4, 8
	s_lshl_b64 s[0:1], s[6:7], 8
	s_lshl_b32 s8, s5, 10
	s_add_i32 s21, s21, s20
	s_mul_i32 s20, s18, s64
	s_add_u32 s38, s41, s20
	v_mul_lo_u32 v0, s6, v0
	s_addc_u32 s39, s42, s21
	s_add_i32 s43, s8, 0
	v_add_lshl_u32 v156, v0, v1, 1
	s_add_i32 m0, s43, 0x10000
	v_mul_lo_u32 v3, s6, v3
	global_load_lds_dwordx4 v156, s[38:39]
	s_add_i32 m0, s43, 0x12000
	v_add_lshl_u32 v152, v3, v1, 1
	s_add_u32 s20, s38, s0
	global_load_lds_dwordx4 v152, s[38:39]
	s_addc_u32 s21, s39, s1
	s_add_i32 m0, s43, 0x14000
	v_and_b32_e32 v16, 0x70, v2
	s_mul_i32 s23, s18, s2
	global_load_lds_dwordx4 v156, s[20:21]
	s_add_i32 m0, s43, 0x16000
	v_or_b32_e32 v0, v16, v15
	s_add_u32 s36, s3, s23
	v_mul_lo_u32 v0, s6, v0
	s_addc_u32 s37, s40, s22
	s_add_i32 s44, s43, 0x2000
	v_add_lshl_u32 v158, v0, v1, 1
	global_load_lds_dwordx4 v152, s[20:21]
	s_mov_b32 m0, s43
	s_add_u32 s22, s36, s0
	global_load_lds_dwordx4 v158, s[36:37]
	s_mov_b32 m0, s44
	s_addc_u32 s23, s37, s1
	s_add_i32 s45, s43, 0x4000
	global_load_lds_dwordx4 v154, s[36:37]
	s_mov_b32 m0, s45
	s_add_i32 s46, s43, 0x6000
	global_load_lds_dwordx4 v158, s[22:23]
	s_mov_b32 m0, s46
	v_mov_b32_e32 v161, 0
	global_load_lds_dwordx4 v154, s[22:23]
	v_mov_b32_e32 v157, v161
	v_mov_b32_e32 v153, v161
	v_mov_b32_e32 v159, v161
	v_mov_b32_e32 v155, v161
	s_cmp_eq_u32 s9, 1
	s_mov_b32 s47, 0
	v_lshl_add_u64 v[8:9], s[38:39], 0, v[156:157]
	v_lshl_add_u64 v[4:5], s[38:39], 0, v[152:153]
	v_lshl_add_u64 v[2:3], s[20:21], 0, v[156:157]
	v_lshl_add_u64 v[0:1], s[20:21], 0, v[152:153]
	v_lshl_add_u64 v[6:7], s[36:37], 0, v[158:159]
	s_cselect_b64 s[20:21], -1, 0
	s_cmp_lg_u32 s9, 1
	v_lshl_add_u64 v[10:11], s[36:37], 0, v[154:155]
	s_cbranch_scc1 .LBB0_1180
	s_barrier
